# P1 tile loop hand-written: scalar-base staging, continuous-DMA K loop, next-tile staging under the epilogue, pipelined rope table loads, LDS-transposed wide stores for the transposed column groups
# speedup vs baseline: 1.1170x; 1.0248x over previous
.LBB0_317:
	s_lshr_b32 s2, s53, 5
	s_mul_hi_u32 s2, s2, 0xcccccccd
	s_lshr_b32 s2, s2, 2
	s_lshl_b32 s3, s2, 4
	s_mul_i32 s2, s2, 0xa0
	s_sub_i32 s2, s53, s2
	s_lshr_b32 s2, s2, 4
	s_and_b32 s6, s53, 15
	s_add_i32 s3, s3, s6
	s_sub_i32 s28, s53, s58
	s_lshr_b32 s28, s28, 4
	s_add_i32 s28, s28, 8
	s_or_b32 s6, s6, 0x80
	s_cmp_ge_i32 s53, s58
	s_cselect_b32 s6, s6, s3
	s_cselect_b32 s28, s28, s2
	s_lshl_b32 s2, s6, 19
	s_add_u32 s12, s64, s2
	s_addc_u32 s13, s65, 0
	s_lshl_b32 s2, s28, 19
	s_add_u32 s14, s34, s2
	s_addc_u32 s15, s35, 0
	v_lshrrev_b32_e32 v194, 3, v222
	v_lshrrev_b32_e32 v195, 4, v222
	v_xor_b32_e32 v195, v195, v222
	v_and_b32_e32 v195, 7, v195
	v_lshlrev_b32_e32 v195, 4, v195
	v_lshlrev_b32_e32 v194, 11, v194
	v_add_u32_e32 v1, v194, v195
	v_readfirstlane_b32 s18, v222
	s_nop 3
	s_lshr_b32 s19, s18, 8
	s_lshr_b32 s18, s18, 6
	s_lshl_b32 s18, s18, 10
	s_barrier
	s_mov_b32 m0, s18
	s_nop 0
	global_load_lds_dwordx4 v1, s[12:13]
	s_add_i32 m0, s18, 0x2000
	s_add_u32 s16, s12, 0x20000
	s_addc_u32 s17, s13, 0
	global_load_lds_dwordx4 v1, s[16:17]
	s_add_i32 m0, s18, 0x4000
	s_add_u32 s16, s12, 0x40000
	s_addc_u32 s17, s13, 0
	global_load_lds_dwordx4 v1, s[16:17]
	s_add_i32 m0, s18, 0x6000
	s_add_u32 s16, s12, 0x60000
	s_addc_u32 s17, s13, 0
	global_load_lds_dwordx4 v1, s[16:17]
	s_add_i32 m0, s18, 0x8000
	s_nop 0
	global_load_lds_dwordx4 v1, s[14:15]
	s_add_i32 m0, s18, 0xa000
	s_add_u32 s16, s14, 0x20000
	s_addc_u32 s17, s15, 0
	global_load_lds_dwordx4 v1, s[16:17]
	s_add_i32 m0, s18, 0xc000
	s_add_u32 s16, s14, 0x40000
	s_addc_u32 s17, s15, 0
	global_load_lds_dwordx4 v1, s[16:17]
	s_add_i32 m0, s18, 0xe000
	s_add_u32 s16, s14, 0x60000
	s_addc_u32 s17, s15, 0
	global_load_lds_dwordx4 v1, s[16:17]
	s_waitcnt vmcnt(0)
.Lp1_cont:
	v_and_b32_e32 v194, 15, v222
	v_bfe_u32 v195, v222, 4, 2
	v_bfe_u32 v196, v194, 1, 3
	v_xor_b32_e32 v195, v195, v196
	v_lshlrev_b32_e32 v195, 4, v195
	v_lshrrev_b32_e32 v196, 8, v222
	v_lshl_or_b32 v196, v196, 7, v194
	v_lshl_or_b32 v200, v196, 7, v195
	v_xor_b32_e32 v201, 64, v200
	v_bfe_u32 v196, v222, 6, 2
	v_lshl_or_b32 v196, v196, 6, v194
	v_lshl_or_b32 v202, v196, 7, v195
	v_xor_b32_e32 v203, 64, v202
	v_add_u32_e32 v204, 0x10000, v200
	v_add_u32_e32 v205, 0x10000, v201
	v_add_u32_e32 v206, 0x10000, v202
	v_add_u32_e32 v207, 0x10000, v203
	v_readfirstlane_b32 s18, v222
	s_nop 3
	s_lshr_b32 s19, s18, 8
	s_lshr_b32 s18, s18, 6
	s_lshl_b32 s18, s18, 10
	s_barrier
	s_add_i32 m0, s18, 0x10000
	s_add_u32 s16, s12, 0x80
	s_addc_u32 s17, s13, 0
	global_load_lds_dwordx4 v1, s[16:17]
	s_add_i32 m0, s18, 0x18000
	s_add_u32 s16, s14, 0x80
	s_addc_u32 s17, s15, 0
	global_load_lds_dwordx4 v1, s[16:17]
	s_waitcnt vmcnt(63)
	s_barrier
	s_cmp_eq_u32 s19, 0
	s_cbranch_scc1 .Lp1_skew0
	s_barrier
.Lp1_skew0:
	ds_read_b128 v[130:133], v200 offset:0
	ds_read_b128 v[134:137], v200 offset:2048
	ds_read_b128 v[138:141], v200 offset:4096
	ds_read_b128 v[142:145], v200 offset:6144
	ds_read_b128 v[162:165], v202 offset:32768
	ds_read_b128 v[166:169], v202 offset:34816
	ds_read_b128 v[170:173], v202 offset:36864
	ds_read_b128 v[174:177], v202 offset:38912
	s_add_i32 m0, s18, 0x14000
	s_add_u32 s16, s12, 0x40080
	s_addc_u32 s17, s13, 0
	global_load_lds_dwordx4 v1, s[16:17]
	s_add_i32 m0, s18, 0x1a000
	s_add_u32 s16, s14, 0x20080
	s_addc_u32 s17, s15, 0
	global_load_lds_dwordx4 v1, s[16:17]
	s_waitcnt lgkmcnt(0)
	s_barrier
	v_mfma_f32_16x16x32_f16 v[126:129], v[162:165], v[130:133], 0
	v_mfma_f32_16x16x32_f16 v[122:125], v[166:169], v[130:133], 0
	v_mfma_f32_16x16x32_f16 v[118:121], v[170:173], v[130:133], 0
	v_mfma_f32_16x16x32_f16 v[114:117], v[174:177], v[130:133], 0
	v_mfma_f32_16x16x32_f16 v[110:113], v[162:165], v[134:137], 0
	v_mfma_f32_16x16x32_f16 v[106:109], v[166:169], v[134:137], 0
	v_mfma_f32_16x16x32_f16 v[102:105], v[170:173], v[134:137], 0
	v_mfma_f32_16x16x32_f16 v[98:101], v[174:177], v[134:137], 0
	v_mfma_f32_16x16x32_f16 v[94:97], v[162:165], v[138:141], 0
	v_mfma_f32_16x16x32_f16 v[90:93], v[166:169], v[138:141], 0
	v_mfma_f32_16x16x32_f16 v[86:89], v[170:173], v[138:141], 0
	v_mfma_f32_16x16x32_f16 v[82:85], v[174:177], v[138:141], 0
	v_mfma_f32_16x16x32_f16 v[78:81], v[162:165], v[142:145], 0
	v_mfma_f32_16x16x32_f16 v[74:77], v[166:169], v[142:145], 0
	v_mfma_f32_16x16x32_f16 v[70:73], v[170:173], v[142:145], 0
	v_mfma_f32_16x16x32_f16 v[66:69], v[174:177], v[142:145], 0
	s_barrier
	ds_read_b128 v[146:149], v200 offset:8192
	ds_read_b128 v[150:153], v200 offset:10240
	ds_read_b128 v[154:157], v200 offset:12288
	ds_read_b128 v[158:161], v200 offset:14336
	s_add_i32 m0, s18, 0x1c000
	s_add_u32 s16, s14, 0x40080
	s_addc_u32 s17, s15, 0
	global_load_lds_dwordx4 v1, s[16:17]
	s_add_i32 m0, s18, 0x1e000
	s_add_u32 s16, s14, 0x60080
	s_addc_u32 s17, s15, 0
	global_load_lds_dwordx4 v1, s[16:17]
	s_waitcnt lgkmcnt(0)
	s_barrier
	v_mfma_f32_16x16x32_f16 v[62:65], v[162:165], v[146:149], 0
	v_mfma_f32_16x16x32_f16 v[58:61], v[166:169], v[146:149], 0
	v_mfma_f32_16x16x32_f16 v[54:57], v[170:173], v[146:149], 0
	v_mfma_f32_16x16x32_f16 v[50:53], v[174:177], v[146:149], 0
	v_mfma_f32_16x16x32_f16 v[46:49], v[162:165], v[150:153], 0
	v_mfma_f32_16x16x32_f16 v[42:45], v[166:169], v[150:153], 0
	v_mfma_f32_16x16x32_f16 v[38:41], v[170:173], v[150:153], 0
	v_mfma_f32_16x16x32_f16 v[34:37], v[174:177], v[150:153], 0
	v_mfma_f32_16x16x32_f16 v[30:33], v[162:165], v[154:157], 0
	v_mfma_f32_16x16x32_f16 v[26:29], v[166:169], v[154:157], 0
	v_mfma_f32_16x16x32_f16 v[22:25], v[170:173], v[154:157], 0
	v_mfma_f32_16x16x32_f16 v[18:21], v[174:177], v[154:157], 0
	v_mfma_f32_16x16x32_f16 v[14:17], v[162:165], v[158:161], 0
	v_mfma_f32_16x16x32_f16 v[10:13], v[166:169], v[158:161], 0
	v_mfma_f32_16x16x32_f16 v[6:9], v[170:173], v[158:161], 0
	v_mfma_f32_16x16x32_f16 v[2:5], v[174:177], v[158:161], 0
	s_barrier
	ds_read_b128 v[130:133], v201 offset:0
	ds_read_b128 v[134:137], v201 offset:2048
	ds_read_b128 v[138:141], v201 offset:4096
	ds_read_b128 v[142:145], v201 offset:6144
	ds_read_b128 v[162:165], v203 offset:32768
	ds_read_b128 v[166:169], v203 offset:34816
	ds_read_b128 v[170:173], v203 offset:36864
	ds_read_b128 v[174:177], v203 offset:38912
	s_add_i32 m0, s18, 0x12000
	s_add_u32 s16, s12, 0x20080
	s_addc_u32 s17, s13, 0
	global_load_lds_dwordx4 v1, s[16:17]
	s_add_i32 m0, s18, 0x16000
	s_add_u32 s16, s12, 0x60080
	s_addc_u32 s17, s13, 0
	global_load_lds_dwordx4 v1, s[16:17]
	s_waitcnt lgkmcnt(0)
	s_barrier
	v_mfma_f32_16x16x32_f16 v[126:129], v[162:165], v[130:133], v[126:129]
	v_mfma_f32_16x16x32_f16 v[122:125], v[166:169], v[130:133], v[122:125]
	v_mfma_f32_16x16x32_f16 v[118:121], v[170:173], v[130:133], v[118:121]
	v_mfma_f32_16x16x32_f16 v[114:117], v[174:177], v[130:133], v[114:117]
	v_mfma_f32_16x16x32_f16 v[110:113], v[162:165], v[134:137], v[110:113]
	v_mfma_f32_16x16x32_f16 v[106:109], v[166:169], v[134:137], v[106:109]
	v_mfma_f32_16x16x32_f16 v[102:105], v[170:173], v[134:137], v[102:105]
	v_mfma_f32_16x16x32_f16 v[98:101], v[174:177], v[134:137], v[98:101]
	v_mfma_f32_16x16x32_f16 v[94:97], v[162:165], v[138:141], v[94:97]
	v_mfma_f32_16x16x32_f16 v[90:93], v[166:169], v[138:141], v[90:93]
	v_mfma_f32_16x16x32_f16 v[86:89], v[170:173], v[138:141], v[86:89]
	v_mfma_f32_16x16x32_f16 v[82:85], v[174:177], v[138:141], v[82:85]
	v_mfma_f32_16x16x32_f16 v[78:81], v[162:165], v[142:145], v[78:81]
	v_mfma_f32_16x16x32_f16 v[74:77], v[166:169], v[142:145], v[74:77]
	v_mfma_f32_16x16x32_f16 v[70:73], v[170:173], v[142:145], v[70:73]
	v_mfma_f32_16x16x32_f16 v[66:69], v[174:177], v[142:145], v[66:69]
	s_barrier
	ds_read_b128 v[146:149], v201 offset:8192
	ds_read_b128 v[150:153], v201 offset:10240
	ds_read_b128 v[154:157], v201 offset:12288
	ds_read_b128 v[158:161], v201 offset:14336
	s_mov_b32 m0, s18
	s_add_u32 s16, s12, 0x100
	s_addc_u32 s17, s13, 0
	global_load_lds_dwordx4 v1, s[16:17]
	s_add_i32 m0, s18, 0x8000
	s_add_u32 s16, s14, 0x100
	s_addc_u32 s17, s15, 0
	global_load_lds_dwordx4 v1, s[16:17]
	s_waitcnt vmcnt(4) lgkmcnt(0)
	s_barrier
	v_mfma_f32_16x16x32_f16 v[62:65], v[162:165], v[146:149], v[62:65]
	v_mfma_f32_16x16x32_f16 v[58:61], v[166:169], v[146:149], v[58:61]
	v_mfma_f32_16x16x32_f16 v[54:57], v[170:173], v[146:149], v[54:57]
	v_mfma_f32_16x16x32_f16 v[50:53], v[174:177], v[146:149], v[50:53]
	v_mfma_f32_16x16x32_f16 v[46:49], v[162:165], v[150:153], v[46:49]
	v_mfma_f32_16x16x32_f16 v[42:45], v[166:169], v[150:153], v[42:45]
	v_mfma_f32_16x16x32_f16 v[38:41], v[170:173], v[150:153], v[38:41]
	v_mfma_f32_16x16x32_f16 v[34:37], v[174:177], v[150:153], v[34:37]
	v_mfma_f32_16x16x32_f16 v[30:33], v[162:165], v[154:157], v[30:33]
	v_mfma_f32_16x16x32_f16 v[26:29], v[166:169], v[154:157], v[26:29]
	v_mfma_f32_16x16x32_f16 v[22:25], v[170:173], v[154:157], v[22:25]
	v_mfma_f32_16x16x32_f16 v[18:21], v[174:177], v[154:157], v[18:21]
	v_mfma_f32_16x16x32_f16 v[14:17], v[162:165], v[158:161], v[14:17]
	v_mfma_f32_16x16x32_f16 v[10:13], v[166:169], v[158:161], v[10:13]
	v_mfma_f32_16x16x32_f16 v[6:9], v[170:173], v[158:161], v[6:9]
	v_mfma_f32_16x16x32_f16 v[2:5], v[174:177], v[158:161], v[2:5]
	s_barrier
	s_add_u32 s12, s12, 0x80
	s_addc_u32 s13, s13, 0
	s_add_u32 s14, s14, 0x80
	s_addc_u32 s15, s15, 0
	ds_read_b128 v[130:133], v204 offset:0
	ds_read_b128 v[134:137], v204 offset:2048
	ds_read_b128 v[138:141], v204 offset:4096
	ds_read_b128 v[142:145], v204 offset:6144
	ds_read_b128 v[162:165], v206 offset:32768
	ds_read_b128 v[166:169], v206 offset:34816
	ds_read_b128 v[170:173], v206 offset:36864
	ds_read_b128 v[174:177], v206 offset:38912
	s_add_i32 m0, s18, 0x4000
	s_add_u32 s16, s12, 0x40080
	s_addc_u32 s17, s13, 0
	global_load_lds_dwordx4 v1, s[16:17]
	s_add_i32 m0, s18, 0xa000
	s_add_u32 s16, s14, 0x20080
	s_addc_u32 s17, s15, 0
	global_load_lds_dwordx4 v1, s[16:17]
	s_waitcnt vmcnt(4) lgkmcnt(0)
	s_barrier
	v_mfma_f32_16x16x32_f16 v[126:129], v[162:165], v[130:133], v[126:129]
	v_mfma_f32_16x16x32_f16 v[122:125], v[166:169], v[130:133], v[122:125]
	v_mfma_f32_16x16x32_f16 v[118:121], v[170:173], v[130:133], v[118:121]
	v_mfma_f32_16x16x32_f16 v[114:117], v[174:177], v[130:133], v[114:117]
	v_mfma_f32_16x16x32_f16 v[110:113], v[162:165], v[134:137], v[110:113]
	v_mfma_f32_16x16x32_f16 v[106:109], v[166:169], v[134:137], v[106:109]
	v_mfma_f32_16x16x32_f16 v[102:105], v[170:173], v[134:137], v[102:105]
	v_mfma_f32_16x16x32_f16 v[98:101], v[174:177], v[134:137], v[98:101]
	v_mfma_f32_16x16x32_f16 v[94:97], v[162:165], v[138:141], v[94:97]
	v_mfma_f32_16x16x32_f16 v[90:93], v[166:169], v[138:141], v[90:93]
	v_mfma_f32_16x16x32_f16 v[86:89], v[170:173], v[138:141], v[86:89]
	v_mfma_f32_16x16x32_f16 v[82:85], v[174:177], v[138:141], v[82:85]
	v_mfma_f32_16x16x32_f16 v[78:81], v[162:165], v[142:145], v[78:81]
	v_mfma_f32_16x16x32_f16 v[74:77], v[166:169], v[142:145], v[74:77]
	v_mfma_f32_16x16x32_f16 v[70:73], v[170:173], v[142:145], v[70:73]
	v_mfma_f32_16x16x32_f16 v[66:69], v[174:177], v[142:145], v[66:69]
	s_barrier
	ds_read_b128 v[146:149], v204 offset:8192
	ds_read_b128 v[150:153], v204 offset:10240
	ds_read_b128 v[154:157], v204 offset:12288
	ds_read_b128 v[158:161], v204 offset:14336
	s_add_i32 m0, s18, 0xc000
	s_add_u32 s16, s14, 0x40080
	s_addc_u32 s17, s15, 0
	global_load_lds_dwordx4 v1, s[16:17]
	s_add_i32 m0, s18, 0xe000
	s_add_u32 s16, s14, 0x60080
	s_addc_u32 s17, s15, 0
	global_load_lds_dwordx4 v1, s[16:17]
	s_waitcnt lgkmcnt(0)
	s_barrier
	v_mfma_f32_16x16x32_f16 v[62:65], v[162:165], v[146:149], v[62:65]
	v_mfma_f32_16x16x32_f16 v[58:61], v[166:169], v[146:149], v[58:61]
	v_mfma_f32_16x16x32_f16 v[54:57], v[170:173], v[146:149], v[54:57]
	v_mfma_f32_16x16x32_f16 v[50:53], v[174:177], v[146:149], v[50:53]
	v_mfma_f32_16x16x32_f16 v[46:49], v[162:165], v[150:153], v[46:49]
	v_mfma_f32_16x16x32_f16 v[42:45], v[166:169], v[150:153], v[42:45]
	v_mfma_f32_16x16x32_f16 v[38:41], v[170:173], v[150:153], v[38:41]
	v_mfma_f32_16x16x32_f16 v[34:37], v[174:177], v[150:153], v[34:37]
	v_mfma_f32_16x16x32_f16 v[30:33], v[162:165], v[154:157], v[30:33]
	v_mfma_f32_16x16x32_f16 v[26:29], v[166:169], v[154:157], v[26:29]
	v_mfma_f32_16x16x32_f16 v[22:25], v[170:173], v[154:157], v[22:25]
	v_mfma_f32_16x16x32_f16 v[18:21], v[174:177], v[154:157], v[18:21]
	v_mfma_f32_16x16x32_f16 v[14:17], v[162:165], v[158:161], v[14:17]
	v_mfma_f32_16x16x32_f16 v[10:13], v[166:169], v[158:161], v[10:13]
	v_mfma_f32_16x16x32_f16 v[6:9], v[170:173], v[158:161], v[6:9]
	v_mfma_f32_16x16x32_f16 v[2:5], v[174:177], v[158:161], v[2:5]
	s_barrier
	ds_read_b128 v[130:133], v205 offset:0
	ds_read_b128 v[134:137], v205 offset:2048
	ds_read_b128 v[138:141], v205 offset:4096
	ds_read_b128 v[142:145], v205 offset:6144
	ds_read_b128 v[162:165], v207 offset:32768
	ds_read_b128 v[166:169], v207 offset:34816
	ds_read_b128 v[170:173], v207 offset:36864
	ds_read_b128 v[174:177], v207 offset:38912
	s_add_i32 m0, s18, 0x2000
	s_add_u32 s16, s12, 0x20080
	s_addc_u32 s17, s13, 0
	global_load_lds_dwordx4 v1, s[16:17]
	s_add_i32 m0, s18, 0x6000
	s_add_u32 s16, s12, 0x60080
	s_addc_u32 s17, s13, 0
	global_load_lds_dwordx4 v1, s[16:17]
	s_waitcnt lgkmcnt(0)
	s_barrier
	v_mfma_f32_16x16x32_f16 v[126:129], v[162:165], v[130:133], v[126:129]
	v_mfma_f32_16x16x32_f16 v[122:125], v[166:169], v[130:133], v[122:125]
	v_mfma_f32_16x16x32_f16 v[118:121], v[170:173], v[130:133], v[118:121]
	v_mfma_f32_16x16x32_f16 v[114:117], v[174:177], v[130:133], v[114:117]
	v_mfma_f32_16x16x32_f16 v[110:113], v[162:165], v[134:137], v[110:113]
	v_mfma_f32_16x16x32_f16 v[106:109], v[166:169], v[134:137], v[106:109]
	v_mfma_f32_16x16x32_f16 v[102:105], v[170:173], v[134:137], v[102:105]
	v_mfma_f32_16x16x32_f16 v[98:101], v[174:177], v[134:137], v[98:101]
	v_mfma_f32_16x16x32_f16 v[94:97], v[162:165], v[138:141], v[94:97]
	v_mfma_f32_16x16x32_f16 v[90:93], v[166:169], v[138:141], v[90:93]
	v_mfma_f32_16x16x32_f16 v[86:89], v[170:173], v[138:141], v[86:89]
	v_mfma_f32_16x16x32_f16 v[82:85], v[174:177], v[138:141], v[82:85]
	v_mfma_f32_16x16x32_f16 v[78:81], v[162:165], v[142:145], v[78:81]
	v_mfma_f32_16x16x32_f16 v[74:77], v[166:169], v[142:145], v[74:77]
	v_mfma_f32_16x16x32_f16 v[70:73], v[170:173], v[142:145], v[70:73]
	v_mfma_f32_16x16x32_f16 v[66:69], v[174:177], v[142:145], v[66:69]
	s_barrier
	ds_read_b128 v[146:149], v205 offset:8192
	ds_read_b128 v[150:153], v205 offset:10240
	ds_read_b128 v[154:157], v205 offset:12288
	ds_read_b128 v[158:161], v205 offset:14336
	s_add_i32 m0, s18, 0x10000
	s_add_u32 s16, s12, 0x100
	s_addc_u32 s17, s13, 0
	global_load_lds_dwordx4 v1, s[16:17]
	s_add_i32 m0, s18, 0x18000
	s_add_u32 s16, s14, 0x100
	s_addc_u32 s17, s15, 0
	global_load_lds_dwordx4 v1, s[16:17]
	s_waitcnt vmcnt(4) lgkmcnt(0)
	s_barrier
	v_mfma_f32_16x16x32_f16 v[62:65], v[162:165], v[146:149], v[62:65]
	v_mfma_f32_16x16x32_f16 v[58:61], v[166:169], v[146:149], v[58:61]
	v_mfma_f32_16x16x32_f16 v[54:57], v[170:173], v[146:149], v[54:57]
	v_mfma_f32_16x16x32_f16 v[50:53], v[174:177], v[146:149], v[50:53]
	v_mfma_f32_16x16x32_f16 v[46:49], v[162:165], v[150:153], v[46:49]
	v_mfma_f32_16x16x32_f16 v[42:45], v[166:169], v[150:153], v[42:45]
	v_mfma_f32_16x16x32_f16 v[38:41], v[170:173], v[150:153], v[38:41]
	v_mfma_f32_16x16x32_f16 v[34:37], v[174:177], v[150:153], v[34:37]
	v_mfma_f32_16x16x32_f16 v[30:33], v[162:165], v[154:157], v[30:33]
	v_mfma_f32_16x16x32_f16 v[26:29], v[166:169], v[154:157], v[26:29]
	v_mfma_f32_16x16x32_f16 v[22:25], v[170:173], v[154:157], v[22:25]
	v_mfma_f32_16x16x32_f16 v[18:21], v[174:177], v[154:157], v[18:21]
	v_mfma_f32_16x16x32_f16 v[14:17], v[162:165], v[158:161], v[14:17]
	v_mfma_f32_16x16x32_f16 v[10:13], v[166:169], v[158:161], v[10:13]
	v_mfma_f32_16x16x32_f16 v[6:9], v[170:173], v[158:161], v[6:9]
	v_mfma_f32_16x16x32_f16 v[2:5], v[174:177], v[158:161], v[2:5]
	s_barrier
	s_add_u32 s12, s12, 0x80
	s_addc_u32 s13, s13, 0
	s_add_u32 s14, s14, 0x80
	s_addc_u32 s15, s15, 0
	s_movk_i32 s20, 6
.Lp1_loop:
	ds_read_b128 v[130:133], v200 offset:0
	ds_read_b128 v[134:137], v200 offset:2048
	ds_read_b128 v[138:141], v200 offset:4096
	ds_read_b128 v[142:145], v200 offset:6144
	ds_read_b128 v[162:165], v202 offset:32768
	ds_read_b128 v[166:169], v202 offset:34816
	ds_read_b128 v[170:173], v202 offset:36864
	ds_read_b128 v[174:177], v202 offset:38912
	s_add_i32 m0, s18, 0x14000
	s_add_u32 s16, s12, 0x40080
	s_addc_u32 s17, s13, 0
	global_load_lds_dwordx4 v1, s[16:17]
	s_add_i32 m0, s18, 0x1a000
	s_add_u32 s16, s14, 0x20080
	s_addc_u32 s17, s15, 0
	global_load_lds_dwordx4 v1, s[16:17]
	s_waitcnt vmcnt(4) lgkmcnt(0)
	s_barrier
	v_mfma_f32_16x16x32_f16 v[126:129], v[162:165], v[130:133], v[126:129]
	v_mfma_f32_16x16x32_f16 v[122:125], v[166:169], v[130:133], v[122:125]
	v_mfma_f32_16x16x32_f16 v[118:121], v[170:173], v[130:133], v[118:121]
	v_mfma_f32_16x16x32_f16 v[114:117], v[174:177], v[130:133], v[114:117]
	v_mfma_f32_16x16x32_f16 v[110:113], v[162:165], v[134:137], v[110:113]
	v_mfma_f32_16x16x32_f16 v[106:109], v[166:169], v[134:137], v[106:109]
	v_mfma_f32_16x16x32_f16 v[102:105], v[170:173], v[134:137], v[102:105]
	v_mfma_f32_16x16x32_f16 v[98:101], v[174:177], v[134:137], v[98:101]
	v_mfma_f32_16x16x32_f16 v[94:97], v[162:165], v[138:141], v[94:97]
	v_mfma_f32_16x16x32_f16 v[90:93], v[166:169], v[138:141], v[90:93]
	v_mfma_f32_16x16x32_f16 v[86:89], v[170:173], v[138:141], v[86:89]
	v_mfma_f32_16x16x32_f16 v[82:85], v[174:177], v[138:141], v[82:85]
	v_mfma_f32_16x16x32_f16 v[78:81], v[162:165], v[142:145], v[78:81]
	v_mfma_f32_16x16x32_f16 v[74:77], v[166:169], v[142:145], v[74:77]
	v_mfma_f32_16x16x32_f16 v[70:73], v[170:173], v[142:145], v[70:73]
	v_mfma_f32_16x16x32_f16 v[66:69], v[174:177], v[142:145], v[66:69]
	s_barrier
	ds_read_b128 v[146:149], v200 offset:8192
	ds_read_b128 v[150:153], v200 offset:10240
	ds_read_b128 v[154:157], v200 offset:12288
	ds_read_b128 v[158:161], v200 offset:14336
	s_add_i32 m0, s18, 0x1c000
	s_add_u32 s16, s14, 0x40080
	s_addc_u32 s17, s15, 0
	global_load_lds_dwordx4 v1, s[16:17]
	s_add_i32 m0, s18, 0x1e000
	s_add_u32 s16, s14, 0x60080
	s_addc_u32 s17, s15, 0
	global_load_lds_dwordx4 v1, s[16:17]
	s_waitcnt lgkmcnt(0)
	s_barrier
	v_mfma_f32_16x16x32_f16 v[62:65], v[162:165], v[146:149], v[62:65]
	v_mfma_f32_16x16x32_f16 v[58:61], v[166:169], v[146:149], v[58:61]
	v_mfma_f32_16x16x32_f16 v[54:57], v[170:173], v[146:149], v[54:57]
	v_mfma_f32_16x16x32_f16 v[50:53], v[174:177], v[146:149], v[50:53]
	v_mfma_f32_16x16x32_f16 v[46:49], v[162:165], v[150:153], v[46:49]
	v_mfma_f32_16x16x32_f16 v[42:45], v[166:169], v[150:153], v[42:45]
	v_mfma_f32_16x16x32_f16 v[38:41], v[170:173], v[150:153], v[38:41]
	v_mfma_f32_16x16x32_f16 v[34:37], v[174:177], v[150:153], v[34:37]
	v_mfma_f32_16x16x32_f16 v[30:33], v[162:165], v[154:157], v[30:33]
	v_mfma_f32_16x16x32_f16 v[26:29], v[166:169], v[154:157], v[26:29]
	v_mfma_f32_16x16x32_f16 v[22:25], v[170:173], v[154:157], v[22:25]
	v_mfma_f32_16x16x32_f16 v[18:21], v[174:177], v[154:157], v[18:21]
	v_mfma_f32_16x16x32_f16 v[14:17], v[162:165], v[158:161], v[14:17]
	v_mfma_f32_16x16x32_f16 v[10:13], v[166:169], v[158:161], v[10:13]
	v_mfma_f32_16x16x32_f16 v[6:9], v[170:173], v[158:161], v[6:9]
	v_mfma_f32_16x16x32_f16 v[2:5], v[174:177], v[158:161], v[2:5]
	s_barrier
	ds_read_b128 v[130:133], v201 offset:0
	ds_read_b128 v[134:137], v201 offset:2048
	ds_read_b128 v[138:141], v201 offset:4096
	ds_read_b128 v[142:145], v201 offset:6144
	ds_read_b128 v[162:165], v203 offset:32768
	ds_read_b128 v[166:169], v203 offset:34816
	ds_read_b128 v[170:173], v203 offset:36864
	ds_read_b128 v[174:177], v203 offset:38912
	s_add_i32 m0, s18, 0x12000
	s_add_u32 s16, s12, 0x20080
	s_addc_u32 s17, s13, 0
	global_load_lds_dwordx4 v1, s[16:17]
	s_add_i32 m0, s18, 0x16000
	s_add_u32 s16, s12, 0x60080
	s_addc_u32 s17, s13, 0
	global_load_lds_dwordx4 v1, s[16:17]
	s_waitcnt lgkmcnt(0)
	s_barrier
	v_mfma_f32_16x16x32_f16 v[126:129], v[162:165], v[130:133], v[126:129]
	v_mfma_f32_16x16x32_f16 v[122:125], v[166:169], v[130:133], v[122:125]
	v_mfma_f32_16x16x32_f16 v[118:121], v[170:173], v[130:133], v[118:121]
	v_mfma_f32_16x16x32_f16 v[114:117], v[174:177], v[130:133], v[114:117]
	v_mfma_f32_16x16x32_f16 v[110:113], v[162:165], v[134:137], v[110:113]
	v_mfma_f32_16x16x32_f16 v[106:109], v[166:169], v[134:137], v[106:109]
	v_mfma_f32_16x16x32_f16 v[102:105], v[170:173], v[134:137], v[102:105]
	v_mfma_f32_16x16x32_f16 v[98:101], v[174:177], v[134:137], v[98:101]
	v_mfma_f32_16x16x32_f16 v[94:97], v[162:165], v[138:141], v[94:97]
	v_mfma_f32_16x16x32_f16 v[90:93], v[166:169], v[138:141], v[90:93]
	v_mfma_f32_16x16x32_f16 v[86:89], v[170:173], v[138:141], v[86:89]
	v_mfma_f32_16x16x32_f16 v[82:85], v[174:177], v[138:141], v[82:85]
	v_mfma_f32_16x16x32_f16 v[78:81], v[162:165], v[142:145], v[78:81]
	v_mfma_f32_16x16x32_f16 v[74:77], v[166:169], v[142:145], v[74:77]
	v_mfma_f32_16x16x32_f16 v[70:73], v[170:173], v[142:145], v[70:73]
	v_mfma_f32_16x16x32_f16 v[66:69], v[174:177], v[142:145], v[66:69]
	s_barrier
	ds_read_b128 v[146:149], v201 offset:8192
	ds_read_b128 v[150:153], v201 offset:10240
	ds_read_b128 v[154:157], v201 offset:12288
	ds_read_b128 v[158:161], v201 offset:14336
	s_mov_b32 m0, s18
	s_add_u32 s16, s12, 0x100
	s_addc_u32 s17, s13, 0
	global_load_lds_dwordx4 v1, s[16:17]
	s_add_i32 m0, s18, 0x8000
	s_add_u32 s16, s14, 0x100
	s_addc_u32 s17, s15, 0
	global_load_lds_dwordx4 v1, s[16:17]
	s_waitcnt vmcnt(4) lgkmcnt(0)
	s_barrier
	v_mfma_f32_16x16x32_f16 v[62:65], v[162:165], v[146:149], v[62:65]
	v_mfma_f32_16x16x32_f16 v[58:61], v[166:169], v[146:149], v[58:61]
	v_mfma_f32_16x16x32_f16 v[54:57], v[170:173], v[146:149], v[54:57]
	v_mfma_f32_16x16x32_f16 v[50:53], v[174:177], v[146:149], v[50:53]
	v_mfma_f32_16x16x32_f16 v[46:49], v[162:165], v[150:153], v[46:49]
	v_mfma_f32_16x16x32_f16 v[42:45], v[166:169], v[150:153], v[42:45]
	v_mfma_f32_16x16x32_f16 v[38:41], v[170:173], v[150:153], v[38:41]
	v_mfma_f32_16x16x32_f16 v[34:37], v[174:177], v[150:153], v[34:37]
	v_mfma_f32_16x16x32_f16 v[30:33], v[162:165], v[154:157], v[30:33]
	v_mfma_f32_16x16x32_f16 v[26:29], v[166:169], v[154:157], v[26:29]
	v_mfma_f32_16x16x32_f16 v[22:25], v[170:173], v[154:157], v[22:25]
	v_mfma_f32_16x16x32_f16 v[18:21], v[174:177], v[154:157], v[18:21]
	v_mfma_f32_16x16x32_f16 v[14:17], v[162:165], v[158:161], v[14:17]
	v_mfma_f32_16x16x32_f16 v[10:13], v[166:169], v[158:161], v[10:13]
	v_mfma_f32_16x16x32_f16 v[6:9], v[170:173], v[158:161], v[6:9]
	v_mfma_f32_16x16x32_f16 v[2:5], v[174:177], v[158:161], v[2:5]
	s_barrier
	s_add_u32 s12, s12, 0x80
	s_addc_u32 s13, s13, 0
	s_add_u32 s14, s14, 0x80
	s_addc_u32 s15, s15, 0
	ds_read_b128 v[130:133], v204 offset:0
	ds_read_b128 v[134:137], v204 offset:2048
	ds_read_b128 v[138:141], v204 offset:4096
	ds_read_b128 v[142:145], v204 offset:6144
	ds_read_b128 v[162:165], v206 offset:32768
	ds_read_b128 v[166:169], v206 offset:34816
	ds_read_b128 v[170:173], v206 offset:36864
	ds_read_b128 v[174:177], v206 offset:38912
	s_add_i32 m0, s18, 0x4000
	s_add_u32 s16, s12, 0x40080
	s_addc_u32 s17, s13, 0
	global_load_lds_dwordx4 v1, s[16:17]
	s_add_i32 m0, s18, 0xa000
	s_add_u32 s16, s14, 0x20080
	s_addc_u32 s17, s15, 0
	global_load_lds_dwordx4 v1, s[16:17]
	s_waitcnt vmcnt(4) lgkmcnt(0)
	s_barrier
	v_mfma_f32_16x16x32_f16 v[126:129], v[162:165], v[130:133], v[126:129]
	v_mfma_f32_16x16x32_f16 v[122:125], v[166:169], v[130:133], v[122:125]
	v_mfma_f32_16x16x32_f16 v[118:121], v[170:173], v[130:133], v[118:121]
	v_mfma_f32_16x16x32_f16 v[114:117], v[174:177], v[130:133], v[114:117]
	v_mfma_f32_16x16x32_f16 v[110:113], v[162:165], v[134:137], v[110:113]
	v_mfma_f32_16x16x32_f16 v[106:109], v[166:169], v[134:137], v[106:109]
	v_mfma_f32_16x16x32_f16 v[102:105], v[170:173], v[134:137], v[102:105]
	v_mfma_f32_16x16x32_f16 v[98:101], v[174:177], v[134:137], v[98:101]
	v_mfma_f32_16x16x32_f16 v[94:97], v[162:165], v[138:141], v[94:97]
	v_mfma_f32_16x16x32_f16 v[90:93], v[166:169], v[138:141], v[90:93]
	v_mfma_f32_16x16x32_f16 v[86:89], v[170:173], v[138:141], v[86:89]
	v_mfma_f32_16x16x32_f16 v[82:85], v[174:177], v[138:141], v[82:85]
	v_mfma_f32_16x16x32_f16 v[78:81], v[162:165], v[142:145], v[78:81]
	v_mfma_f32_16x16x32_f16 v[74:77], v[166:169], v[142:145], v[74:77]
	v_mfma_f32_16x16x32_f16 v[70:73], v[170:173], v[142:145], v[70:73]
	v_mfma_f32_16x16x32_f16 v[66:69], v[174:177], v[142:145], v[66:69]
	s_barrier
	ds_read_b128 v[146:149], v204 offset:8192
	ds_read_b128 v[150:153], v204 offset:10240
	ds_read_b128 v[154:157], v204 offset:12288
	ds_read_b128 v[158:161], v204 offset:14336
	s_add_i32 m0, s18, 0xc000
	s_add_u32 s16, s14, 0x40080
	s_addc_u32 s17, s15, 0
	global_load_lds_dwordx4 v1, s[16:17]
	s_add_i32 m0, s18, 0xe000
	s_add_u32 s16, s14, 0x60080
	s_addc_u32 s17, s15, 0
	global_load_lds_dwordx4 v1, s[16:17]
	s_waitcnt lgkmcnt(0)
	s_barrier
	v_mfma_f32_16x16x32_f16 v[62:65], v[162:165], v[146:149], v[62:65]
	v_mfma_f32_16x16x32_f16 v[58:61], v[166:169], v[146:149], v[58:61]
	v_mfma_f32_16x16x32_f16 v[54:57], v[170:173], v[146:149], v[54:57]
	v_mfma_f32_16x16x32_f16 v[50:53], v[174:177], v[146:149], v[50:53]
	v_mfma_f32_16x16x32_f16 v[46:49], v[162:165], v[150:153], v[46:49]
	v_mfma_f32_16x16x32_f16 v[42:45], v[166:169], v[150:153], v[42:45]
	v_mfma_f32_16x16x32_f16 v[38:41], v[170:173], v[150:153], v[38:41]
	v_mfma_f32_16x16x32_f16 v[34:37], v[174:177], v[150:153], v[34:37]
	v_mfma_f32_16x16x32_f16 v[30:33], v[162:165], v[154:157], v[30:33]
	v_mfma_f32_16x16x32_f16 v[26:29], v[166:169], v[154:157], v[26:29]
	v_mfma_f32_16x16x32_f16 v[22:25], v[170:173], v[154:157], v[22:25]
	v_mfma_f32_16x16x32_f16 v[18:21], v[174:177], v[154:157], v[18:21]
	v_mfma_f32_16x16x32_f16 v[14:17], v[162:165], v[158:161], v[14:17]
	v_mfma_f32_16x16x32_f16 v[10:13], v[166:169], v[158:161], v[10:13]
	v_mfma_f32_16x16x32_f16 v[6:9], v[170:173], v[158:161], v[6:9]
	v_mfma_f32_16x16x32_f16 v[2:5], v[174:177], v[158:161], v[2:5]
	s_barrier
	ds_read_b128 v[130:133], v205 offset:0
	ds_read_b128 v[134:137], v205 offset:2048
	ds_read_b128 v[138:141], v205 offset:4096
	ds_read_b128 v[142:145], v205 offset:6144
	ds_read_b128 v[162:165], v207 offset:32768
	ds_read_b128 v[166:169], v207 offset:34816
	ds_read_b128 v[170:173], v207 offset:36864
	ds_read_b128 v[174:177], v207 offset:38912
	s_add_i32 m0, s18, 0x2000
	s_add_u32 s16, s12, 0x20080
	s_addc_u32 s17, s13, 0
	global_load_lds_dwordx4 v1, s[16:17]
	s_add_i32 m0, s18, 0x6000
	s_add_u32 s16, s12, 0x60080
	s_addc_u32 s17, s13, 0
	global_load_lds_dwordx4 v1, s[16:17]
	s_waitcnt lgkmcnt(0)
	s_barrier
	v_mfma_f32_16x16x32_f16 v[126:129], v[162:165], v[130:133], v[126:129]
	v_mfma_f32_16x16x32_f16 v[122:125], v[166:169], v[130:133], v[122:125]
	v_mfma_f32_16x16x32_f16 v[118:121], v[170:173], v[130:133], v[118:121]
	v_mfma_f32_16x16x32_f16 v[114:117], v[174:177], v[130:133], v[114:117]
	v_mfma_f32_16x16x32_f16 v[110:113], v[162:165], v[134:137], v[110:113]
	v_mfma_f32_16x16x32_f16 v[106:109], v[166:169], v[134:137], v[106:109]
	v_mfma_f32_16x16x32_f16 v[102:105], v[170:173], v[134:137], v[102:105]
	v_mfma_f32_16x16x32_f16 v[98:101], v[174:177], v[134:137], v[98:101]
	v_mfma_f32_16x16x32_f16 v[94:97], v[162:165], v[138:141], v[94:97]
	v_mfma_f32_16x16x32_f16 v[90:93], v[166:169], v[138:141], v[90:93]
	v_mfma_f32_16x16x32_f16 v[86:89], v[170:173], v[138:141], v[86:89]
	v_mfma_f32_16x16x32_f16 v[82:85], v[174:177], v[138:141], v[82:85]
	v_mfma_f32_16x16x32_f16 v[78:81], v[162:165], v[142:145], v[78:81]
	v_mfma_f32_16x16x32_f16 v[74:77], v[166:169], v[142:145], v[74:77]
	v_mfma_f32_16x16x32_f16 v[70:73], v[170:173], v[142:145], v[70:73]
	v_mfma_f32_16x16x32_f16 v[66:69], v[174:177], v[142:145], v[66:69]
	s_barrier
	ds_read_b128 v[146:149], v205 offset:8192
	ds_read_b128 v[150:153], v205 offset:10240
	ds_read_b128 v[154:157], v205 offset:12288
	ds_read_b128 v[158:161], v205 offset:14336
	s_add_i32 m0, s18, 0x10000
	s_add_u32 s16, s12, 0x100
	s_addc_u32 s17, s13, 0
	global_load_lds_dwordx4 v1, s[16:17]
	s_add_i32 m0, s18, 0x18000
	s_add_u32 s16, s14, 0x100
	s_addc_u32 s17, s15, 0
	global_load_lds_dwordx4 v1, s[16:17]
	s_waitcnt vmcnt(4) lgkmcnt(0)
	s_barrier
	v_mfma_f32_16x16x32_f16 v[62:65], v[162:165], v[146:149], v[62:65]
	v_mfma_f32_16x16x32_f16 v[58:61], v[166:169], v[146:149], v[58:61]
	v_mfma_f32_16x16x32_f16 v[54:57], v[170:173], v[146:149], v[54:57]
	v_mfma_f32_16x16x32_f16 v[50:53], v[174:177], v[146:149], v[50:53]
	v_mfma_f32_16x16x32_f16 v[46:49], v[162:165], v[150:153], v[46:49]
	v_mfma_f32_16x16x32_f16 v[42:45], v[166:169], v[150:153], v[42:45]
	v_mfma_f32_16x16x32_f16 v[38:41], v[170:173], v[150:153], v[38:41]
	v_mfma_f32_16x16x32_f16 v[34:37], v[174:177], v[150:153], v[34:37]
	v_mfma_f32_16x16x32_f16 v[30:33], v[162:165], v[154:157], v[30:33]
	v_mfma_f32_16x16x32_f16 v[26:29], v[166:169], v[154:157], v[26:29]
	v_mfma_f32_16x16x32_f16 v[22:25], v[170:173], v[154:157], v[22:25]
	v_mfma_f32_16x16x32_f16 v[18:21], v[174:177], v[154:157], v[18:21]
	v_mfma_f32_16x16x32_f16 v[14:17], v[162:165], v[158:161], v[14:17]
	v_mfma_f32_16x16x32_f16 v[10:13], v[166:169], v[158:161], v[10:13]
	v_mfma_f32_16x16x32_f16 v[6:9], v[170:173], v[158:161], v[6:9]
	v_mfma_f32_16x16x32_f16 v[2:5], v[174:177], v[158:161], v[2:5]
	s_barrier
	s_add_u32 s12, s12, 0x80
	s_addc_u32 s13, s13, 0
	s_add_u32 s14, s14, 0x80
	s_addc_u32 s15, s15, 0
	s_add_i32 s20, s20, -1
	s_cmp_lg_u32 s20, 0
	s_cbranch_scc1 .Lp1_loop
	ds_read_b128 v[130:133], v200 offset:0
	ds_read_b128 v[134:137], v200 offset:2048
	ds_read_b128 v[138:141], v200 offset:4096
	ds_read_b128 v[142:145], v200 offset:6144
	ds_read_b128 v[162:165], v202 offset:32768
	ds_read_b128 v[166:169], v202 offset:34816
	ds_read_b128 v[170:173], v202 offset:36864
	ds_read_b128 v[174:177], v202 offset:38912
	s_add_i32 m0, s18, 0x14000
	s_add_u32 s16, s12, 0x40080
	s_addc_u32 s17, s13, 0
	global_load_lds_dwordx4 v1, s[16:17]
	s_add_i32 m0, s18, 0x1a000
	s_add_u32 s16, s14, 0x20080
	s_addc_u32 s17, s15, 0
	global_load_lds_dwordx4 v1, s[16:17]
	s_waitcnt vmcnt(4) lgkmcnt(0)
	s_barrier
	v_mfma_f32_16x16x32_f16 v[126:129], v[162:165], v[130:133], v[126:129]
	v_mfma_f32_16x16x32_f16 v[122:125], v[166:169], v[130:133], v[122:125]
	v_mfma_f32_16x16x32_f16 v[118:121], v[170:173], v[130:133], v[118:121]
	v_mfma_f32_16x16x32_f16 v[114:117], v[174:177], v[130:133], v[114:117]
	v_mfma_f32_16x16x32_f16 v[110:113], v[162:165], v[134:137], v[110:113]
	v_mfma_f32_16x16x32_f16 v[106:109], v[166:169], v[134:137], v[106:109]
	v_mfma_f32_16x16x32_f16 v[102:105], v[170:173], v[134:137], v[102:105]
	v_mfma_f32_16x16x32_f16 v[98:101], v[174:177], v[134:137], v[98:101]
	v_mfma_f32_16x16x32_f16 v[94:97], v[162:165], v[138:141], v[94:97]
	v_mfma_f32_16x16x32_f16 v[90:93], v[166:169], v[138:141], v[90:93]
	v_mfma_f32_16x16x32_f16 v[86:89], v[170:173], v[138:141], v[86:89]
	v_mfma_f32_16x16x32_f16 v[82:85], v[174:177], v[138:141], v[82:85]
	v_mfma_f32_16x16x32_f16 v[78:81], v[162:165], v[142:145], v[78:81]
	v_mfma_f32_16x16x32_f16 v[74:77], v[166:169], v[142:145], v[74:77]
	v_mfma_f32_16x16x32_f16 v[70:73], v[170:173], v[142:145], v[70:73]
	v_mfma_f32_16x16x32_f16 v[66:69], v[174:177], v[142:145], v[66:69]
	s_barrier
	ds_read_b128 v[146:149], v200 offset:8192
	ds_read_b128 v[150:153], v200 offset:10240
	ds_read_b128 v[154:157], v200 offset:12288
	ds_read_b128 v[158:161], v200 offset:14336
	s_add_i32 m0, s18, 0x1c000
	s_add_u32 s16, s14, 0x40080
	s_addc_u32 s17, s15, 0
	global_load_lds_dwordx4 v1, s[16:17]
	s_add_i32 m0, s18, 0x1e000
	s_add_u32 s16, s14, 0x60080
	s_addc_u32 s17, s15, 0
	global_load_lds_dwordx4 v1, s[16:17]
	s_waitcnt lgkmcnt(0)
	s_barrier
	v_mfma_f32_16x16x32_f16 v[62:65], v[162:165], v[146:149], v[62:65]
	v_mfma_f32_16x16x32_f16 v[58:61], v[166:169], v[146:149], v[58:61]
	v_mfma_f32_16x16x32_f16 v[54:57], v[170:173], v[146:149], v[54:57]
	v_mfma_f32_16x16x32_f16 v[50:53], v[174:177], v[146:149], v[50:53]
	v_mfma_f32_16x16x32_f16 v[46:49], v[162:165], v[150:153], v[46:49]
	v_mfma_f32_16x16x32_f16 v[42:45], v[166:169], v[150:153], v[42:45]
	v_mfma_f32_16x16x32_f16 v[38:41], v[170:173], v[150:153], v[38:41]
	v_mfma_f32_16x16x32_f16 v[34:37], v[174:177], v[150:153], v[34:37]
	v_mfma_f32_16x16x32_f16 v[30:33], v[162:165], v[154:157], v[30:33]
	v_mfma_f32_16x16x32_f16 v[26:29], v[166:169], v[154:157], v[26:29]
	v_mfma_f32_16x16x32_f16 v[22:25], v[170:173], v[154:157], v[22:25]
	v_mfma_f32_16x16x32_f16 v[18:21], v[174:177], v[154:157], v[18:21]
	v_mfma_f32_16x16x32_f16 v[14:17], v[162:165], v[158:161], v[14:17]
	v_mfma_f32_16x16x32_f16 v[10:13], v[166:169], v[158:161], v[10:13]
	v_mfma_f32_16x16x32_f16 v[6:9], v[170:173], v[158:161], v[6:9]
	v_mfma_f32_16x16x32_f16 v[2:5], v[174:177], v[158:161], v[2:5]
	s_barrier
	ds_read_b128 v[130:133], v201 offset:0
	ds_read_b128 v[134:137], v201 offset:2048
	ds_read_b128 v[138:141], v201 offset:4096
	ds_read_b128 v[142:145], v201 offset:6144
	ds_read_b128 v[162:165], v203 offset:32768
	ds_read_b128 v[166:169], v203 offset:34816
	ds_read_b128 v[170:173], v203 offset:36864
	ds_read_b128 v[174:177], v203 offset:38912
	s_add_i32 m0, s18, 0x12000
	s_add_u32 s16, s12, 0x20080
	s_addc_u32 s17, s13, 0
	global_load_lds_dwordx4 v1, s[16:17]
	s_add_i32 m0, s18, 0x16000
	s_add_u32 s16, s12, 0x60080
	s_addc_u32 s17, s13, 0
	global_load_lds_dwordx4 v1, s[16:17]
	s_waitcnt lgkmcnt(0)
	s_barrier
	v_mfma_f32_16x16x32_f16 v[126:129], v[162:165], v[130:133], v[126:129]
	v_mfma_f32_16x16x32_f16 v[122:125], v[166:169], v[130:133], v[122:125]
	v_mfma_f32_16x16x32_f16 v[118:121], v[170:173], v[130:133], v[118:121]
	v_mfma_f32_16x16x32_f16 v[114:117], v[174:177], v[130:133], v[114:117]
	v_mfma_f32_16x16x32_f16 v[110:113], v[162:165], v[134:137], v[110:113]
	v_mfma_f32_16x16x32_f16 v[106:109], v[166:169], v[134:137], v[106:109]
	v_mfma_f32_16x16x32_f16 v[102:105], v[170:173], v[134:137], v[102:105]
	v_mfma_f32_16x16x32_f16 v[98:101], v[174:177], v[134:137], v[98:101]
	v_mfma_f32_16x16x32_f16 v[94:97], v[162:165], v[138:141], v[94:97]
	v_mfma_f32_16x16x32_f16 v[90:93], v[166:169], v[138:141], v[90:93]
	v_mfma_f32_16x16x32_f16 v[86:89], v[170:173], v[138:141], v[86:89]
	v_mfma_f32_16x16x32_f16 v[82:85], v[174:177], v[138:141], v[82:85]
	v_mfma_f32_16x16x32_f16 v[78:81], v[162:165], v[142:145], v[78:81]
	v_mfma_f32_16x16x32_f16 v[74:77], v[166:169], v[142:145], v[74:77]
	v_mfma_f32_16x16x32_f16 v[70:73], v[170:173], v[142:145], v[70:73]
	v_mfma_f32_16x16x32_f16 v[66:69], v[174:177], v[142:145], v[66:69]
	s_barrier
	ds_read_b128 v[146:149], v201 offset:8192
	ds_read_b128 v[150:153], v201 offset:10240
	ds_read_b128 v[154:157], v201 offset:12288
	ds_read_b128 v[158:161], v201 offset:14336
	s_waitcnt vmcnt(2) lgkmcnt(0)
	s_barrier
	v_mfma_f32_16x16x32_f16 v[62:65], v[162:165], v[146:149], v[62:65]
	v_mfma_f32_16x16x32_f16 v[58:61], v[166:169], v[146:149], v[58:61]
	v_mfma_f32_16x16x32_f16 v[54:57], v[170:173], v[146:149], v[54:57]
	v_mfma_f32_16x16x32_f16 v[50:53], v[174:177], v[146:149], v[50:53]
	v_mfma_f32_16x16x32_f16 v[46:49], v[162:165], v[150:153], v[46:49]
	v_mfma_f32_16x16x32_f16 v[42:45], v[166:169], v[150:153], v[42:45]
	v_mfma_f32_16x16x32_f16 v[38:41], v[170:173], v[150:153], v[38:41]
	v_mfma_f32_16x16x32_f16 v[34:37], v[174:177], v[150:153], v[34:37]
	v_mfma_f32_16x16x32_f16 v[30:33], v[162:165], v[154:157], v[30:33]
	v_mfma_f32_16x16x32_f16 v[26:29], v[166:169], v[154:157], v[26:29]
	v_mfma_f32_16x16x32_f16 v[22:25], v[170:173], v[154:157], v[22:25]
	v_mfma_f32_16x16x32_f16 v[18:21], v[174:177], v[154:157], v[18:21]
	v_mfma_f32_16x16x32_f16 v[14:17], v[162:165], v[158:161], v[14:17]
	v_mfma_f32_16x16x32_f16 v[10:13], v[166:169], v[158:161], v[10:13]
	v_mfma_f32_16x16x32_f16 v[6:9], v[170:173], v[158:161], v[6:9]
	v_mfma_f32_16x16x32_f16 v[2:5], v[174:177], v[158:161], v[2:5]
	s_barrier
	s_add_u32 s12, s12, 0x80
	s_addc_u32 s13, s13, 0
	s_add_u32 s14, s14, 0x80
	s_addc_u32 s15, s15, 0
	ds_read_b128 v[130:133], v204 offset:0
	ds_read_b128 v[134:137], v204 offset:2048
	ds_read_b128 v[138:141], v204 offset:4096
	ds_read_b128 v[142:145], v204 offset:6144
	ds_read_b128 v[162:165], v206 offset:32768
	ds_read_b128 v[166:169], v206 offset:34816
	ds_read_b128 v[170:173], v206 offset:36864
	ds_read_b128 v[174:177], v206 offset:38912
	s_waitcnt vmcnt(0) lgkmcnt(0)
	s_barrier
	v_mfma_f32_16x16x32_f16 v[126:129], v[162:165], v[130:133], v[126:129]
	v_mfma_f32_16x16x32_f16 v[122:125], v[166:169], v[130:133], v[122:125]
	v_mfma_f32_16x16x32_f16 v[118:121], v[170:173], v[130:133], v[118:121]
	v_mfma_f32_16x16x32_f16 v[114:117], v[174:177], v[130:133], v[114:117]
	v_mfma_f32_16x16x32_f16 v[110:113], v[162:165], v[134:137], v[110:113]
	v_mfma_f32_16x16x32_f16 v[106:109], v[166:169], v[134:137], v[106:109]
	v_mfma_f32_16x16x32_f16 v[102:105], v[170:173], v[134:137], v[102:105]
	v_mfma_f32_16x16x32_f16 v[98:101], v[174:177], v[134:137], v[98:101]
	v_mfma_f32_16x16x32_f16 v[94:97], v[162:165], v[138:141], v[94:97]
	v_mfma_f32_16x16x32_f16 v[90:93], v[166:169], v[138:141], v[90:93]
	v_mfma_f32_16x16x32_f16 v[86:89], v[170:173], v[138:141], v[86:89]
	v_mfma_f32_16x16x32_f16 v[82:85], v[174:177], v[138:141], v[82:85]
	v_mfma_f32_16x16x32_f16 v[78:81], v[162:165], v[142:145], v[78:81]
	v_mfma_f32_16x16x32_f16 v[74:77], v[166:169], v[142:145], v[74:77]
	v_mfma_f32_16x16x32_f16 v[70:73], v[170:173], v[142:145], v[70:73]
	v_mfma_f32_16x16x32_f16 v[66:69], v[174:177], v[142:145], v[66:69]
	s_barrier
	ds_read_b128 v[146:149], v204 offset:8192
	ds_read_b128 v[150:153], v204 offset:10240
	ds_read_b128 v[154:157], v204 offset:12288
	ds_read_b128 v[158:161], v204 offset:14336
	s_waitcnt lgkmcnt(0)
	s_barrier
	v_mfma_f32_16x16x32_f16 v[62:65], v[162:165], v[146:149], v[62:65]
	v_mfma_f32_16x16x32_f16 v[58:61], v[166:169], v[146:149], v[58:61]
	v_mfma_f32_16x16x32_f16 v[54:57], v[170:173], v[146:149], v[54:57]
	v_mfma_f32_16x16x32_f16 v[50:53], v[174:177], v[146:149], v[50:53]
	v_mfma_f32_16x16x32_f16 v[46:49], v[162:165], v[150:153], v[46:49]
	v_mfma_f32_16x16x32_f16 v[42:45], v[166:169], v[150:153], v[42:45]
	v_mfma_f32_16x16x32_f16 v[38:41], v[170:173], v[150:153], v[38:41]
	v_mfma_f32_16x16x32_f16 v[34:37], v[174:177], v[150:153], v[34:37]
	v_mfma_f32_16x16x32_f16 v[30:33], v[162:165], v[154:157], v[30:33]
	v_mfma_f32_16x16x32_f16 v[26:29], v[166:169], v[154:157], v[26:29]
	v_mfma_f32_16x16x32_f16 v[22:25], v[170:173], v[154:157], v[22:25]
	v_mfma_f32_16x16x32_f16 v[18:21], v[174:177], v[154:157], v[18:21]
	v_mfma_f32_16x16x32_f16 v[14:17], v[162:165], v[158:161], v[14:17]
	v_mfma_f32_16x16x32_f16 v[10:13], v[166:169], v[158:161], v[10:13]
	v_mfma_f32_16x16x32_f16 v[6:9], v[170:173], v[158:161], v[6:9]
	v_mfma_f32_16x16x32_f16 v[2:5], v[174:177], v[158:161], v[2:5]
	s_barrier
	ds_read_b128 v[130:133], v205 offset:0
	ds_read_b128 v[134:137], v205 offset:2048
	ds_read_b128 v[138:141], v205 offset:4096
	ds_read_b128 v[142:145], v205 offset:6144
	ds_read_b128 v[162:165], v207 offset:32768
	ds_read_b128 v[166:169], v207 offset:34816
	ds_read_b128 v[170:173], v207 offset:36864
	ds_read_b128 v[174:177], v207 offset:38912
	s_waitcnt lgkmcnt(0)
	s_barrier
	v_mfma_f32_16x16x32_f16 v[126:129], v[162:165], v[130:133], v[126:129]
	v_mfma_f32_16x16x32_f16 v[122:125], v[166:169], v[130:133], v[122:125]
	v_mfma_f32_16x16x32_f16 v[118:121], v[170:173], v[130:133], v[118:121]
	v_mfma_f32_16x16x32_f16 v[114:117], v[174:177], v[130:133], v[114:117]
	v_mfma_f32_16x16x32_f16 v[110:113], v[162:165], v[134:137], v[110:113]
	v_mfma_f32_16x16x32_f16 v[106:109], v[166:169], v[134:137], v[106:109]
	v_mfma_f32_16x16x32_f16 v[102:105], v[170:173], v[134:137], v[102:105]
	v_mfma_f32_16x16x32_f16 v[98:101], v[174:177], v[134:137], v[98:101]
	v_mfma_f32_16x16x32_f16 v[94:97], v[162:165], v[138:141], v[94:97]
	v_mfma_f32_16x16x32_f16 v[90:93], v[166:169], v[138:141], v[90:93]
	v_mfma_f32_16x16x32_f16 v[86:89], v[170:173], v[138:141], v[86:89]
	v_mfma_f32_16x16x32_f16 v[82:85], v[174:177], v[138:141], v[82:85]
	v_mfma_f32_16x16x32_f16 v[78:81], v[162:165], v[142:145], v[78:81]
	v_mfma_f32_16x16x32_f16 v[74:77], v[166:169], v[142:145], v[74:77]
	v_mfma_f32_16x16x32_f16 v[70:73], v[170:173], v[142:145], v[70:73]
	v_mfma_f32_16x16x32_f16 v[66:69], v[174:177], v[142:145], v[66:69]
	s_barrier
	ds_read_b128 v[146:149], v205 offset:8192
	ds_read_b128 v[150:153], v205 offset:10240
	ds_read_b128 v[154:157], v205 offset:12288
	ds_read_b128 v[158:161], v205 offset:14336
	s_waitcnt lgkmcnt(0)
	s_barrier
	v_mfma_f32_16x16x32_f16 v[62:65], v[162:165], v[146:149], v[62:65]
	v_mfma_f32_16x16x32_f16 v[58:61], v[166:169], v[146:149], v[58:61]
	v_mfma_f32_16x16x32_f16 v[54:57], v[170:173], v[146:149], v[54:57]
	v_mfma_f32_16x16x32_f16 v[50:53], v[174:177], v[146:149], v[50:53]
	v_mfma_f32_16x16x32_f16 v[46:49], v[162:165], v[150:153], v[46:49]
	v_mfma_f32_16x16x32_f16 v[42:45], v[166:169], v[150:153], v[42:45]
	v_mfma_f32_16x16x32_f16 v[38:41], v[170:173], v[150:153], v[38:41]
	v_mfma_f32_16x16x32_f16 v[34:37], v[174:177], v[150:153], v[34:37]
	v_mfma_f32_16x16x32_f16 v[30:33], v[162:165], v[154:157], v[30:33]
	v_mfma_f32_16x16x32_f16 v[26:29], v[166:169], v[154:157], v[26:29]
	v_mfma_f32_16x16x32_f16 v[22:25], v[170:173], v[154:157], v[22:25]
	v_mfma_f32_16x16x32_f16 v[18:21], v[174:177], v[154:157], v[18:21]
	v_mfma_f32_16x16x32_f16 v[14:17], v[162:165], v[158:161], v[14:17]
	v_mfma_f32_16x16x32_f16 v[10:13], v[166:169], v[158:161], v[10:13]
	v_mfma_f32_16x16x32_f16 v[6:9], v[170:173], v[158:161], v[6:9]
	v_mfma_f32_16x16x32_f16 v[2:5], v[174:177], v[158:161], v[2:5]
	s_barrier
	s_cmp_eq_u32 s19, 1
	s_cbranch_scc1 .Lp1_skew1
	s_barrier
.Lp1_skew1:
	s_nop 7
	s_nop 1
	s_mov_b32 s4, s6
	s_mov_b32 s5, s28
	s_cmp_eq_u32 s5, 0
	s_cbranch_scc1 .Lp1_e_gelu
	s_cmp_eq_u32 s5, 1
	s_cbranch_scc1 .Lp1_e_norm
	s_cmp_lt_u32 s5, 5
	s_cbranch_scc1 .Lp1_e_plain
	s_cmp_lt_u32 s5, 7
	s_cbranch_scc1 .Lp1_e_gt
	s_cmp_lt_u32 s5, 9
	s_cbranch_scc1 .Lp1_e_rope
	v_and_b32_e32 v194, 15, v222
	v_bfe_u32 v195, v222, 4, 2
	v_bfe_u32 v196, v222, 6, 2
	v_lshrrev_b32_e32 v197, 8, v222
	v_lshl_or_b32 v198, v197, 7, v194
	v_lshlrev_b32_e32 v199, 2, v195
	v_lshl_or_b32 v199, v196, 6, v199
	s_lshr_b32 s2, s4, 3
	s_and_b32 s3, s4, 7
	s_lshl_b32 s3, s3, 9
	s_add_i32 s7, s4, 0xffffff80
	s_mul_i32 s2, s2, 0x120000
	s_add_i32 s2, s2, s3
	s_addk_i32 s2, 0x200
	s_mul_i32 s7, s7, 0x120000
	s_cmp_lt_u32 s4, 0x80
	s_cselect_b32 s2, s2, s7
	s_add_i32 s2, s2, 0x13aae500
	s_movk_i32 s7, 0x1200
	v_readlane_b32 s22, v254, 14
	v_readlane_b32 s23, v254, 15
	s_nop 3
	s_add_u32 s22, s22, s2
	s_addc_u32 s23, s23, 0
	v_and_b32_e32 v190, 63, v222
	v_lshrrev_b32_e32 v191, 3, v190
	v_and_b32_e32 v192, 7, v190
	v_lshl_or_b32 v193, v196, 6, v191
	v_mul_lo_u32 v193, v193, s7
	v_lshlrev_b32_e32 v189, 4, v192
	v_lshl_add_u32 v189, v197, 8, v189
	v_add_u32_e32 v193, v193, v189
	v_lshrrev_b32_e32 v188, 6, v222
	v_mul_u32_u24_e32 v188, 0x2400, v188
	v_add_u32_e32 v188, 0x10000, v188
	v_mul_u32_u24_e32 v189, 0x90, v191
	v_lshl_add_u32 v189, v192, 4, v189
	v_add_u32_e32 v189, v189, v188
	v_mul_u32_u24_e32 v187, 0x240, v195
	v_lshl_add_u32 v187, v194, 1, v187
	v_add_u32_e32 v187, v187, v188
	s_add_i32 s2, s53, s95
	s_cmp_lt_i32 s2, s9
	s_cselect_b32 s21, 1, 0
	s_cselect_b32 s53, s2, s53
	s_lshr_b32 s2, s53, 5
	s_mul_hi_u32 s2, s2, 0xcccccccd
	s_lshr_b32 s2, s2, 2
	s_lshl_b32 s3, s2, 4
	s_mul_i32 s2, s2, 0xa0
	s_sub_i32 s2, s53, s2
	s_lshr_b32 s2, s2, 4
	s_and_b32 s6, s53, 15
	s_add_i32 s3, s3, s6
	s_sub_i32 s28, s53, s58
	s_lshr_b32 s28, s28, 4
	s_add_i32 s28, s28, 8
	s_or_b32 s6, s6, 0x80
	s_cmp_ge_i32 s53, s58
	s_cselect_b32 s6, s6, s3
	s_cselect_b32 s28, s28, s2
	s_lshl_b32 s2, s6, 19
	s_add_u32 s12, s64, s2
	s_addc_u32 s13, s65, 0
	s_lshl_b32 s2, s28, 19
	s_add_u32 s14, s34, s2
	s_addc_u32 s15, s35, 0
	s_mov_b32 m0, s18
	s_nop 0
	global_load_lds_dwordx4 v1, s[12:13]
	s_add_i32 m0, s18, 0x2000
	s_add_u32 s16, s12, 0x20000
	s_addc_u32 s17, s13, 0
	global_load_lds_dwordx4 v1, s[16:17]
	s_add_i32 m0, s18, 0x4000
	s_add_u32 s16, s12, 0x40000
	s_addc_u32 s17, s13, 0
	global_load_lds_dwordx4 v1, s[16:17]
	s_add_i32 m0, s18, 0x6000
	s_add_u32 s16, s12, 0x60000
	s_addc_u32 s17, s13, 0
	global_load_lds_dwordx4 v1, s[16:17]
	s_add_i32 m0, s18, 0x8000
	s_nop 0
	global_load_lds_dwordx4 v1, s[14:15]
	s_add_i32 m0, s18, 0xa000
	s_add_u32 s16, s14, 0x20000
	s_addc_u32 s17, s15, 0
	global_load_lds_dwordx4 v1, s[16:17]
	s_add_i32 m0, s18, 0xc000
	s_add_u32 s16, s14, 0x40000
	s_addc_u32 s17, s15, 0
	global_load_lds_dwordx4 v1, s[16:17]
	s_add_i32 m0, s18, 0xe000
	s_add_u32 s16, s14, 0x60000
	s_addc_u32 s17, s15, 0
	global_load_lds_dwordx4 v1, s[16:17]
	s_lshl_b32 s3, s7, 3
	v_cvt_pk_f16_f32 v130, v126, v127
	ds_write_b16 v187, v130 offset:0
	ds_write_b16_d16_hi v187, v130 offset:144
	v_cvt_pk_f16_f32 v131, v128, v129
	ds_write_b16 v187, v131 offset:288
	ds_write_b16_d16_hi v187, v131 offset:432
	v_cvt_pk_f16_f32 v132, v122, v123
	ds_write_b16 v187, v132 offset:2304
	ds_write_b16_d16_hi v187, v132 offset:2448
	v_cvt_pk_f16_f32 v133, v124, v125
	ds_write_b16 v187, v133 offset:2592
	ds_write_b16_d16_hi v187, v133 offset:2736
	v_cvt_pk_f16_f32 v134, v118, v119
	ds_write_b16 v187, v134 offset:4608
	ds_write_b16_d16_hi v187, v134 offset:4752
	v_cvt_pk_f16_f32 v135, v120, v121
	ds_write_b16 v187, v135 offset:4896
	ds_write_b16_d16_hi v187, v135 offset:5040
	v_cvt_pk_f16_f32 v136, v114, v115
	ds_write_b16 v187, v136 offset:6912
	ds_write_b16_d16_hi v187, v136 offset:7056
	v_cvt_pk_f16_f32 v137, v116, v117
	ds_write_b16 v187, v137 offset:7200
	ds_write_b16_d16_hi v187, v137 offset:7344
	v_cvt_pk_f16_f32 v130, v110, v111
	ds_write_b16 v187, v130 offset:32
	ds_write_b16_d16_hi v187, v130 offset:176
	v_cvt_pk_f16_f32 v131, v112, v113
	ds_write_b16 v187, v131 offset:320
	ds_write_b16_d16_hi v187, v131 offset:464
	v_cvt_pk_f16_f32 v132, v106, v107
	ds_write_b16 v187, v132 offset:2336
	ds_write_b16_d16_hi v187, v132 offset:2480
	v_cvt_pk_f16_f32 v133, v108, v109
	ds_write_b16 v187, v133 offset:2624
	ds_write_b16_d16_hi v187, v133 offset:2768
	v_cvt_pk_f16_f32 v134, v102, v103
	ds_write_b16 v187, v134 offset:4640
	ds_write_b16_d16_hi v187, v134 offset:4784
	v_cvt_pk_f16_f32 v135, v104, v105
	ds_write_b16 v187, v135 offset:4928
	ds_write_b16_d16_hi v187, v135 offset:5072
	v_cvt_pk_f16_f32 v136, v98, v99
	ds_write_b16 v187, v136 offset:6944
	ds_write_b16_d16_hi v187, v136 offset:7088
	v_cvt_pk_f16_f32 v137, v100, v101
	ds_write_b16 v187, v137 offset:7232
	ds_write_b16_d16_hi v187, v137 offset:7376
	v_cvt_pk_f16_f32 v130, v94, v95
	ds_write_b16 v187, v130 offset:64
	ds_write_b16_d16_hi v187, v130 offset:208
	v_cvt_pk_f16_f32 v131, v96, v97
	ds_write_b16 v187, v131 offset:352
	ds_write_b16_d16_hi v187, v131 offset:496
	v_cvt_pk_f16_f32 v132, v90, v91
	ds_write_b16 v187, v132 offset:2368
	ds_write_b16_d16_hi v187, v132 offset:2512
	v_cvt_pk_f16_f32 v133, v92, v93
	ds_write_b16 v187, v133 offset:2656
	ds_write_b16_d16_hi v187, v133 offset:2800
	v_cvt_pk_f16_f32 v134, v86, v87
	ds_write_b16 v187, v134 offset:4672
	ds_write_b16_d16_hi v187, v134 offset:4816
	v_cvt_pk_f16_f32 v135, v88, v89
	ds_write_b16 v187, v135 offset:4960
	ds_write_b16_d16_hi v187, v135 offset:5104
	v_cvt_pk_f16_f32 v136, v82, v83
	ds_write_b16 v187, v136 offset:6976
	ds_write_b16_d16_hi v187, v136 offset:7120
	v_cvt_pk_f16_f32 v137, v84, v85
	ds_write_b16 v187, v137 offset:7264
	ds_write_b16_d16_hi v187, v137 offset:7408
	v_cvt_pk_f16_f32 v130, v78, v79
	ds_write_b16 v187, v130 offset:96
	ds_write_b16_d16_hi v187, v130 offset:240
	v_cvt_pk_f16_f32 v131, v80, v81
	ds_write_b16 v187, v131 offset:384
	ds_write_b16_d16_hi v187, v131 offset:528
	v_cvt_pk_f16_f32 v132, v74, v75
	ds_write_b16 v187, v132 offset:2400
	ds_write_b16_d16_hi v187, v132 offset:2544
	v_cvt_pk_f16_f32 v133, v76, v77
	ds_write_b16 v187, v133 offset:2688
	ds_write_b16_d16_hi v187, v133 offset:2832
	v_cvt_pk_f16_f32 v134, v70, v71
	ds_write_b16 v187, v134 offset:4704
	ds_write_b16_d16_hi v187, v134 offset:4848
	v_cvt_pk_f16_f32 v135, v72, v73
	ds_write_b16 v187, v135 offset:4992
	ds_write_b16_d16_hi v187, v135 offset:5136
	v_cvt_pk_f16_f32 v136, v66, v67
	ds_write_b16 v187, v136 offset:7008
	ds_write_b16_d16_hi v187, v136 offset:7152
	v_cvt_pk_f16_f32 v137, v68, v69
	ds_write_b16 v187, v137 offset:7296
	ds_write_b16_d16_hi v187, v137 offset:7440
	s_waitcnt lgkmcnt(0)
	ds_read_b128 v[152:155], v189 offset:0
	ds_read_b128 v[156:159], v189 offset:1152
	ds_read_b128 v[160:163], v189 offset:2304
	ds_read_b128 v[164:167], v189 offset:3456
	ds_read_b128 v[168:171], v189 offset:4608
	ds_read_b128 v[172:175], v189 offset:5760
	ds_read_b128 v[176:179], v189 offset:6912
	ds_read_b128 v[180:183], v189 offset:8064
	s_waitcnt lgkmcnt(7)
	global_store_dwordx4 v193, v[152:155], s[22:23]
	v_add_u32_e32 v193, s3, v193
	s_waitcnt lgkmcnt(6)
	global_store_dwordx4 v193, v[156:159], s[22:23]
	v_add_u32_e32 v193, s3, v193
	s_waitcnt lgkmcnt(5)
	global_store_dwordx4 v193, v[160:163], s[22:23]
	v_add_u32_e32 v193, s3, v193
	s_waitcnt lgkmcnt(4)
	global_store_dwordx4 v193, v[164:167], s[22:23]
	v_add_u32_e32 v193, s3, v193
	s_waitcnt lgkmcnt(3)
	global_store_dwordx4 v193, v[168:171], s[22:23]
	v_add_u32_e32 v193, s3, v193
	s_waitcnt lgkmcnt(2)
	global_store_dwordx4 v193, v[172:175], s[22:23]
	v_add_u32_e32 v193, s3, v193
	s_waitcnt lgkmcnt(1)
	global_store_dwordx4 v193, v[176:179], s[22:23]
	v_add_u32_e32 v193, s3, v193
	s_waitcnt lgkmcnt(0)
	global_store_dwordx4 v193, v[180:183], s[22:23]
	s_lshl_b32 s2, s3, 3
	s_sub_i32 s2, 0x80, s2
	s_add_i32 s2, s2, s3
	v_add_u32_e32 v193, s2, v193
	v_cvt_pk_f16_f32 v130, v62, v63
	ds_write_b16 v187, v130 offset:0
	ds_write_b16_d16_hi v187, v130 offset:144
	v_cvt_pk_f16_f32 v131, v64, v65
	ds_write_b16 v187, v131 offset:288
	ds_write_b16_d16_hi v187, v131 offset:432
	v_cvt_pk_f16_f32 v132, v58, v59
	ds_write_b16 v187, v132 offset:2304
	ds_write_b16_d16_hi v187, v132 offset:2448
	v_cvt_pk_f16_f32 v133, v60, v61
	ds_write_b16 v187, v133 offset:2592
	ds_write_b16_d16_hi v187, v133 offset:2736
	v_cvt_pk_f16_f32 v134, v54, v55
	ds_write_b16 v187, v134 offset:4608
	ds_write_b16_d16_hi v187, v134 offset:4752
	v_cvt_pk_f16_f32 v135, v56, v57
	ds_write_b16 v187, v135 offset:4896
	ds_write_b16_d16_hi v187, v135 offset:5040
	v_cvt_pk_f16_f32 v136, v50, v51
	ds_write_b16 v187, v136 offset:6912
	ds_write_b16_d16_hi v187, v136 offset:7056
	v_cvt_pk_f16_f32 v137, v52, v53
	ds_write_b16 v187, v137 offset:7200
	ds_write_b16_d16_hi v187, v137 offset:7344
	v_cvt_pk_f16_f32 v130, v46, v47
	ds_write_b16 v187, v130 offset:32
	ds_write_b16_d16_hi v187, v130 offset:176
	v_cvt_pk_f16_f32 v131, v48, v49
	ds_write_b16 v187, v131 offset:320
	ds_write_b16_d16_hi v187, v131 offset:464
	v_cvt_pk_f16_f32 v132, v42, v43
	ds_write_b16 v187, v132 offset:2336
	ds_write_b16_d16_hi v187, v132 offset:2480
	v_cvt_pk_f16_f32 v133, v44, v45
	ds_write_b16 v187, v133 offset:2624
	ds_write_b16_d16_hi v187, v133 offset:2768
	v_cvt_pk_f16_f32 v134, v38, v39
	ds_write_b16 v187, v134 offset:4640
	ds_write_b16_d16_hi v187, v134 offset:4784
	v_cvt_pk_f16_f32 v135, v40, v41
	ds_write_b16 v187, v135 offset:4928
	ds_write_b16_d16_hi v187, v135 offset:5072
	v_cvt_pk_f16_f32 v136, v34, v35
	ds_write_b16 v187, v136 offset:6944
	ds_write_b16_d16_hi v187, v136 offset:7088
	v_cvt_pk_f16_f32 v137, v36, v37
	ds_write_b16 v187, v137 offset:7232
	ds_write_b16_d16_hi v187, v137 offset:7376
	v_cvt_pk_f16_f32 v130, v30, v31
	ds_write_b16 v187, v130 offset:64
	ds_write_b16_d16_hi v187, v130 offset:208
	v_cvt_pk_f16_f32 v131, v32, v33
	ds_write_b16 v187, v131 offset:352
	ds_write_b16_d16_hi v187, v131 offset:496
	v_cvt_pk_f16_f32 v132, v26, v27
	ds_write_b16 v187, v132 offset:2368
	ds_write_b16_d16_hi v187, v132 offset:2512
	v_cvt_pk_f16_f32 v133, v28, v29
	ds_write_b16 v187, v133 offset:2656
	ds_write_b16_d16_hi v187, v133 offset:2800
	v_cvt_pk_f16_f32 v134, v22, v23
	ds_write_b16 v187, v134 offset:4672
	ds_write_b16_d16_hi v187, v134 offset:4816
	v_cvt_pk_f16_f32 v135, v24, v25
	ds_write_b16 v187, v135 offset:4960
	ds_write_b16_d16_hi v187, v135 offset:5104
	v_cvt_pk_f16_f32 v136, v18, v19
	ds_write_b16 v187, v136 offset:6976
	ds_write_b16_d16_hi v187, v136 offset:7120
	v_cvt_pk_f16_f32 v137, v20, v21
	ds_write_b16 v187, v137 offset:7264
	ds_write_b16_d16_hi v187, v137 offset:7408
	v_cvt_pk_f16_f32 v130, v14, v15
	ds_write_b16 v187, v130 offset:96
	ds_write_b16_d16_hi v187, v130 offset:240
	v_cvt_pk_f16_f32 v131, v16, v17
	ds_write_b16 v187, v131 offset:384
	ds_write_b16_d16_hi v187, v131 offset:528
	v_cvt_pk_f16_f32 v132, v10, v11
	ds_write_b16 v187, v132 offset:2400
	ds_write_b16_d16_hi v187, v132 offset:2544
	v_cvt_pk_f16_f32 v133, v12, v13
	ds_write_b16 v187, v133 offset:2688
	ds_write_b16_d16_hi v187, v133 offset:2832
	v_cvt_pk_f16_f32 v134, v6, v7
	ds_write_b16 v187, v134 offset:4704
	ds_write_b16_d16_hi v187, v134 offset:4848
	v_cvt_pk_f16_f32 v135, v8, v9
	ds_write_b16 v187, v135 offset:4992
	ds_write_b16_d16_hi v187, v135 offset:5136
	v_cvt_pk_f16_f32 v136, v2, v3
	ds_write_b16 v187, v136 offset:7008
	ds_write_b16_d16_hi v187, v136 offset:7152
	v_cvt_pk_f16_f32 v137, v4, v5
	ds_write_b16 v187, v137 offset:7296
	ds_write_b16_d16_hi v187, v137 offset:7440
	s_waitcnt lgkmcnt(0)
	ds_read_b128 v[152:155], v189 offset:0
	ds_read_b128 v[156:159], v189 offset:1152
	ds_read_b128 v[160:163], v189 offset:2304
	ds_read_b128 v[164:167], v189 offset:3456
	ds_read_b128 v[168:171], v189 offset:4608
	ds_read_b128 v[172:175], v189 offset:5760
	ds_read_b128 v[176:179], v189 offset:6912
	ds_read_b128 v[180:183], v189 offset:8064
	s_waitcnt lgkmcnt(7)
	global_store_dwordx4 v193, v[152:155], s[22:23]
	v_add_u32_e32 v193, s3, v193
	s_waitcnt lgkmcnt(6)
	global_store_dwordx4 v193, v[156:159], s[22:23]
	v_add_u32_e32 v193, s3, v193
	s_waitcnt lgkmcnt(5)
	global_store_dwordx4 v193, v[160:163], s[22:23]
	v_add_u32_e32 v193, s3, v193
	s_waitcnt lgkmcnt(4)
	global_store_dwordx4 v193, v[164:167], s[22:23]
	v_add_u32_e32 v193, s3, v193
	s_waitcnt lgkmcnt(3)
	global_store_dwordx4 v193, v[168:171], s[22:23]
	v_add_u32_e32 v193, s3, v193
	s_waitcnt lgkmcnt(2)
	global_store_dwordx4 v193, v[172:175], s[22:23]
	v_add_u32_e32 v193, s3, v193
	s_waitcnt lgkmcnt(1)
	global_store_dwordx4 v193, v[176:179], s[22:23]
	v_add_u32_e32 v193, s3, v193
	s_waitcnt lgkmcnt(0)
	global_store_dwordx4 v193, v[180:183], s[22:23]
	s_waitcnt vmcnt(16)
	s_branch .Lp1_join
.Lp1_e_gt:
	v_and_b32_e32 v194, 15, v222
	v_bfe_u32 v195, v222, 4, 2
	v_bfe_u32 v196, v222, 6, 2
	v_lshrrev_b32_e32 v197, 8, v222
	v_lshl_or_b32 v198, v197, 7, v194
	v_lshlrev_b32_e32 v199, 2, v195
	v_lshl_or_b32 v199, v196, 6, v199
	s_lshr_b32 s2, s4, 3
	s_and_b32 s3, s4, 7
	s_lshl_b32 s3, s3, 9
	s_add_i32 s7, s4, 0xffffff80
	s_lshl_b32 s2, s2, 21
	s_add_i32 s2, s2, s3
	s_add_i32 s2, s2, 0xf2ae500
	s_lshl_b32 s7, s7, 18
	s_add_i32 s7, s7, 0x112ae500
	s_cmp_eq_u32 s5, 6
	s_cselect_b32 s3, 0x1000, 0
	s_add_i32 s2, s2, s3
	s_lshr_b32 s3, s3, 3
	s_add_i32 s7, s7, s3
	s_cmp_lt_u32 s4, 0x80
	s_cselect_b32 s2, s2, s7
	s_movk_i32 s7, 0x400
	s_cselect_b32 s7, 0x2000, s7
	v_readlane_b32 s22, v254, 14
	v_readlane_b32 s23, v254, 15
	s_nop 3
	s_add_u32 s22, s22, s2
	s_addc_u32 s23, s23, 0
	v_and_b32_e32 v190, 63, v222
	v_lshrrev_b32_e32 v191, 3, v190
	v_and_b32_e32 v192, 7, v190
	v_lshl_or_b32 v193, v196, 6, v191
	v_mul_lo_u32 v193, v193, s7
	v_lshlrev_b32_e32 v189, 4, v192
	v_lshl_add_u32 v189, v197, 8, v189
	v_add_u32_e32 v193, v193, v189
	v_lshrrev_b32_e32 v188, 6, v222
	v_mul_u32_u24_e32 v188, 0x2400, v188
	v_add_u32_e32 v188, 0x10000, v188
	v_mul_u32_u24_e32 v189, 0x90, v191
	v_lshl_add_u32 v189, v192, 4, v189
	v_add_u32_e32 v189, v189, v188
	v_mul_u32_u24_e32 v187, 0x240, v195
	v_lshl_add_u32 v187, v194, 1, v187
	v_add_u32_e32 v187, v187, v188
	s_add_i32 s2, s53, s95
	s_cmp_lt_i32 s2, s9
	s_cselect_b32 s21, 1, 0
	s_cselect_b32 s53, s2, s53
	s_lshr_b32 s2, s53, 5
	s_mul_hi_u32 s2, s2, 0xcccccccd
	s_lshr_b32 s2, s2, 2
	s_lshl_b32 s3, s2, 4
	s_mul_i32 s2, s2, 0xa0
	s_sub_i32 s2, s53, s2
	s_lshr_b32 s2, s2, 4
	s_and_b32 s6, s53, 15
	s_add_i32 s3, s3, s6
	s_sub_i32 s28, s53, s58
	s_lshr_b32 s28, s28, 4
	s_add_i32 s28, s28, 8
	s_or_b32 s6, s6, 0x80
	s_cmp_ge_i32 s53, s58
	s_cselect_b32 s6, s6, s3
	s_cselect_b32 s28, s28, s2
	s_lshl_b32 s2, s6, 19
	s_add_u32 s12, s64, s2
	s_addc_u32 s13, s65, 0
	s_lshl_b32 s2, s28, 19
	s_add_u32 s14, s34, s2
	s_addc_u32 s15, s35, 0
	s_mov_b32 m0, s18
	s_nop 0
	global_load_lds_dwordx4 v1, s[12:13]
	s_add_i32 m0, s18, 0x2000
	s_add_u32 s16, s12, 0x20000
	s_addc_u32 s17, s13, 0
	global_load_lds_dwordx4 v1, s[16:17]
	s_add_i32 m0, s18, 0x4000
	s_add_u32 s16, s12, 0x40000
	s_addc_u32 s17, s13, 0
	global_load_lds_dwordx4 v1, s[16:17]
	s_add_i32 m0, s18, 0x6000
	s_add_u32 s16, s12, 0x60000
	s_addc_u32 s17, s13, 0
	global_load_lds_dwordx4 v1, s[16:17]
	s_add_i32 m0, s18, 0x8000
	s_nop 0
	global_load_lds_dwordx4 v1, s[14:15]
	s_add_i32 m0, s18, 0xa000
	s_add_u32 s16, s14, 0x20000
	s_addc_u32 s17, s15, 0
	global_load_lds_dwordx4 v1, s[16:17]
	s_add_i32 m0, s18, 0xc000
	s_add_u32 s16, s14, 0x40000
	s_addc_u32 s17, s15, 0
	global_load_lds_dwordx4 v1, s[16:17]
	s_add_i32 m0, s18, 0xe000
	s_add_u32 s16, s14, 0x60000
	s_addc_u32 s17, s15, 0
	global_load_lds_dwordx4 v1, s[16:17]
	s_lshl_b32 s3, s7, 3
	v_cvt_pk_f16_f32 v130, v126, v127
	ds_write_b16 v187, v130 offset:0
	ds_write_b16_d16_hi v187, v130 offset:144
	v_cvt_pk_f16_f32 v131, v128, v129
	ds_write_b16 v187, v131 offset:288
	ds_write_b16_d16_hi v187, v131 offset:432
	v_cvt_pk_f16_f32 v132, v122, v123
	ds_write_b16 v187, v132 offset:2304
	ds_write_b16_d16_hi v187, v132 offset:2448
	v_cvt_pk_f16_f32 v133, v124, v125
	ds_write_b16 v187, v133 offset:2592
	ds_write_b16_d16_hi v187, v133 offset:2736
	v_cvt_pk_f16_f32 v134, v118, v119
	ds_write_b16 v187, v134 offset:4608
	ds_write_b16_d16_hi v187, v134 offset:4752
	v_cvt_pk_f16_f32 v135, v120, v121
	ds_write_b16 v187, v135 offset:4896
	ds_write_b16_d16_hi v187, v135 offset:5040
	v_cvt_pk_f16_f32 v136, v114, v115
	ds_write_b16 v187, v136 offset:6912
	ds_write_b16_d16_hi v187, v136 offset:7056
	v_cvt_pk_f16_f32 v137, v116, v117
	ds_write_b16 v187, v137 offset:7200
	ds_write_b16_d16_hi v187, v137 offset:7344
	v_cvt_pk_f16_f32 v130, v110, v111
	ds_write_b16 v187, v130 offset:32
	ds_write_b16_d16_hi v187, v130 offset:176
	v_cvt_pk_f16_f32 v131, v112, v113
	ds_write_b16 v187, v131 offset:320
	ds_write_b16_d16_hi v187, v131 offset:464
	v_cvt_pk_f16_f32 v132, v106, v107
	ds_write_b16 v187, v132 offset:2336
	ds_write_b16_d16_hi v187, v132 offset:2480
	v_cvt_pk_f16_f32 v133, v108, v109
	ds_write_b16 v187, v133 offset:2624
	ds_write_b16_d16_hi v187, v133 offset:2768
	v_cvt_pk_f16_f32 v134, v102, v103
	ds_write_b16 v187, v134 offset:4640
	ds_write_b16_d16_hi v187, v134 offset:4784
	v_cvt_pk_f16_f32 v135, v104, v105
	ds_write_b16 v187, v135 offset:4928
	ds_write_b16_d16_hi v187, v135 offset:5072
	v_cvt_pk_f16_f32 v136, v98, v99
	ds_write_b16 v187, v136 offset:6944
	ds_write_b16_d16_hi v187, v136 offset:7088
	v_cvt_pk_f16_f32 v137, v100, v101
	ds_write_b16 v187, v137 offset:7232
	ds_write_b16_d16_hi v187, v137 offset:7376
	v_cvt_pk_f16_f32 v130, v94, v95
	ds_write_b16 v187, v130 offset:64
	ds_write_b16_d16_hi v187, v130 offset:208
	v_cvt_pk_f16_f32 v131, v96, v97
	ds_write_b16 v187, v131 offset:352
	ds_write_b16_d16_hi v187, v131 offset:496
	v_cvt_pk_f16_f32 v132, v90, v91
	ds_write_b16 v187, v132 offset:2368
	ds_write_b16_d16_hi v187, v132 offset:2512
	v_cvt_pk_f16_f32 v133, v92, v93
	ds_write_b16 v187, v133 offset:2656
	ds_write_b16_d16_hi v187, v133 offset:2800
	v_cvt_pk_f16_f32 v134, v86, v87
	ds_write_b16 v187, v134 offset:4672
	ds_write_b16_d16_hi v187, v134 offset:4816
	v_cvt_pk_f16_f32 v135, v88, v89
	ds_write_b16 v187, v135 offset:4960
	ds_write_b16_d16_hi v187, v135 offset:5104
	v_cvt_pk_f16_f32 v136, v82, v83
	ds_write_b16 v187, v136 offset:6976
	ds_write_b16_d16_hi v187, v136 offset:7120
	v_cvt_pk_f16_f32 v137, v84, v85
	ds_write_b16 v187, v137 offset:7264
	ds_write_b16_d16_hi v187, v137 offset:7408
	v_cvt_pk_f16_f32 v130, v78, v79
	ds_write_b16 v187, v130 offset:96
	ds_write_b16_d16_hi v187, v130 offset:240
	v_cvt_pk_f16_f32 v131, v80, v81
	ds_write_b16 v187, v131 offset:384
	ds_write_b16_d16_hi v187, v131 offset:528
	v_cvt_pk_f16_f32 v132, v74, v75
	ds_write_b16 v187, v132 offset:2400
	ds_write_b16_d16_hi v187, v132 offset:2544
	v_cvt_pk_f16_f32 v133, v76, v77
	ds_write_b16 v187, v133 offset:2688
	ds_write_b16_d16_hi v187, v133 offset:2832
	v_cvt_pk_f16_f32 v134, v70, v71
	ds_write_b16 v187, v134 offset:4704
	ds_write_b16_d16_hi v187, v134 offset:4848
	v_cvt_pk_f16_f32 v135, v72, v73
	ds_write_b16 v187, v135 offset:4992
	ds_write_b16_d16_hi v187, v135 offset:5136
	v_cvt_pk_f16_f32 v136, v66, v67
	ds_write_b16 v187, v136 offset:7008
	ds_write_b16_d16_hi v187, v136 offset:7152
	v_cvt_pk_f16_f32 v137, v68, v69
	ds_write_b16 v187, v137 offset:7296
	ds_write_b16_d16_hi v187, v137 offset:7440
	s_waitcnt lgkmcnt(0)
	ds_read_b128 v[152:155], v189 offset:0
	ds_read_b128 v[156:159], v189 offset:1152
	ds_read_b128 v[160:163], v189 offset:2304
	ds_read_b128 v[164:167], v189 offset:3456
	ds_read_b128 v[168:171], v189 offset:4608
	ds_read_b128 v[172:175], v189 offset:5760
	ds_read_b128 v[176:179], v189 offset:6912
	ds_read_b128 v[180:183], v189 offset:8064
	s_waitcnt lgkmcnt(7)
	global_store_dwordx4 v193, v[152:155], s[22:23]
	v_add_u32_e32 v193, s3, v193
	s_waitcnt lgkmcnt(6)
	global_store_dwordx4 v193, v[156:159], s[22:23]
	v_add_u32_e32 v193, s3, v193
	s_waitcnt lgkmcnt(5)
	global_store_dwordx4 v193, v[160:163], s[22:23]
	v_add_u32_e32 v193, s3, v193
	s_waitcnt lgkmcnt(4)
	global_store_dwordx4 v193, v[164:167], s[22:23]
	v_add_u32_e32 v193, s3, v193
	s_waitcnt lgkmcnt(3)
	global_store_dwordx4 v193, v[168:171], s[22:23]
	v_add_u32_e32 v193, s3, v193
	s_waitcnt lgkmcnt(2)
	global_store_dwordx4 v193, v[172:175], s[22:23]
	v_add_u32_e32 v193, s3, v193
	s_waitcnt lgkmcnt(1)
	global_store_dwordx4 v193, v[176:179], s[22:23]
	v_add_u32_e32 v193, s3, v193
	s_waitcnt lgkmcnt(0)
	global_store_dwordx4 v193, v[180:183], s[22:23]
	s_lshl_b32 s2, s3, 3
	s_sub_i32 s2, 0x80, s2
	s_add_i32 s2, s2, s3
	v_add_u32_e32 v193, s2, v193
	v_cvt_pk_f16_f32 v130, v62, v63
	ds_write_b16 v187, v130 offset:0
	ds_write_b16_d16_hi v187, v130 offset:144
	v_cvt_pk_f16_f32 v131, v64, v65
	ds_write_b16 v187, v131 offset:288
	ds_write_b16_d16_hi v187, v131 offset:432
	v_cvt_pk_f16_f32 v132, v58, v59
	ds_write_b16 v187, v132 offset:2304
	ds_write_b16_d16_hi v187, v132 offset:2448
	v_cvt_pk_f16_f32 v133, v60, v61
	ds_write_b16 v187, v133 offset:2592
	ds_write_b16_d16_hi v187, v133 offset:2736
	v_cvt_pk_f16_f32 v134, v54, v55
	ds_write_b16 v187, v134 offset:4608
	ds_write_b16_d16_hi v187, v134 offset:4752
	v_cvt_pk_f16_f32 v135, v56, v57
	ds_write_b16 v187, v135 offset:4896
	ds_write_b16_d16_hi v187, v135 offset:5040
	v_cvt_pk_f16_f32 v136, v50, v51
	ds_write_b16 v187, v136 offset:6912
	ds_write_b16_d16_hi v187, v136 offset:7056
	v_cvt_pk_f16_f32 v137, v52, v53
	ds_write_b16 v187, v137 offset:7200
	ds_write_b16_d16_hi v187, v137 offset:7344
	v_cvt_pk_f16_f32 v130, v46, v47
	ds_write_b16 v187, v130 offset:32
	ds_write_b16_d16_hi v187, v130 offset:176
	v_cvt_pk_f16_f32 v131, v48, v49
	ds_write_b16 v187, v131 offset:320
	ds_write_b16_d16_hi v187, v131 offset:464
	v_cvt_pk_f16_f32 v132, v42, v43
	ds_write_b16 v187, v132 offset:2336
	ds_write_b16_d16_hi v187, v132 offset:2480
	v_cvt_pk_f16_f32 v133, v44, v45
	ds_write_b16 v187, v133 offset:2624
	ds_write_b16_d16_hi v187, v133 offset:2768
	v_cvt_pk_f16_f32 v134, v38, v39
	ds_write_b16 v187, v134 offset:4640
	ds_write_b16_d16_hi v187, v134 offset:4784
	v_cvt_pk_f16_f32 v135, v40, v41
	ds_write_b16 v187, v135 offset:4928
	ds_write_b16_d16_hi v187, v135 offset:5072
	v_cvt_pk_f16_f32 v136, v34, v35
	ds_write_b16 v187, v136 offset:6944
	ds_write_b16_d16_hi v187, v136 offset:7088
	v_cvt_pk_f16_f32 v137, v36, v37
	ds_write_b16 v187, v137 offset:7232
	ds_write_b16_d16_hi v187, v137 offset:7376
	v_cvt_pk_f16_f32 v130, v30, v31
	ds_write_b16 v187, v130 offset:64
	ds_write_b16_d16_hi v187, v130 offset:208
	v_cvt_pk_f16_f32 v131, v32, v33
	ds_write_b16 v187, v131 offset:352
	ds_write_b16_d16_hi v187, v131 offset:496
	v_cvt_pk_f16_f32 v132, v26, v27
	ds_write_b16 v187, v132 offset:2368
	ds_write_b16_d16_hi v187, v132 offset:2512
	v_cvt_pk_f16_f32 v133, v28, v29
	ds_write_b16 v187, v133 offset:2656
	ds_write_b16_d16_hi v187, v133 offset:2800
	v_cvt_pk_f16_f32 v134, v22, v23
	ds_write_b16 v187, v134 offset:4672
	ds_write_b16_d16_hi v187, v134 offset:4816
	v_cvt_pk_f16_f32 v135, v24, v25
	ds_write_b16 v187, v135 offset:4960
	ds_write_b16_d16_hi v187, v135 offset:5104
	v_cvt_pk_f16_f32 v136, v18, v19
	ds_write_b16 v187, v136 offset:6976
	ds_write_b16_d16_hi v187, v136 offset:7120
	v_cvt_pk_f16_f32 v137, v20, v21
	ds_write_b16 v187, v137 offset:7264
	ds_write_b16_d16_hi v187, v137 offset:7408
	v_cvt_pk_f16_f32 v130, v14, v15
	ds_write_b16 v187, v130 offset:96
	ds_write_b16_d16_hi v187, v130 offset:240
	v_cvt_pk_f16_f32 v131, v16, v17
	ds_write_b16 v187, v131 offset:384
	ds_write_b16_d16_hi v187, v131 offset:528
	v_cvt_pk_f16_f32 v132, v10, v11
	ds_write_b16 v187, v132 offset:2400
	ds_write_b16_d16_hi v187, v132 offset:2544
	v_cvt_pk_f16_f32 v133, v12, v13
	ds_write_b16 v187, v133 offset:2688
	ds_write_b16_d16_hi v187, v133 offset:2832
	v_cvt_pk_f16_f32 v134, v6, v7
	ds_write_b16 v187, v134 offset:4704
	ds_write_b16_d16_hi v187, v134 offset:4848
	v_cvt_pk_f16_f32 v135, v8, v9
	ds_write_b16 v187, v135 offset:4992
	ds_write_b16_d16_hi v187, v135 offset:5136
	v_cvt_pk_f16_f32 v136, v2, v3
	ds_write_b16 v187, v136 offset:7008
	ds_write_b16_d16_hi v187, v136 offset:7152
	v_cvt_pk_f16_f32 v137, v4, v5
	ds_write_b16 v187, v137 offset:7296
	ds_write_b16_d16_hi v187, v137 offset:7440
	s_waitcnt lgkmcnt(0)
	ds_read_b128 v[152:155], v189 offset:0
	ds_read_b128 v[156:159], v189 offset:1152
	ds_read_b128 v[160:163], v189 offset:2304
	ds_read_b128 v[164:167], v189 offset:3456
	ds_read_b128 v[168:171], v189 offset:4608
	ds_read_b128 v[172:175], v189 offset:5760
	ds_read_b128 v[176:179], v189 offset:6912
	ds_read_b128 v[180:183], v189 offset:8064
	s_waitcnt lgkmcnt(7)
	global_store_dwordx4 v193, v[152:155], s[22:23]
	v_add_u32_e32 v193, s3, v193
	s_waitcnt lgkmcnt(6)
	global_store_dwordx4 v193, v[156:159], s[22:23]
	v_add_u32_e32 v193, s3, v193
	s_waitcnt lgkmcnt(5)
	global_store_dwordx4 v193, v[160:163], s[22:23]
	v_add_u32_e32 v193, s3, v193
	s_waitcnt lgkmcnt(4)
	global_store_dwordx4 v193, v[164:167], s[22:23]
	v_add_u32_e32 v193, s3, v193
	s_waitcnt lgkmcnt(3)
	global_store_dwordx4 v193, v[168:171], s[22:23]
	v_add_u32_e32 v193, s3, v193
	s_waitcnt lgkmcnt(2)
	global_store_dwordx4 v193, v[172:175], s[22:23]
	v_add_u32_e32 v193, s3, v193
	s_waitcnt lgkmcnt(1)
	global_store_dwordx4 v193, v[176:179], s[22:23]
	v_add_u32_e32 v193, s3, v193
	s_waitcnt lgkmcnt(0)
	global_store_dwordx4 v193, v[180:183], s[22:23]
	s_waitcnt vmcnt(16)
	s_branch .Lp1_join
.Lp1_e_norm:
	v_and_b32_e32 v194, 15, v222
	v_bfe_u32 v195, v222, 4, 2
	v_bfe_u32 v196, v222, 6, 2
	v_lshrrev_b32_e32 v197, 8, v222
	v_lshl_or_b32 v198, v197, 7, v194
	v_lshlrev_b32_e32 v199, 2, v195
	v_lshl_or_b32 v199, v196, 6, v199
	s_lshr_b32 s2, s4, 3
	s_and_b32 s3, s4, 7
	s_lshl_b32 s3, s3, 9
	s_add_i32 s7, s4, 0xffffff80
	s_lshl_b32 s2, s2, 18
	s_add_i32 s2, s2, s3
	s_add_i32 s2, s2, 0xaaae500
	s_lshl_b32 s7, s7, 15
	s_add_i32 s7, s7, 0xbaae500
	s_cmp_lt_u32 s4, 0x80
	s_cselect_b32 s2, s2, s7
	s_movk_i32 s7, 0x200
	s_cselect_b32 s7, 0x1000, s7
	v_readlane_b32 s22, v254, 14
	v_readlane_b32 s23, v254, 15
	s_nop 3
	s_add_u32 s22, s22, s2
	s_addc_u32 s23, s23, 0
	v_and_b32_e32 v190, 63, v222
	v_lshrrev_b32_e32 v191, 3, v190
	v_and_b32_e32 v192, 7, v190
	v_lshl_or_b32 v193, v196, 10, v191
	v_mul_lo_u32 v193, v193, s7
	v_lshlrev_b32_e32 v189, 4, v192
	v_lshl_add_u32 v189, v197, 8, v189
	v_add_u32_e32 v193, v193, v189
	v_lshrrev_b32_e32 v188, 6, v222
	v_mul_u32_u24_e32 v188, 0x2400, v188
	v_add_u32_e32 v188, 0x10000, v188
	v_mul_u32_u24_e32 v189, 0x90, v191
	v_lshl_add_u32 v189, v192, 4, v189
	v_add_u32_e32 v189, v189, v188
	v_mul_u32_u24_e32 v187, 0x240, v195
	v_lshl_add_u32 v187, v194, 1, v187
	v_add_u32_e32 v187, v187, v188
	v_xor_b32_e32 v186, 16, v190
	v_lshlrev_b32_e32 v186, 2, v186
	v_xor_b32_e32 v185, 32, v190
	v_lshlrev_b32_e32 v185, 2, v185
	s_add_i32 s2, s53, s95
	s_cmp_lt_i32 s2, s9
	s_cselect_b32 s21, 1, 0
	s_cselect_b32 s53, s2, s53
	s_lshr_b32 s2, s53, 5
	s_mul_hi_u32 s2, s2, 0xcccccccd
	s_lshr_b32 s2, s2, 2
	s_lshl_b32 s3, s2, 4
	s_mul_i32 s2, s2, 0xa0
	s_sub_i32 s2, s53, s2
	s_lshr_b32 s2, s2, 4
	s_and_b32 s6, s53, 15
	s_add_i32 s3, s3, s6
	s_sub_i32 s28, s53, s58
	s_lshr_b32 s28, s28, 4
	s_add_i32 s28, s28, 8
	s_or_b32 s6, s6, 0x80
	s_cmp_ge_i32 s53, s58
	s_cselect_b32 s6, s6, s3
	s_cselect_b32 s28, s28, s2
	s_lshl_b32 s2, s6, 19
	s_add_u32 s12, s64, s2
	s_addc_u32 s13, s65, 0
	s_lshl_b32 s2, s28, 19
	s_add_u32 s14, s34, s2
	s_addc_u32 s15, s35, 0
	s_mov_b32 m0, s18
	s_nop 0
	global_load_lds_dwordx4 v1, s[12:13]
	s_add_i32 m0, s18, 0x2000
	s_add_u32 s16, s12, 0x20000
	s_addc_u32 s17, s13, 0
	global_load_lds_dwordx4 v1, s[16:17]
	s_add_i32 m0, s18, 0x4000
	s_add_u32 s16, s12, 0x40000
	s_addc_u32 s17, s13, 0
	global_load_lds_dwordx4 v1, s[16:17]
	s_add_i32 m0, s18, 0x6000
	s_add_u32 s16, s12, 0x60000
	s_addc_u32 s17, s13, 0
	global_load_lds_dwordx4 v1, s[16:17]
	s_add_i32 m0, s18, 0x8000
	s_nop 0
	global_load_lds_dwordx4 v1, s[14:15]
	s_add_i32 m0, s18, 0xa000
	s_add_u32 s16, s14, 0x20000
	s_addc_u32 s17, s15, 0
	global_load_lds_dwordx4 v1, s[16:17]
	s_add_i32 m0, s18, 0xc000
	s_add_u32 s16, s14, 0x40000
	s_addc_u32 s17, s15, 0
	global_load_lds_dwordx4 v1, s[16:17]
	s_add_i32 m0, s18, 0xe000
	s_add_u32 s16, s14, 0x60000
	s_addc_u32 s17, s15, 0
	global_load_lds_dwordx4 v1, s[16:17]
	s_lshl_b32 s3, s7, 3
	v_mul_f32_e32 v130, 0x3d372713, v126
	v_mul_f32_e32 v131, 0x3d372713, v127
	v_mul_f32_e32 v132, 0x3d372713, v128
	v_mul_f32_e32 v133, 0x3d372713, v129
	v_mul_f32_e32 v130, v126, v130
	v_mul_f32_e32 v131, v127, v131
	v_mul_f32_e32 v132, v128, v132
	v_mul_f32_e32 v133, v129, v133
	v_fma_f32 v130, v126, v130, v126
	v_fma_f32 v131, v127, v131, v127
	v_fma_f32 v132, v128, v132, v128
	v_fma_f32 v133, v129, v133, v129
	v_mul_f32_e32 v130, 0x3f4c422a, v130
	v_mul_f32_e32 v131, 0x3f4c422a, v131
	v_mul_f32_e32 v132, 0x3f4c422a, v132
	v_mul_f32_e32 v133, 0x3f4c422a, v133
	v_mul_f32_e32 v130, -2.0, v130
	v_mul_f32_e32 v131, -2.0, v131
	v_mul_f32_e32 v132, -2.0, v132
	v_mul_f32_e32 v133, -2.0, v133
	v_mul_f32_e32 v130, 0x3fb8aa3b, v130
	v_mul_f32_e32 v131, 0x3fb8aa3b, v131
	v_mul_f32_e32 v132, 0x3fb8aa3b, v132
	v_mul_f32_e32 v133, 0x3fb8aa3b, v133
	v_exp_f32_e32 v130, v130
	v_exp_f32_e32 v131, v131
	v_exp_f32_e32 v132, v132
	v_exp_f32_e32 v133, v133
	v_add_f32_e32 v130, 1.0, v130
	v_add_f32_e32 v131, 1.0, v131
	v_add_f32_e32 v132, 1.0, v132
	v_add_f32_e32 v133, 1.0, v133
	v_rcp_f32_e32 v130, v130
	v_rcp_f32_e32 v131, v131
	v_rcp_f32_e32 v132, v132
	v_rcp_f32_e32 v133, v133
	s_nop 0
	v_mul_f32_e32 v126, v126, v130
	v_mul_f32_e32 v127, v127, v131
	v_mul_f32_e32 v128, v128, v132
	v_mul_f32_e32 v129, v129, v133
	v_mul_f32_e32 v134, 0x3d372713, v122
	v_mul_f32_e32 v135, 0x3d372713, v123
	v_mul_f32_e32 v136, 0x3d372713, v124
	v_mul_f32_e32 v137, 0x3d372713, v125
	v_mul_f32_e32 v134, v122, v134
	v_mul_f32_e32 v135, v123, v135
	v_mul_f32_e32 v136, v124, v136
	v_mul_f32_e32 v137, v125, v137
	v_fma_f32 v134, v122, v134, v122
	v_fma_f32 v135, v123, v135, v123
	v_fma_f32 v136, v124, v136, v124
	v_fma_f32 v137, v125, v137, v125
	v_mul_f32_e32 v134, 0x3f4c422a, v134
	v_mul_f32_e32 v135, 0x3f4c422a, v135
	v_mul_f32_e32 v136, 0x3f4c422a, v136
	v_mul_f32_e32 v137, 0x3f4c422a, v137
	v_mul_f32_e32 v134, -2.0, v134
	v_mul_f32_e32 v135, -2.0, v135
	v_mul_f32_e32 v136, -2.0, v136
	v_mul_f32_e32 v137, -2.0, v137
	v_mul_f32_e32 v134, 0x3fb8aa3b, v134
	v_mul_f32_e32 v135, 0x3fb8aa3b, v135
	v_mul_f32_e32 v136, 0x3fb8aa3b, v136
	v_mul_f32_e32 v137, 0x3fb8aa3b, v137
	v_exp_f32_e32 v134, v134
	v_exp_f32_e32 v135, v135
	v_exp_f32_e32 v136, v136
	v_exp_f32_e32 v137, v137
	v_add_f32_e32 v134, 1.0, v134
	v_add_f32_e32 v135, 1.0, v135
	v_add_f32_e32 v136, 1.0, v136
	v_add_f32_e32 v137, 1.0, v137
	v_rcp_f32_e32 v134, v134
	v_rcp_f32_e32 v135, v135
	v_rcp_f32_e32 v136, v136
	v_rcp_f32_e32 v137, v137
	s_nop 0
	v_mul_f32_e32 v122, v122, v134
	v_mul_f32_e32 v123, v123, v135
	v_mul_f32_e32 v124, v124, v136
	v_mul_f32_e32 v125, v125, v137
	v_mul_f32_e32 v130, 0x3d372713, v118
	v_mul_f32_e32 v131, 0x3d372713, v119
	v_mul_f32_e32 v132, 0x3d372713, v120
	v_mul_f32_e32 v133, 0x3d372713, v121
	v_mul_f32_e32 v130, v118, v130
	v_mul_f32_e32 v131, v119, v131
	v_mul_f32_e32 v132, v120, v132
	v_mul_f32_e32 v133, v121, v133
	v_fma_f32 v130, v118, v130, v118
	v_fma_f32 v131, v119, v131, v119
	v_fma_f32 v132, v120, v132, v120
	v_fma_f32 v133, v121, v133, v121
	v_mul_f32_e32 v130, 0x3f4c422a, v130
	v_mul_f32_e32 v131, 0x3f4c422a, v131
	v_mul_f32_e32 v132, 0x3f4c422a, v132
	v_mul_f32_e32 v133, 0x3f4c422a, v133
	v_mul_f32_e32 v130, -2.0, v130
	v_mul_f32_e32 v131, -2.0, v131
	v_mul_f32_e32 v132, -2.0, v132
	v_mul_f32_e32 v133, -2.0, v133
	v_mul_f32_e32 v130, 0x3fb8aa3b, v130
	v_mul_f32_e32 v131, 0x3fb8aa3b, v131
	v_mul_f32_e32 v132, 0x3fb8aa3b, v132
	v_mul_f32_e32 v133, 0x3fb8aa3b, v133
	v_exp_f32_e32 v130, v130
	v_exp_f32_e32 v131, v131
	v_exp_f32_e32 v132, v132
	v_exp_f32_e32 v133, v133
	v_add_f32_e32 v130, 1.0, v130
	v_add_f32_e32 v131, 1.0, v131
	v_add_f32_e32 v132, 1.0, v132
	v_add_f32_e32 v133, 1.0, v133
	v_rcp_f32_e32 v130, v130
	v_rcp_f32_e32 v131, v131
	v_rcp_f32_e32 v132, v132
	v_rcp_f32_e32 v133, v133
	s_nop 0
	v_mul_f32_e32 v118, v118, v130
	v_mul_f32_e32 v119, v119, v131
	v_mul_f32_e32 v120, v120, v132
	v_mul_f32_e32 v121, v121, v133
	v_mul_f32_e32 v134, 0x3d372713, v114
	v_mul_f32_e32 v135, 0x3d372713, v115
	v_mul_f32_e32 v136, 0x3d372713, v116
	v_mul_f32_e32 v137, 0x3d372713, v117
	v_mul_f32_e32 v134, v114, v134
	v_mul_f32_e32 v135, v115, v135
	v_mul_f32_e32 v136, v116, v136
	v_mul_f32_e32 v137, v117, v137
	v_fma_f32 v134, v114, v134, v114
	v_fma_f32 v135, v115, v135, v115
	v_fma_f32 v136, v116, v136, v116
	v_fma_f32 v137, v117, v137, v117
	v_mul_f32_e32 v134, 0x3f4c422a, v134
	v_mul_f32_e32 v135, 0x3f4c422a, v135
	v_mul_f32_e32 v136, 0x3f4c422a, v136
	v_mul_f32_e32 v137, 0x3f4c422a, v137
	v_mul_f32_e32 v134, -2.0, v134
	v_mul_f32_e32 v135, -2.0, v135
	v_mul_f32_e32 v136, -2.0, v136
	v_mul_f32_e32 v137, -2.0, v137
	v_mul_f32_e32 v134, 0x3fb8aa3b, v134
	v_mul_f32_e32 v135, 0x3fb8aa3b, v135
	v_mul_f32_e32 v136, 0x3fb8aa3b, v136
	v_mul_f32_e32 v137, 0x3fb8aa3b, v137
	v_exp_f32_e32 v134, v134
	v_exp_f32_e32 v135, v135
	v_exp_f32_e32 v136, v136
	v_exp_f32_e32 v137, v137
	v_add_f32_e32 v134, 1.0, v134
	v_add_f32_e32 v135, 1.0, v135
	v_add_f32_e32 v136, 1.0, v136
	v_add_f32_e32 v137, 1.0, v137
	v_rcp_f32_e32 v134, v134
	v_rcp_f32_e32 v135, v135
	v_rcp_f32_e32 v136, v136
	v_rcp_f32_e32 v137, v137
	s_nop 0
	v_mul_f32_e32 v114, v114, v134
	v_mul_f32_e32 v115, v115, v135
	v_mul_f32_e32 v116, v116, v136
	v_mul_f32_e32 v117, v117, v137
	v_pk_mul_f32 v[136:137], v[126:127], v[126:127]
	v_pk_mul_f32 v[138:139], v[128:129], v[128:129]
	v_add_f32_e32 v140, 0, v136
	v_add_f32_e32 v140, v137, v140
	v_add_f32_e32 v140, v138, v140
	v_add_f32_e32 v140, v139, v140
	v_pk_mul_f32 v[136:137], v[122:123], v[122:123]
	v_pk_mul_f32 v[138:139], v[124:125], v[124:125]
	v_add_f32_e32 v140, v136, v140
	v_add_f32_e32 v140, v137, v140
	v_add_f32_e32 v140, v138, v140
	v_add_f32_e32 v140, v139, v140
	v_pk_mul_f32 v[136:137], v[118:119], v[118:119]
	v_pk_mul_f32 v[138:139], v[120:121], v[120:121]
	v_add_f32_e32 v140, v136, v140
	v_add_f32_e32 v140, v137, v140
	v_add_f32_e32 v140, v138, v140
	v_add_f32_e32 v140, v139, v140
	v_pk_mul_f32 v[136:137], v[114:115], v[114:115]
	v_pk_mul_f32 v[138:139], v[116:117], v[116:117]
	v_add_f32_e32 v140, v136, v140
	v_add_f32_e32 v140, v137, v140
	v_add_f32_e32 v140, v138, v140
	v_add_f32_e32 v140, v139, v140
	ds_bpermute_b32 v141, v186, v140
	s_waitcnt lgkmcnt(0)
	v_add_f32_e32 v140, v140, v141
	ds_bpermute_b32 v141, v185, v140
	s_waitcnt lgkmcnt(0)
	v_add_f32_e32 v140, v140, v141
	v_mov_b32_e32 v141, 0x358637bd
	v_fmamk_f32 v140, v140, 0x3c800000, v141
	v_mul_f32_e32 v141, 0x4b800000, v140
	v_cmp_gt_f32_e32 vcc, 0x800000, v140
	s_nop 1
	v_cndmask_b32_e32 v140, v140, v141, vcc
	v_rsq_f32_e32 v140, v140
	s_nop 0
	v_mul_f32_e32 v141, 0x45800000, v140
	v_cndmask_b32_e32 v144, v140, v141, vcc
	v_mul_f32_e32 v130, 0x3d372713, v110
	v_mul_f32_e32 v131, 0x3d372713, v111
	v_mul_f32_e32 v132, 0x3d372713, v112
	v_mul_f32_e32 v133, 0x3d372713, v113
	v_mul_f32_e32 v130, v110, v130
	v_mul_f32_e32 v131, v111, v131
	v_mul_f32_e32 v132, v112, v132
	v_mul_f32_e32 v133, v113, v133
	v_fma_f32 v130, v110, v130, v110
	v_fma_f32 v131, v111, v131, v111
	v_fma_f32 v132, v112, v132, v112
	v_fma_f32 v133, v113, v133, v113
	v_mul_f32_e32 v130, 0x3f4c422a, v130
	v_mul_f32_e32 v131, 0x3f4c422a, v131
	v_mul_f32_e32 v132, 0x3f4c422a, v132
	v_mul_f32_e32 v133, 0x3f4c422a, v133
	v_mul_f32_e32 v130, -2.0, v130
	v_mul_f32_e32 v131, -2.0, v131
	v_mul_f32_e32 v132, -2.0, v132
	v_mul_f32_e32 v133, -2.0, v133
	v_mul_f32_e32 v130, 0x3fb8aa3b, v130
	v_mul_f32_e32 v131, 0x3fb8aa3b, v131
	v_mul_f32_e32 v132, 0x3fb8aa3b, v132
	v_mul_f32_e32 v133, 0x3fb8aa3b, v133
	v_exp_f32_e32 v130, v130
	v_exp_f32_e32 v131, v131
	v_exp_f32_e32 v132, v132
	v_exp_f32_e32 v133, v133
	v_add_f32_e32 v130, 1.0, v130
	v_add_f32_e32 v131, 1.0, v131
	v_add_f32_e32 v132, 1.0, v132
	v_add_f32_e32 v133, 1.0, v133
	v_rcp_f32_e32 v130, v130
	v_rcp_f32_e32 v131, v131
	v_rcp_f32_e32 v132, v132
	v_rcp_f32_e32 v133, v133
	s_nop 0
	v_mul_f32_e32 v110, v110, v130
	v_mul_f32_e32 v111, v111, v131
	v_mul_f32_e32 v112, v112, v132
	v_mul_f32_e32 v113, v113, v133
	v_mul_f32_e32 v134, 0x3d372713, v106
	v_mul_f32_e32 v135, 0x3d372713, v107
	v_mul_f32_e32 v136, 0x3d372713, v108
	v_mul_f32_e32 v137, 0x3d372713, v109
	v_mul_f32_e32 v134, v106, v134
	v_mul_f32_e32 v135, v107, v135
	v_mul_f32_e32 v136, v108, v136
	v_mul_f32_e32 v137, v109, v137
	v_fma_f32 v134, v106, v134, v106
	v_fma_f32 v135, v107, v135, v107
	v_fma_f32 v136, v108, v136, v108
	v_fma_f32 v137, v109, v137, v109
	v_mul_f32_e32 v134, 0x3f4c422a, v134
	v_mul_f32_e32 v135, 0x3f4c422a, v135
	v_mul_f32_e32 v136, 0x3f4c422a, v136
	v_mul_f32_e32 v137, 0x3f4c422a, v137
	v_mul_f32_e32 v134, -2.0, v134
	v_mul_f32_e32 v135, -2.0, v135
	v_mul_f32_e32 v136, -2.0, v136
	v_mul_f32_e32 v137, -2.0, v137
	v_mul_f32_e32 v134, 0x3fb8aa3b, v134
	v_mul_f32_e32 v135, 0x3fb8aa3b, v135
	v_mul_f32_e32 v136, 0x3fb8aa3b, v136
	v_mul_f32_e32 v137, 0x3fb8aa3b, v137
	v_exp_f32_e32 v134, v134
	v_exp_f32_e32 v135, v135
	v_exp_f32_e32 v136, v136
	v_exp_f32_e32 v137, v137
	v_add_f32_e32 v134, 1.0, v134
	v_add_f32_e32 v135, 1.0, v135
	v_add_f32_e32 v136, 1.0, v136
	v_add_f32_e32 v137, 1.0, v137
	v_rcp_f32_e32 v134, v134
	v_rcp_f32_e32 v135, v135
	v_rcp_f32_e32 v136, v136
	v_rcp_f32_e32 v137, v137
	s_nop 0
	v_mul_f32_e32 v106, v106, v134
	v_mul_f32_e32 v107, v107, v135
	v_mul_f32_e32 v108, v108, v136
	v_mul_f32_e32 v109, v109, v137
	v_mul_f32_e32 v130, 0x3d372713, v102
	v_mul_f32_e32 v131, 0x3d372713, v103
	v_mul_f32_e32 v132, 0x3d372713, v104
	v_mul_f32_e32 v133, 0x3d372713, v105
	v_mul_f32_e32 v130, v102, v130
	v_mul_f32_e32 v131, v103, v131
	v_mul_f32_e32 v132, v104, v132
	v_mul_f32_e32 v133, v105, v133
	v_fma_f32 v130, v102, v130, v102
	v_fma_f32 v131, v103, v131, v103
	v_fma_f32 v132, v104, v132, v104
	v_fma_f32 v133, v105, v133, v105
	v_mul_f32_e32 v130, 0x3f4c422a, v130
	v_mul_f32_e32 v131, 0x3f4c422a, v131
	v_mul_f32_e32 v132, 0x3f4c422a, v132
	v_mul_f32_e32 v133, 0x3f4c422a, v133
	v_mul_f32_e32 v130, -2.0, v130
	v_mul_f32_e32 v131, -2.0, v131
	v_mul_f32_e32 v132, -2.0, v132
	v_mul_f32_e32 v133, -2.0, v133
	v_mul_f32_e32 v130, 0x3fb8aa3b, v130
	v_mul_f32_e32 v131, 0x3fb8aa3b, v131
	v_mul_f32_e32 v132, 0x3fb8aa3b, v132
	v_mul_f32_e32 v133, 0x3fb8aa3b, v133
	v_exp_f32_e32 v130, v130
	v_exp_f32_e32 v131, v131
	v_exp_f32_e32 v132, v132
	v_exp_f32_e32 v133, v133
	v_add_f32_e32 v130, 1.0, v130
	v_add_f32_e32 v131, 1.0, v131
	v_add_f32_e32 v132, 1.0, v132
	v_add_f32_e32 v133, 1.0, v133
	v_rcp_f32_e32 v130, v130
	v_rcp_f32_e32 v131, v131
	v_rcp_f32_e32 v132, v132
	v_rcp_f32_e32 v133, v133
	s_nop 0
	v_mul_f32_e32 v102, v102, v130
	v_mul_f32_e32 v103, v103, v131
	v_mul_f32_e32 v104, v104, v132
	v_mul_f32_e32 v105, v105, v133
	v_mul_f32_e32 v134, 0x3d372713, v98
	v_mul_f32_e32 v135, 0x3d372713, v99
	v_mul_f32_e32 v136, 0x3d372713, v100
	v_mul_f32_e32 v137, 0x3d372713, v101
	v_mul_f32_e32 v134, v98, v134
	v_mul_f32_e32 v135, v99, v135
	v_mul_f32_e32 v136, v100, v136
	v_mul_f32_e32 v137, v101, v137
	v_fma_f32 v134, v98, v134, v98
	v_fma_f32 v135, v99, v135, v99
	v_fma_f32 v136, v100, v136, v100
	v_fma_f32 v137, v101, v137, v101
	v_mul_f32_e32 v134, 0x3f4c422a, v134
	v_mul_f32_e32 v135, 0x3f4c422a, v135
	v_mul_f32_e32 v136, 0x3f4c422a, v136
	v_mul_f32_e32 v137, 0x3f4c422a, v137
	v_mul_f32_e32 v134, -2.0, v134
	v_mul_f32_e32 v135, -2.0, v135
	v_mul_f32_e32 v136, -2.0, v136
	v_mul_f32_e32 v137, -2.0, v137
	v_mul_f32_e32 v134, 0x3fb8aa3b, v134
	v_mul_f32_e32 v135, 0x3fb8aa3b, v135
	v_mul_f32_e32 v136, 0x3fb8aa3b, v136
	v_mul_f32_e32 v137, 0x3fb8aa3b, v137
	v_exp_f32_e32 v134, v134
	v_exp_f32_e32 v135, v135
	v_exp_f32_e32 v136, v136
	v_exp_f32_e32 v137, v137
	v_add_f32_e32 v134, 1.0, v134
	v_add_f32_e32 v135, 1.0, v135
	v_add_f32_e32 v136, 1.0, v136
	v_add_f32_e32 v137, 1.0, v137
	v_rcp_f32_e32 v134, v134
	v_rcp_f32_e32 v135, v135
	v_rcp_f32_e32 v136, v136
	v_rcp_f32_e32 v137, v137
	s_nop 0
	v_mul_f32_e32 v98, v98, v134
	v_mul_f32_e32 v99, v99, v135
	v_mul_f32_e32 v100, v100, v136
	v_mul_f32_e32 v101, v101, v137
	v_pk_mul_f32 v[136:137], v[110:111], v[110:111]
	v_pk_mul_f32 v[138:139], v[112:113], v[112:113]
	v_add_f32_e32 v140, 0, v136
	v_add_f32_e32 v140, v137, v140
	v_add_f32_e32 v140, v138, v140
	v_add_f32_e32 v140, v139, v140
	v_pk_mul_f32 v[136:137], v[106:107], v[106:107]
	v_pk_mul_f32 v[138:139], v[108:109], v[108:109]
	v_add_f32_e32 v140, v136, v140
	v_add_f32_e32 v140, v137, v140
	v_add_f32_e32 v140, v138, v140
	v_add_f32_e32 v140, v139, v140
	v_pk_mul_f32 v[136:137], v[102:103], v[102:103]
	v_pk_mul_f32 v[138:139], v[104:105], v[104:105]
	v_add_f32_e32 v140, v136, v140
	v_add_f32_e32 v140, v137, v140
	v_add_f32_e32 v140, v138, v140
	v_add_f32_e32 v140, v139, v140
	v_pk_mul_f32 v[136:137], v[98:99], v[98:99]
	v_pk_mul_f32 v[138:139], v[100:101], v[100:101]
	v_add_f32_e32 v140, v136, v140
	v_add_f32_e32 v140, v137, v140
	v_add_f32_e32 v140, v138, v140
	v_add_f32_e32 v140, v139, v140
	ds_bpermute_b32 v141, v186, v140
	s_waitcnt lgkmcnt(0)
	v_add_f32_e32 v140, v140, v141
	ds_bpermute_b32 v141, v185, v140
	s_waitcnt lgkmcnt(0)
	v_add_f32_e32 v140, v140, v141
	v_mov_b32_e32 v141, 0x358637bd
	v_fmamk_f32 v140, v140, 0x3c800000, v141
	v_mul_f32_e32 v141, 0x4b800000, v140
	v_cmp_gt_f32_e32 vcc, 0x800000, v140
	s_nop 1
	v_cndmask_b32_e32 v140, v140, v141, vcc
	v_rsq_f32_e32 v140, v140
	s_nop 0
	v_mul_f32_e32 v141, 0x45800000, v140
	v_cndmask_b32_e32 v145, v140, v141, vcc
	v_mul_f32_e32 v130, 0x3d372713, v94
	v_mul_f32_e32 v131, 0x3d372713, v95
	v_mul_f32_e32 v132, 0x3d372713, v96
	v_mul_f32_e32 v133, 0x3d372713, v97
	v_mul_f32_e32 v130, v94, v130
	v_mul_f32_e32 v131, v95, v131
	v_mul_f32_e32 v132, v96, v132
	v_mul_f32_e32 v133, v97, v133
	v_fma_f32 v130, v94, v130, v94
	v_fma_f32 v131, v95, v131, v95
	v_fma_f32 v132, v96, v132, v96
	v_fma_f32 v133, v97, v133, v97
	v_mul_f32_e32 v130, 0x3f4c422a, v130
	v_mul_f32_e32 v131, 0x3f4c422a, v131
	v_mul_f32_e32 v132, 0x3f4c422a, v132
	v_mul_f32_e32 v133, 0x3f4c422a, v133
	v_mul_f32_e32 v130, -2.0, v130
	v_mul_f32_e32 v131, -2.0, v131
	v_mul_f32_e32 v132, -2.0, v132
	v_mul_f32_e32 v133, -2.0, v133
	v_mul_f32_e32 v130, 0x3fb8aa3b, v130
	v_mul_f32_e32 v131, 0x3fb8aa3b, v131
	v_mul_f32_e32 v132, 0x3fb8aa3b, v132
	v_mul_f32_e32 v133, 0x3fb8aa3b, v133
	v_exp_f32_e32 v130, v130
	v_exp_f32_e32 v131, v131
	v_exp_f32_e32 v132, v132
	v_exp_f32_e32 v133, v133
	v_add_f32_e32 v130, 1.0, v130
	v_add_f32_e32 v131, 1.0, v131
	v_add_f32_e32 v132, 1.0, v132
	v_add_f32_e32 v133, 1.0, v133
	v_rcp_f32_e32 v130, v130
	v_rcp_f32_e32 v131, v131
	v_rcp_f32_e32 v132, v132
	v_rcp_f32_e32 v133, v133
	s_nop 0
	v_mul_f32_e32 v94, v94, v130
	v_mul_f32_e32 v95, v95, v131
	v_mul_f32_e32 v96, v96, v132
	v_mul_f32_e32 v97, v97, v133
	v_mul_f32_e32 v134, 0x3d372713, v90
	v_mul_f32_e32 v135, 0x3d372713, v91
	v_mul_f32_e32 v136, 0x3d372713, v92
	v_mul_f32_e32 v137, 0x3d372713, v93
	v_mul_f32_e32 v134, v90, v134
	v_mul_f32_e32 v135, v91, v135
	v_mul_f32_e32 v136, v92, v136
	v_mul_f32_e32 v137, v93, v137
	v_fma_f32 v134, v90, v134, v90
	v_fma_f32 v135, v91, v135, v91
	v_fma_f32 v136, v92, v136, v92
	v_fma_f32 v137, v93, v137, v93
	v_mul_f32_e32 v134, 0x3f4c422a, v134
	v_mul_f32_e32 v135, 0x3f4c422a, v135
	v_mul_f32_e32 v136, 0x3f4c422a, v136
	v_mul_f32_e32 v137, 0x3f4c422a, v137
	v_mul_f32_e32 v134, -2.0, v134
	v_mul_f32_e32 v135, -2.0, v135
	v_mul_f32_e32 v136, -2.0, v136
	v_mul_f32_e32 v137, -2.0, v137
	v_mul_f32_e32 v134, 0x3fb8aa3b, v134
	v_mul_f32_e32 v135, 0x3fb8aa3b, v135
	v_mul_f32_e32 v136, 0x3fb8aa3b, v136
	v_mul_f32_e32 v137, 0x3fb8aa3b, v137
	v_exp_f32_e32 v134, v134
	v_exp_f32_e32 v135, v135
	v_exp_f32_e32 v136, v136
	v_exp_f32_e32 v137, v137
	v_add_f32_e32 v134, 1.0, v134
	v_add_f32_e32 v135, 1.0, v135
	v_add_f32_e32 v136, 1.0, v136
	v_add_f32_e32 v137, 1.0, v137
	v_rcp_f32_e32 v134, v134
	v_rcp_f32_e32 v135, v135
	v_rcp_f32_e32 v136, v136
	v_rcp_f32_e32 v137, v137
	s_nop 0
	v_mul_f32_e32 v90, v90, v134
	v_mul_f32_e32 v91, v91, v135
	v_mul_f32_e32 v92, v92, v136
	v_mul_f32_e32 v93, v93, v137
	v_mul_f32_e32 v130, 0x3d372713, v86
	v_mul_f32_e32 v131, 0x3d372713, v87
	v_mul_f32_e32 v132, 0x3d372713, v88
	v_mul_f32_e32 v133, 0x3d372713, v89
	v_mul_f32_e32 v130, v86, v130
	v_mul_f32_e32 v131, v87, v131
	v_mul_f32_e32 v132, v88, v132
	v_mul_f32_e32 v133, v89, v133
	v_fma_f32 v130, v86, v130, v86
	v_fma_f32 v131, v87, v131, v87
	v_fma_f32 v132, v88, v132, v88
	v_fma_f32 v133, v89, v133, v89
	v_mul_f32_e32 v130, 0x3f4c422a, v130
	v_mul_f32_e32 v131, 0x3f4c422a, v131
	v_mul_f32_e32 v132, 0x3f4c422a, v132
	v_mul_f32_e32 v133, 0x3f4c422a, v133
	v_mul_f32_e32 v130, -2.0, v130
	v_mul_f32_e32 v131, -2.0, v131
	v_mul_f32_e32 v132, -2.0, v132
	v_mul_f32_e32 v133, -2.0, v133
	v_mul_f32_e32 v130, 0x3fb8aa3b, v130
	v_mul_f32_e32 v131, 0x3fb8aa3b, v131
	v_mul_f32_e32 v132, 0x3fb8aa3b, v132
	v_mul_f32_e32 v133, 0x3fb8aa3b, v133
	v_exp_f32_e32 v130, v130
	v_exp_f32_e32 v131, v131
	v_exp_f32_e32 v132, v132
	v_exp_f32_e32 v133, v133
	v_add_f32_e32 v130, 1.0, v130
	v_add_f32_e32 v131, 1.0, v131
	v_add_f32_e32 v132, 1.0, v132
	v_add_f32_e32 v133, 1.0, v133
	v_rcp_f32_e32 v130, v130
	v_rcp_f32_e32 v131, v131
	v_rcp_f32_e32 v132, v132
	v_rcp_f32_e32 v133, v133
	s_nop 0
	v_mul_f32_e32 v86, v86, v130
	v_mul_f32_e32 v87, v87, v131
	v_mul_f32_e32 v88, v88, v132
	v_mul_f32_e32 v89, v89, v133
	v_mul_f32_e32 v134, 0x3d372713, v82
	v_mul_f32_e32 v135, 0x3d372713, v83
	v_mul_f32_e32 v136, 0x3d372713, v84
	v_mul_f32_e32 v137, 0x3d372713, v85
	v_mul_f32_e32 v134, v82, v134
	v_mul_f32_e32 v135, v83, v135
	v_mul_f32_e32 v136, v84, v136
	v_mul_f32_e32 v137, v85, v137
	v_fma_f32 v134, v82, v134, v82
	v_fma_f32 v135, v83, v135, v83
	v_fma_f32 v136, v84, v136, v84
	v_fma_f32 v137, v85, v137, v85
	v_mul_f32_e32 v134, 0x3f4c422a, v134
	v_mul_f32_e32 v135, 0x3f4c422a, v135
	v_mul_f32_e32 v136, 0x3f4c422a, v136
	v_mul_f32_e32 v137, 0x3f4c422a, v137
	v_mul_f32_e32 v134, -2.0, v134
	v_mul_f32_e32 v135, -2.0, v135
	v_mul_f32_e32 v136, -2.0, v136
	v_mul_f32_e32 v137, -2.0, v137
	v_mul_f32_e32 v134, 0x3fb8aa3b, v134
	v_mul_f32_e32 v135, 0x3fb8aa3b, v135
	v_mul_f32_e32 v136, 0x3fb8aa3b, v136
	v_mul_f32_e32 v137, 0x3fb8aa3b, v137
	v_exp_f32_e32 v134, v134
	v_exp_f32_e32 v135, v135
	v_exp_f32_e32 v136, v136
	v_exp_f32_e32 v137, v137
	v_add_f32_e32 v134, 1.0, v134
	v_add_f32_e32 v135, 1.0, v135
	v_add_f32_e32 v136, 1.0, v136
	v_add_f32_e32 v137, 1.0, v137
	v_rcp_f32_e32 v134, v134
	v_rcp_f32_e32 v135, v135
	v_rcp_f32_e32 v136, v136
	v_rcp_f32_e32 v137, v137
	s_nop 0
	v_mul_f32_e32 v82, v82, v134
	v_mul_f32_e32 v83, v83, v135
	v_mul_f32_e32 v84, v84, v136
	v_mul_f32_e32 v85, v85, v137
	v_pk_mul_f32 v[136:137], v[94:95], v[94:95]
	v_pk_mul_f32 v[138:139], v[96:97], v[96:97]
	v_add_f32_e32 v140, 0, v136
	v_add_f32_e32 v140, v137, v140
	v_add_f32_e32 v140, v138, v140
	v_add_f32_e32 v140, v139, v140
	v_pk_mul_f32 v[136:137], v[90:91], v[90:91]
	v_pk_mul_f32 v[138:139], v[92:93], v[92:93]
	v_add_f32_e32 v140, v136, v140
	v_add_f32_e32 v140, v137, v140
	v_add_f32_e32 v140, v138, v140
	v_add_f32_e32 v140, v139, v140
	v_pk_mul_f32 v[136:137], v[86:87], v[86:87]
	v_pk_mul_f32 v[138:139], v[88:89], v[88:89]
	v_add_f32_e32 v140, v136, v140
	v_add_f32_e32 v140, v137, v140
	v_add_f32_e32 v140, v138, v140
	v_add_f32_e32 v140, v139, v140
	v_pk_mul_f32 v[136:137], v[82:83], v[82:83]
	v_pk_mul_f32 v[138:139], v[84:85], v[84:85]
	v_add_f32_e32 v140, v136, v140
	v_add_f32_e32 v140, v137, v140
	v_add_f32_e32 v140, v138, v140
	v_add_f32_e32 v140, v139, v140
	ds_bpermute_b32 v141, v186, v140
	s_waitcnt lgkmcnt(0)
	v_add_f32_e32 v140, v140, v141
	ds_bpermute_b32 v141, v185, v140
	s_waitcnt lgkmcnt(0)
	v_add_f32_e32 v140, v140, v141
	v_mov_b32_e32 v141, 0x358637bd
	v_fmamk_f32 v140, v140, 0x3c800000, v141
	v_mul_f32_e32 v141, 0x4b800000, v140
	v_cmp_gt_f32_e32 vcc, 0x800000, v140
	s_nop 1
	v_cndmask_b32_e32 v140, v140, v141, vcc
	v_rsq_f32_e32 v140, v140
	s_nop 0
	v_mul_f32_e32 v141, 0x45800000, v140
	v_cndmask_b32_e32 v146, v140, v141, vcc
	v_mul_f32_e32 v130, 0x3d372713, v78
	v_mul_f32_e32 v131, 0x3d372713, v79
	v_mul_f32_e32 v132, 0x3d372713, v80
	v_mul_f32_e32 v133, 0x3d372713, v81
	v_mul_f32_e32 v130, v78, v130
	v_mul_f32_e32 v131, v79, v131
	v_mul_f32_e32 v132, v80, v132
	v_mul_f32_e32 v133, v81, v133
	v_fma_f32 v130, v78, v130, v78
	v_fma_f32 v131, v79, v131, v79
	v_fma_f32 v132, v80, v132, v80
	v_fma_f32 v133, v81, v133, v81
	v_mul_f32_e32 v130, 0x3f4c422a, v130
	v_mul_f32_e32 v131, 0x3f4c422a, v131
	v_mul_f32_e32 v132, 0x3f4c422a, v132
	v_mul_f32_e32 v133, 0x3f4c422a, v133
	v_mul_f32_e32 v130, -2.0, v130
	v_mul_f32_e32 v131, -2.0, v131
	v_mul_f32_e32 v132, -2.0, v132
	v_mul_f32_e32 v133, -2.0, v133
	v_mul_f32_e32 v130, 0x3fb8aa3b, v130
	v_mul_f32_e32 v131, 0x3fb8aa3b, v131
	v_mul_f32_e32 v132, 0x3fb8aa3b, v132
	v_mul_f32_e32 v133, 0x3fb8aa3b, v133
	v_exp_f32_e32 v130, v130
	v_exp_f32_e32 v131, v131
	v_exp_f32_e32 v132, v132
	v_exp_f32_e32 v133, v133
	v_add_f32_e32 v130, 1.0, v130
	v_add_f32_e32 v131, 1.0, v131
	v_add_f32_e32 v132, 1.0, v132
	v_add_f32_e32 v133, 1.0, v133
	v_rcp_f32_e32 v130, v130
	v_rcp_f32_e32 v131, v131
	v_rcp_f32_e32 v132, v132
	v_rcp_f32_e32 v133, v133
	s_nop 0
	v_mul_f32_e32 v78, v78, v130
	v_mul_f32_e32 v79, v79, v131
	v_mul_f32_e32 v80, v80, v132
	v_mul_f32_e32 v81, v81, v133
	v_mul_f32_e32 v134, 0x3d372713, v74
	v_mul_f32_e32 v135, 0x3d372713, v75
	v_mul_f32_e32 v136, 0x3d372713, v76
	v_mul_f32_e32 v137, 0x3d372713, v77
	v_mul_f32_e32 v134, v74, v134
	v_mul_f32_e32 v135, v75, v135
	v_mul_f32_e32 v136, v76, v136
	v_mul_f32_e32 v137, v77, v137
	v_fma_f32 v134, v74, v134, v74
	v_fma_f32 v135, v75, v135, v75
	v_fma_f32 v136, v76, v136, v76
	v_fma_f32 v137, v77, v137, v77
	v_mul_f32_e32 v134, 0x3f4c422a, v134
	v_mul_f32_e32 v135, 0x3f4c422a, v135
	v_mul_f32_e32 v136, 0x3f4c422a, v136
	v_mul_f32_e32 v137, 0x3f4c422a, v137
	v_mul_f32_e32 v134, -2.0, v134
	v_mul_f32_e32 v135, -2.0, v135
	v_mul_f32_e32 v136, -2.0, v136
	v_mul_f32_e32 v137, -2.0, v137
	v_mul_f32_e32 v134, 0x3fb8aa3b, v134
	v_mul_f32_e32 v135, 0x3fb8aa3b, v135
	v_mul_f32_e32 v136, 0x3fb8aa3b, v136
	v_mul_f32_e32 v137, 0x3fb8aa3b, v137
	v_exp_f32_e32 v134, v134
	v_exp_f32_e32 v135, v135
	v_exp_f32_e32 v136, v136
	v_exp_f32_e32 v137, v137
	v_add_f32_e32 v134, 1.0, v134
	v_add_f32_e32 v135, 1.0, v135
	v_add_f32_e32 v136, 1.0, v136
	v_add_f32_e32 v137, 1.0, v137
	v_rcp_f32_e32 v134, v134
	v_rcp_f32_e32 v135, v135
	v_rcp_f32_e32 v136, v136
	v_rcp_f32_e32 v137, v137
	s_nop 0
	v_mul_f32_e32 v74, v74, v134
	v_mul_f32_e32 v75, v75, v135
	v_mul_f32_e32 v76, v76, v136
	v_mul_f32_e32 v77, v77, v137
	v_mul_f32_e32 v130, 0x3d372713, v70
	v_mul_f32_e32 v131, 0x3d372713, v71
	v_mul_f32_e32 v132, 0x3d372713, v72
	v_mul_f32_e32 v133, 0x3d372713, v73
	v_mul_f32_e32 v130, v70, v130
	v_mul_f32_e32 v131, v71, v131
	v_mul_f32_e32 v132, v72, v132
	v_mul_f32_e32 v133, v73, v133
	v_fma_f32 v130, v70, v130, v70
	v_fma_f32 v131, v71, v131, v71
	v_fma_f32 v132, v72, v132, v72
	v_fma_f32 v133, v73, v133, v73
	v_mul_f32_e32 v130, 0x3f4c422a, v130
	v_mul_f32_e32 v131, 0x3f4c422a, v131
	v_mul_f32_e32 v132, 0x3f4c422a, v132
	v_mul_f32_e32 v133, 0x3f4c422a, v133
	v_mul_f32_e32 v130, -2.0, v130
	v_mul_f32_e32 v131, -2.0, v131
	v_mul_f32_e32 v132, -2.0, v132
	v_mul_f32_e32 v133, -2.0, v133
	v_mul_f32_e32 v130, 0x3fb8aa3b, v130
	v_mul_f32_e32 v131, 0x3fb8aa3b, v131
	v_mul_f32_e32 v132, 0x3fb8aa3b, v132
	v_mul_f32_e32 v133, 0x3fb8aa3b, v133
	v_exp_f32_e32 v130, v130
	v_exp_f32_e32 v131, v131
	v_exp_f32_e32 v132, v132
	v_exp_f32_e32 v133, v133
	v_add_f32_e32 v130, 1.0, v130
	v_add_f32_e32 v131, 1.0, v131
	v_add_f32_e32 v132, 1.0, v132
	v_add_f32_e32 v133, 1.0, v133
	v_rcp_f32_e32 v130, v130
	v_rcp_f32_e32 v131, v131
	v_rcp_f32_e32 v132, v132
	v_rcp_f32_e32 v133, v133
	s_nop 0
	v_mul_f32_e32 v70, v70, v130
	v_mul_f32_e32 v71, v71, v131
	v_mul_f32_e32 v72, v72, v132
	v_mul_f32_e32 v73, v73, v133
	v_mul_f32_e32 v134, 0x3d372713, v66
	v_mul_f32_e32 v135, 0x3d372713, v67
	v_mul_f32_e32 v136, 0x3d372713, v68
	v_mul_f32_e32 v137, 0x3d372713, v69
	v_mul_f32_e32 v134, v66, v134
	v_mul_f32_e32 v135, v67, v135
	v_mul_f32_e32 v136, v68, v136
	v_mul_f32_e32 v137, v69, v137
	v_fma_f32 v134, v66, v134, v66
	v_fma_f32 v135, v67, v135, v67
	v_fma_f32 v136, v68, v136, v68
	v_fma_f32 v137, v69, v137, v69
	v_mul_f32_e32 v134, 0x3f4c422a, v134
	v_mul_f32_e32 v135, 0x3f4c422a, v135
	v_mul_f32_e32 v136, 0x3f4c422a, v136
	v_mul_f32_e32 v137, 0x3f4c422a, v137
	v_mul_f32_e32 v134, -2.0, v134
	v_mul_f32_e32 v135, -2.0, v135
	v_mul_f32_e32 v136, -2.0, v136
	v_mul_f32_e32 v137, -2.0, v137
	v_mul_f32_e32 v134, 0x3fb8aa3b, v134
	v_mul_f32_e32 v135, 0x3fb8aa3b, v135
	v_mul_f32_e32 v136, 0x3fb8aa3b, v136
	v_mul_f32_e32 v137, 0x3fb8aa3b, v137
	v_exp_f32_e32 v134, v134
	v_exp_f32_e32 v135, v135
	v_exp_f32_e32 v136, v136
	v_exp_f32_e32 v137, v137
	v_add_f32_e32 v134, 1.0, v134
	v_add_f32_e32 v135, 1.0, v135
	v_add_f32_e32 v136, 1.0, v136
	v_add_f32_e32 v137, 1.0, v137
	v_rcp_f32_e32 v134, v134
	v_rcp_f32_e32 v135, v135
	v_rcp_f32_e32 v136, v136
	v_rcp_f32_e32 v137, v137
	s_nop 0
	v_mul_f32_e32 v66, v66, v134
	v_mul_f32_e32 v67, v67, v135
	v_mul_f32_e32 v68, v68, v136
	v_mul_f32_e32 v69, v69, v137
	v_pk_mul_f32 v[136:137], v[78:79], v[78:79]
	v_pk_mul_f32 v[138:139], v[80:81], v[80:81]
	v_add_f32_e32 v140, 0, v136
	v_add_f32_e32 v140, v137, v140
	v_add_f32_e32 v140, v138, v140
	v_add_f32_e32 v140, v139, v140
	v_pk_mul_f32 v[136:137], v[74:75], v[74:75]
	v_pk_mul_f32 v[138:139], v[76:77], v[76:77]
	v_add_f32_e32 v140, v136, v140
	v_add_f32_e32 v140, v137, v140
	v_add_f32_e32 v140, v138, v140
	v_add_f32_e32 v140, v139, v140
	v_pk_mul_f32 v[136:137], v[70:71], v[70:71]
	v_pk_mul_f32 v[138:139], v[72:73], v[72:73]
	v_add_f32_e32 v140, v136, v140
	v_add_f32_e32 v140, v137, v140
	v_add_f32_e32 v140, v138, v140
	v_add_f32_e32 v140, v139, v140
	v_pk_mul_f32 v[136:137], v[66:67], v[66:67]
	v_pk_mul_f32 v[138:139], v[68:69], v[68:69]
	v_add_f32_e32 v140, v136, v140
	v_add_f32_e32 v140, v137, v140
	v_add_f32_e32 v140, v138, v140
	v_add_f32_e32 v140, v139, v140
	ds_bpermute_b32 v141, v186, v140
	s_waitcnt lgkmcnt(0)
	v_add_f32_e32 v140, v140, v141
	ds_bpermute_b32 v141, v185, v140
	s_waitcnt lgkmcnt(0)
	v_add_f32_e32 v140, v140, v141
	v_mov_b32_e32 v141, 0x358637bd
	v_fmamk_f32 v140, v140, 0x3c800000, v141
	v_mul_f32_e32 v141, 0x4b800000, v140
	v_cmp_gt_f32_e32 vcc, 0x800000, v140
	s_nop 1
	v_cndmask_b32_e32 v140, v140, v141, vcc
	v_rsq_f32_e32 v140, v140
	s_nop 0
	v_mul_f32_e32 v141, 0x45800000, v140
	v_cndmask_b32_e32 v147, v140, v141, vcc
	v_mul_f32_e32 v130, 0x3d372713, v62
	v_mul_f32_e32 v131, 0x3d372713, v63
	v_mul_f32_e32 v132, 0x3d372713, v64
	v_mul_f32_e32 v133, 0x3d372713, v65
	v_mul_f32_e32 v130, v62, v130
	v_mul_f32_e32 v131, v63, v131
	v_mul_f32_e32 v132, v64, v132
	v_mul_f32_e32 v133, v65, v133
	v_fma_f32 v130, v62, v130, v62
	v_fma_f32 v131, v63, v131, v63
	v_fma_f32 v132, v64, v132, v64
	v_fma_f32 v133, v65, v133, v65
	v_mul_f32_e32 v130, 0x3f4c422a, v130
	v_mul_f32_e32 v131, 0x3f4c422a, v131
	v_mul_f32_e32 v132, 0x3f4c422a, v132
	v_mul_f32_e32 v133, 0x3f4c422a, v133
	v_mul_f32_e32 v130, -2.0, v130
	v_mul_f32_e32 v131, -2.0, v131
	v_mul_f32_e32 v132, -2.0, v132
	v_mul_f32_e32 v133, -2.0, v133
	v_mul_f32_e32 v130, 0x3fb8aa3b, v130
	v_mul_f32_e32 v131, 0x3fb8aa3b, v131
	v_mul_f32_e32 v132, 0x3fb8aa3b, v132
	v_mul_f32_e32 v133, 0x3fb8aa3b, v133
	v_exp_f32_e32 v130, v130
	v_exp_f32_e32 v131, v131
	v_exp_f32_e32 v132, v132
	v_exp_f32_e32 v133, v133
	v_add_f32_e32 v130, 1.0, v130
	v_add_f32_e32 v131, 1.0, v131
	v_add_f32_e32 v132, 1.0, v132
	v_add_f32_e32 v133, 1.0, v133
	v_rcp_f32_e32 v130, v130
	v_rcp_f32_e32 v131, v131
	v_rcp_f32_e32 v132, v132
	v_rcp_f32_e32 v133, v133
	s_nop 0
	v_mul_f32_e32 v62, v62, v130
	v_mul_f32_e32 v63, v63, v131
	v_mul_f32_e32 v64, v64, v132
	v_mul_f32_e32 v65, v65, v133
	v_mul_f32_e32 v134, 0x3d372713, v58
	v_mul_f32_e32 v135, 0x3d372713, v59
	v_mul_f32_e32 v136, 0x3d372713, v60
	v_mul_f32_e32 v137, 0x3d372713, v61
	v_mul_f32_e32 v134, v58, v134
	v_mul_f32_e32 v135, v59, v135
	v_mul_f32_e32 v136, v60, v136
	v_mul_f32_e32 v137, v61, v137
	v_fma_f32 v134, v58, v134, v58
	v_fma_f32 v135, v59, v135, v59
	v_fma_f32 v136, v60, v136, v60
	v_fma_f32 v137, v61, v137, v61
	v_mul_f32_e32 v134, 0x3f4c422a, v134
	v_mul_f32_e32 v135, 0x3f4c422a, v135
	v_mul_f32_e32 v136, 0x3f4c422a, v136
	v_mul_f32_e32 v137, 0x3f4c422a, v137
	v_mul_f32_e32 v134, -2.0, v134
	v_mul_f32_e32 v135, -2.0, v135
	v_mul_f32_e32 v136, -2.0, v136
	v_mul_f32_e32 v137, -2.0, v137
	v_mul_f32_e32 v134, 0x3fb8aa3b, v134
	v_mul_f32_e32 v135, 0x3fb8aa3b, v135
	v_mul_f32_e32 v136, 0x3fb8aa3b, v136
	v_mul_f32_e32 v137, 0x3fb8aa3b, v137
	v_exp_f32_e32 v134, v134
	v_exp_f32_e32 v135, v135
	v_exp_f32_e32 v136, v136
	v_exp_f32_e32 v137, v137
	v_add_f32_e32 v134, 1.0, v134
	v_add_f32_e32 v135, 1.0, v135
	v_add_f32_e32 v136, 1.0, v136
	v_add_f32_e32 v137, 1.0, v137
	v_rcp_f32_e32 v134, v134
	v_rcp_f32_e32 v135, v135
	v_rcp_f32_e32 v136, v136
	v_rcp_f32_e32 v137, v137
	s_nop 0
	v_mul_f32_e32 v58, v58, v134
	v_mul_f32_e32 v59, v59, v135
	v_mul_f32_e32 v60, v60, v136
	v_mul_f32_e32 v61, v61, v137
	v_mul_f32_e32 v130, 0x3d372713, v54
	v_mul_f32_e32 v131, 0x3d372713, v55
	v_mul_f32_e32 v132, 0x3d372713, v56
	v_mul_f32_e32 v133, 0x3d372713, v57
	v_mul_f32_e32 v130, v54, v130
	v_mul_f32_e32 v131, v55, v131
	v_mul_f32_e32 v132, v56, v132
	v_mul_f32_e32 v133, v57, v133
	v_fma_f32 v130, v54, v130, v54
	v_fma_f32 v131, v55, v131, v55
	v_fma_f32 v132, v56, v132, v56
	v_fma_f32 v133, v57, v133, v57
	v_mul_f32_e32 v130, 0x3f4c422a, v130
	v_mul_f32_e32 v131, 0x3f4c422a, v131
	v_mul_f32_e32 v132, 0x3f4c422a, v132
	v_mul_f32_e32 v133, 0x3f4c422a, v133
	v_mul_f32_e32 v130, -2.0, v130
	v_mul_f32_e32 v131, -2.0, v131
	v_mul_f32_e32 v132, -2.0, v132
	v_mul_f32_e32 v133, -2.0, v133
	v_mul_f32_e32 v130, 0x3fb8aa3b, v130
	v_mul_f32_e32 v131, 0x3fb8aa3b, v131
	v_mul_f32_e32 v132, 0x3fb8aa3b, v132
	v_mul_f32_e32 v133, 0x3fb8aa3b, v133
	v_exp_f32_e32 v130, v130
	v_exp_f32_e32 v131, v131
	v_exp_f32_e32 v132, v132
	v_exp_f32_e32 v133, v133
	v_add_f32_e32 v130, 1.0, v130
	v_add_f32_e32 v131, 1.0, v131
	v_add_f32_e32 v132, 1.0, v132
	v_add_f32_e32 v133, 1.0, v133
	v_rcp_f32_e32 v130, v130
	v_rcp_f32_e32 v131, v131
	v_rcp_f32_e32 v132, v132
	v_rcp_f32_e32 v133, v133
	s_nop 0
	v_mul_f32_e32 v54, v54, v130
	v_mul_f32_e32 v55, v55, v131
	v_mul_f32_e32 v56, v56, v132
	v_mul_f32_e32 v57, v57, v133
	v_mul_f32_e32 v134, 0x3d372713, v50
	v_mul_f32_e32 v135, 0x3d372713, v51
	v_mul_f32_e32 v136, 0x3d372713, v52
	v_mul_f32_e32 v137, 0x3d372713, v53
	v_mul_f32_e32 v134, v50, v134
	v_mul_f32_e32 v135, v51, v135
	v_mul_f32_e32 v136, v52, v136
	v_mul_f32_e32 v137, v53, v137
	v_fma_f32 v134, v50, v134, v50
	v_fma_f32 v135, v51, v135, v51
	v_fma_f32 v136, v52, v136, v52
	v_fma_f32 v137, v53, v137, v53
	v_mul_f32_e32 v134, 0x3f4c422a, v134
	v_mul_f32_e32 v135, 0x3f4c422a, v135
	v_mul_f32_e32 v136, 0x3f4c422a, v136
	v_mul_f32_e32 v137, 0x3f4c422a, v137
	v_mul_f32_e32 v134, -2.0, v134
	v_mul_f32_e32 v135, -2.0, v135
	v_mul_f32_e32 v136, -2.0, v136
	v_mul_f32_e32 v137, -2.0, v137
	v_mul_f32_e32 v134, 0x3fb8aa3b, v134
	v_mul_f32_e32 v135, 0x3fb8aa3b, v135
	v_mul_f32_e32 v136, 0x3fb8aa3b, v136
	v_mul_f32_e32 v137, 0x3fb8aa3b, v137
	v_exp_f32_e32 v134, v134
	v_exp_f32_e32 v135, v135
	v_exp_f32_e32 v136, v136
	v_exp_f32_e32 v137, v137
	v_add_f32_e32 v134, 1.0, v134
	v_add_f32_e32 v135, 1.0, v135
	v_add_f32_e32 v136, 1.0, v136
	v_add_f32_e32 v137, 1.0, v137
	v_rcp_f32_e32 v134, v134
	v_rcp_f32_e32 v135, v135
	v_rcp_f32_e32 v136, v136
	v_rcp_f32_e32 v137, v137
	s_nop 0
	v_mul_f32_e32 v50, v50, v134
	v_mul_f32_e32 v51, v51, v135
	v_mul_f32_e32 v52, v52, v136
	v_mul_f32_e32 v53, v53, v137
	v_pk_mul_f32 v[136:137], v[62:63], v[62:63]
	v_pk_mul_f32 v[138:139], v[64:65], v[64:65]
	v_add_f32_e32 v140, 0, v136
	v_add_f32_e32 v140, v137, v140
	v_add_f32_e32 v140, v138, v140
	v_add_f32_e32 v140, v139, v140
	v_pk_mul_f32 v[136:137], v[58:59], v[58:59]
	v_pk_mul_f32 v[138:139], v[60:61], v[60:61]
	v_add_f32_e32 v140, v136, v140
	v_add_f32_e32 v140, v137, v140
	v_add_f32_e32 v140, v138, v140
	v_add_f32_e32 v140, v139, v140
	v_pk_mul_f32 v[136:137], v[54:55], v[54:55]
	v_pk_mul_f32 v[138:139], v[56:57], v[56:57]
	v_add_f32_e32 v140, v136, v140
	v_add_f32_e32 v140, v137, v140
	v_add_f32_e32 v140, v138, v140
	v_add_f32_e32 v140, v139, v140
	v_pk_mul_f32 v[136:137], v[50:51], v[50:51]
	v_pk_mul_f32 v[138:139], v[52:53], v[52:53]
	v_add_f32_e32 v140, v136, v140
	v_add_f32_e32 v140, v137, v140
	v_add_f32_e32 v140, v138, v140
	v_add_f32_e32 v140, v139, v140
	ds_bpermute_b32 v141, v186, v140
	s_waitcnt lgkmcnt(0)
	v_add_f32_e32 v140, v140, v141
	ds_bpermute_b32 v141, v185, v140
	s_waitcnt lgkmcnt(0)
	v_add_f32_e32 v140, v140, v141
	v_mov_b32_e32 v141, 0x358637bd
	v_fmamk_f32 v140, v140, 0x3c800000, v141
	v_mul_f32_e32 v141, 0x4b800000, v140
	v_cmp_gt_f32_e32 vcc, 0x800000, v140
	s_nop 1
	v_cndmask_b32_e32 v140, v140, v141, vcc
	v_rsq_f32_e32 v140, v140
	s_nop 0
	v_mul_f32_e32 v141, 0x45800000, v140
	v_cndmask_b32_e32 v148, v140, v141, vcc
	v_mul_f32_e32 v130, 0x3d372713, v46
	v_mul_f32_e32 v131, 0x3d372713, v47
	v_mul_f32_e32 v132, 0x3d372713, v48
	v_mul_f32_e32 v133, 0x3d372713, v49
	v_mul_f32_e32 v130, v46, v130
	v_mul_f32_e32 v131, v47, v131
	v_mul_f32_e32 v132, v48, v132
	v_mul_f32_e32 v133, v49, v133
	v_fma_f32 v130, v46, v130, v46
	v_fma_f32 v131, v47, v131, v47
	v_fma_f32 v132, v48, v132, v48
	v_fma_f32 v133, v49, v133, v49
	v_mul_f32_e32 v130, 0x3f4c422a, v130
	v_mul_f32_e32 v131, 0x3f4c422a, v131
	v_mul_f32_e32 v132, 0x3f4c422a, v132
	v_mul_f32_e32 v133, 0x3f4c422a, v133
	v_mul_f32_e32 v130, -2.0, v130
	v_mul_f32_e32 v131, -2.0, v131
	v_mul_f32_e32 v132, -2.0, v132
	v_mul_f32_e32 v133, -2.0, v133
	v_mul_f32_e32 v130, 0x3fb8aa3b, v130
	v_mul_f32_e32 v131, 0x3fb8aa3b, v131
	v_mul_f32_e32 v132, 0x3fb8aa3b, v132
	v_mul_f32_e32 v133, 0x3fb8aa3b, v133
	v_exp_f32_e32 v130, v130
	v_exp_f32_e32 v131, v131
	v_exp_f32_e32 v132, v132
	v_exp_f32_e32 v133, v133
	v_add_f32_e32 v130, 1.0, v130
	v_add_f32_e32 v131, 1.0, v131
	v_add_f32_e32 v132, 1.0, v132
	v_add_f32_e32 v133, 1.0, v133
	v_rcp_f32_e32 v130, v130
	v_rcp_f32_e32 v131, v131
	v_rcp_f32_e32 v132, v132
	v_rcp_f32_e32 v133, v133
	s_nop 0
	v_mul_f32_e32 v46, v46, v130
	v_mul_f32_e32 v47, v47, v131
	v_mul_f32_e32 v48, v48, v132
	v_mul_f32_e32 v49, v49, v133
	v_mul_f32_e32 v134, 0x3d372713, v42
	v_mul_f32_e32 v135, 0x3d372713, v43
	v_mul_f32_e32 v136, 0x3d372713, v44
	v_mul_f32_e32 v137, 0x3d372713, v45
	v_mul_f32_e32 v134, v42, v134
	v_mul_f32_e32 v135, v43, v135
	v_mul_f32_e32 v136, v44, v136
	v_mul_f32_e32 v137, v45, v137
	v_fma_f32 v134, v42, v134, v42
	v_fma_f32 v135, v43, v135, v43
	v_fma_f32 v136, v44, v136, v44
	v_fma_f32 v137, v45, v137, v45
	v_mul_f32_e32 v134, 0x3f4c422a, v134
	v_mul_f32_e32 v135, 0x3f4c422a, v135
	v_mul_f32_e32 v136, 0x3f4c422a, v136
	v_mul_f32_e32 v137, 0x3f4c422a, v137
	v_mul_f32_e32 v134, -2.0, v134
	v_mul_f32_e32 v135, -2.0, v135
	v_mul_f32_e32 v136, -2.0, v136
	v_mul_f32_e32 v137, -2.0, v137
	v_mul_f32_e32 v134, 0x3fb8aa3b, v134
	v_mul_f32_e32 v135, 0x3fb8aa3b, v135
	v_mul_f32_e32 v136, 0x3fb8aa3b, v136
	v_mul_f32_e32 v137, 0x3fb8aa3b, v137
	v_exp_f32_e32 v134, v134
	v_exp_f32_e32 v135, v135
	v_exp_f32_e32 v136, v136
	v_exp_f32_e32 v137, v137
	v_add_f32_e32 v134, 1.0, v134
	v_add_f32_e32 v135, 1.0, v135
	v_add_f32_e32 v136, 1.0, v136
	v_add_f32_e32 v137, 1.0, v137
	v_rcp_f32_e32 v134, v134
	v_rcp_f32_e32 v135, v135
	v_rcp_f32_e32 v136, v136
	v_rcp_f32_e32 v137, v137
	s_nop 0
	v_mul_f32_e32 v42, v42, v134
	v_mul_f32_e32 v43, v43, v135
	v_mul_f32_e32 v44, v44, v136
	v_mul_f32_e32 v45, v45, v137
	v_mul_f32_e32 v130, 0x3d372713, v38
	v_mul_f32_e32 v131, 0x3d372713, v39
	v_mul_f32_e32 v132, 0x3d372713, v40
	v_mul_f32_e32 v133, 0x3d372713, v41
	v_mul_f32_e32 v130, v38, v130
	v_mul_f32_e32 v131, v39, v131
	v_mul_f32_e32 v132, v40, v132
	v_mul_f32_e32 v133, v41, v133
	v_fma_f32 v130, v38, v130, v38
	v_fma_f32 v131, v39, v131, v39
	v_fma_f32 v132, v40, v132, v40
	v_fma_f32 v133, v41, v133, v41
	v_mul_f32_e32 v130, 0x3f4c422a, v130
	v_mul_f32_e32 v131, 0x3f4c422a, v131
	v_mul_f32_e32 v132, 0x3f4c422a, v132
	v_mul_f32_e32 v133, 0x3f4c422a, v133
	v_mul_f32_e32 v130, -2.0, v130
	v_mul_f32_e32 v131, -2.0, v131
	v_mul_f32_e32 v132, -2.0, v132
	v_mul_f32_e32 v133, -2.0, v133
	v_mul_f32_e32 v130, 0x3fb8aa3b, v130
	v_mul_f32_e32 v131, 0x3fb8aa3b, v131
	v_mul_f32_e32 v132, 0x3fb8aa3b, v132
	v_mul_f32_e32 v133, 0x3fb8aa3b, v133
	v_exp_f32_e32 v130, v130
	v_exp_f32_e32 v131, v131
	v_exp_f32_e32 v132, v132
	v_exp_f32_e32 v133, v133
	v_add_f32_e32 v130, 1.0, v130
	v_add_f32_e32 v131, 1.0, v131
	v_add_f32_e32 v132, 1.0, v132
	v_add_f32_e32 v133, 1.0, v133
	v_rcp_f32_e32 v130, v130
	v_rcp_f32_e32 v131, v131
	v_rcp_f32_e32 v132, v132
	v_rcp_f32_e32 v133, v133
	s_nop 0
	v_mul_f32_e32 v38, v38, v130
	v_mul_f32_e32 v39, v39, v131
	v_mul_f32_e32 v40, v40, v132
	v_mul_f32_e32 v41, v41, v133
	v_mul_f32_e32 v134, 0x3d372713, v34
	v_mul_f32_e32 v135, 0x3d372713, v35
	v_mul_f32_e32 v136, 0x3d372713, v36
	v_mul_f32_e32 v137, 0x3d372713, v37
	v_mul_f32_e32 v134, v34, v134
	v_mul_f32_e32 v135, v35, v135
	v_mul_f32_e32 v136, v36, v136
	v_mul_f32_e32 v137, v37, v137
	v_fma_f32 v134, v34, v134, v34
	v_fma_f32 v135, v35, v135, v35
	v_fma_f32 v136, v36, v136, v36
	v_fma_f32 v137, v37, v137, v37
	v_mul_f32_e32 v134, 0x3f4c422a, v134
	v_mul_f32_e32 v135, 0x3f4c422a, v135
	v_mul_f32_e32 v136, 0x3f4c422a, v136
	v_mul_f32_e32 v137, 0x3f4c422a, v137
	v_mul_f32_e32 v134, -2.0, v134
	v_mul_f32_e32 v135, -2.0, v135
	v_mul_f32_e32 v136, -2.0, v136
	v_mul_f32_e32 v137, -2.0, v137
	v_mul_f32_e32 v134, 0x3fb8aa3b, v134
	v_mul_f32_e32 v135, 0x3fb8aa3b, v135
	v_mul_f32_e32 v136, 0x3fb8aa3b, v136
	v_mul_f32_e32 v137, 0x3fb8aa3b, v137
	v_exp_f32_e32 v134, v134
	v_exp_f32_e32 v135, v135
	v_exp_f32_e32 v136, v136
	v_exp_f32_e32 v137, v137
	v_add_f32_e32 v134, 1.0, v134
	v_add_f32_e32 v135, 1.0, v135
	v_add_f32_e32 v136, 1.0, v136
	v_add_f32_e32 v137, 1.0, v137
	v_rcp_f32_e32 v134, v134
	v_rcp_f32_e32 v135, v135
	v_rcp_f32_e32 v136, v136
	v_rcp_f32_e32 v137, v137
	s_nop 0
	v_mul_f32_e32 v34, v34, v134
	v_mul_f32_e32 v35, v35, v135
	v_mul_f32_e32 v36, v36, v136
	v_mul_f32_e32 v37, v37, v137
	v_pk_mul_f32 v[136:137], v[46:47], v[46:47]
	v_pk_mul_f32 v[138:139], v[48:49], v[48:49]
	v_add_f32_e32 v140, 0, v136
	v_add_f32_e32 v140, v137, v140
	v_add_f32_e32 v140, v138, v140
	v_add_f32_e32 v140, v139, v140
	v_pk_mul_f32 v[136:137], v[42:43], v[42:43]
	v_pk_mul_f32 v[138:139], v[44:45], v[44:45]
	v_add_f32_e32 v140, v136, v140
	v_add_f32_e32 v140, v137, v140
	v_add_f32_e32 v140, v138, v140
	v_add_f32_e32 v140, v139, v140
	v_pk_mul_f32 v[136:137], v[38:39], v[38:39]
	v_pk_mul_f32 v[138:139], v[40:41], v[40:41]
	v_add_f32_e32 v140, v136, v140
	v_add_f32_e32 v140, v137, v140
	v_add_f32_e32 v140, v138, v140
	v_add_f32_e32 v140, v139, v140
	v_pk_mul_f32 v[136:137], v[34:35], v[34:35]
	v_pk_mul_f32 v[138:139], v[36:37], v[36:37]
	v_add_f32_e32 v140, v136, v140
	v_add_f32_e32 v140, v137, v140
	v_add_f32_e32 v140, v138, v140
	v_add_f32_e32 v140, v139, v140
	ds_bpermute_b32 v141, v186, v140
	s_waitcnt lgkmcnt(0)
	v_add_f32_e32 v140, v140, v141
	ds_bpermute_b32 v141, v185, v140
	s_waitcnt lgkmcnt(0)
	v_add_f32_e32 v140, v140, v141
	v_mov_b32_e32 v141, 0x358637bd
	v_fmamk_f32 v140, v140, 0x3c800000, v141
	v_mul_f32_e32 v141, 0x4b800000, v140
	v_cmp_gt_f32_e32 vcc, 0x800000, v140
	s_nop 1
	v_cndmask_b32_e32 v140, v140, v141, vcc
	v_rsq_f32_e32 v140, v140
	s_nop 0
	v_mul_f32_e32 v141, 0x45800000, v140
	v_cndmask_b32_e32 v149, v140, v141, vcc
	v_mul_f32_e32 v130, 0x3d372713, v30
	v_mul_f32_e32 v131, 0x3d372713, v31
	v_mul_f32_e32 v132, 0x3d372713, v32
	v_mul_f32_e32 v133, 0x3d372713, v33
	v_mul_f32_e32 v130, v30, v130
	v_mul_f32_e32 v131, v31, v131
	v_mul_f32_e32 v132, v32, v132
	v_mul_f32_e32 v133, v33, v133
	v_fma_f32 v130, v30, v130, v30
	v_fma_f32 v131, v31, v131, v31
	v_fma_f32 v132, v32, v132, v32
	v_fma_f32 v133, v33, v133, v33
	v_mul_f32_e32 v130, 0x3f4c422a, v130
	v_mul_f32_e32 v131, 0x3f4c422a, v131
	v_mul_f32_e32 v132, 0x3f4c422a, v132
	v_mul_f32_e32 v133, 0x3f4c422a, v133
	v_mul_f32_e32 v130, -2.0, v130
	v_mul_f32_e32 v131, -2.0, v131
	v_mul_f32_e32 v132, -2.0, v132
	v_mul_f32_e32 v133, -2.0, v133
	v_mul_f32_e32 v130, 0x3fb8aa3b, v130
	v_mul_f32_e32 v131, 0x3fb8aa3b, v131
	v_mul_f32_e32 v132, 0x3fb8aa3b, v132
	v_mul_f32_e32 v133, 0x3fb8aa3b, v133
	v_exp_f32_e32 v130, v130
	v_exp_f32_e32 v131, v131
	v_exp_f32_e32 v132, v132
	v_exp_f32_e32 v133, v133
	v_add_f32_e32 v130, 1.0, v130
	v_add_f32_e32 v131, 1.0, v131
	v_add_f32_e32 v132, 1.0, v132
	v_add_f32_e32 v133, 1.0, v133
	v_rcp_f32_e32 v130, v130
	v_rcp_f32_e32 v131, v131
	v_rcp_f32_e32 v132, v132
	v_rcp_f32_e32 v133, v133
	s_nop 0
	v_mul_f32_e32 v30, v30, v130
	v_mul_f32_e32 v31, v31, v131
	v_mul_f32_e32 v32, v32, v132
	v_mul_f32_e32 v33, v33, v133
	v_mul_f32_e32 v134, 0x3d372713, v26
	v_mul_f32_e32 v135, 0x3d372713, v27
	v_mul_f32_e32 v136, 0x3d372713, v28
	v_mul_f32_e32 v137, 0x3d372713, v29
	v_mul_f32_e32 v134, v26, v134
	v_mul_f32_e32 v135, v27, v135
	v_mul_f32_e32 v136, v28, v136
	v_mul_f32_e32 v137, v29, v137
	v_fma_f32 v134, v26, v134, v26
	v_fma_f32 v135, v27, v135, v27
	v_fma_f32 v136, v28, v136, v28
	v_fma_f32 v137, v29, v137, v29
	v_mul_f32_e32 v134, 0x3f4c422a, v134
	v_mul_f32_e32 v135, 0x3f4c422a, v135
	v_mul_f32_e32 v136, 0x3f4c422a, v136
	v_mul_f32_e32 v137, 0x3f4c422a, v137
	v_mul_f32_e32 v134, -2.0, v134
	v_mul_f32_e32 v135, -2.0, v135
	v_mul_f32_e32 v136, -2.0, v136
	v_mul_f32_e32 v137, -2.0, v137
	v_mul_f32_e32 v134, 0x3fb8aa3b, v134
	v_mul_f32_e32 v135, 0x3fb8aa3b, v135
	v_mul_f32_e32 v136, 0x3fb8aa3b, v136
	v_mul_f32_e32 v137, 0x3fb8aa3b, v137
	v_exp_f32_e32 v134, v134
	v_exp_f32_e32 v135, v135
	v_exp_f32_e32 v136, v136
	v_exp_f32_e32 v137, v137
	v_add_f32_e32 v134, 1.0, v134
	v_add_f32_e32 v135, 1.0, v135
	v_add_f32_e32 v136, 1.0, v136
	v_add_f32_e32 v137, 1.0, v137
	v_rcp_f32_e32 v134, v134
	v_rcp_f32_e32 v135, v135
	v_rcp_f32_e32 v136, v136
	v_rcp_f32_e32 v137, v137
	s_nop 0
	v_mul_f32_e32 v26, v26, v134
	v_mul_f32_e32 v27, v27, v135
	v_mul_f32_e32 v28, v28, v136
	v_mul_f32_e32 v29, v29, v137
	v_mul_f32_e32 v130, 0x3d372713, v22
	v_mul_f32_e32 v131, 0x3d372713, v23
	v_mul_f32_e32 v132, 0x3d372713, v24
	v_mul_f32_e32 v133, 0x3d372713, v25
	v_mul_f32_e32 v130, v22, v130
	v_mul_f32_e32 v131, v23, v131
	v_mul_f32_e32 v132, v24, v132
	v_mul_f32_e32 v133, v25, v133
	v_fma_f32 v130, v22, v130, v22
	v_fma_f32 v131, v23, v131, v23
	v_fma_f32 v132, v24, v132, v24
	v_fma_f32 v133, v25, v133, v25
	v_mul_f32_e32 v130, 0x3f4c422a, v130
	v_mul_f32_e32 v131, 0x3f4c422a, v131
	v_mul_f32_e32 v132, 0x3f4c422a, v132
	v_mul_f32_e32 v133, 0x3f4c422a, v133
	v_mul_f32_e32 v130, -2.0, v130
	v_mul_f32_e32 v131, -2.0, v131
	v_mul_f32_e32 v132, -2.0, v132
	v_mul_f32_e32 v133, -2.0, v133
	v_mul_f32_e32 v130, 0x3fb8aa3b, v130
	v_mul_f32_e32 v131, 0x3fb8aa3b, v131
	v_mul_f32_e32 v132, 0x3fb8aa3b, v132
	v_mul_f32_e32 v133, 0x3fb8aa3b, v133
	v_exp_f32_e32 v130, v130
	v_exp_f32_e32 v131, v131
	v_exp_f32_e32 v132, v132
	v_exp_f32_e32 v133, v133
	v_add_f32_e32 v130, 1.0, v130
	v_add_f32_e32 v131, 1.0, v131
	v_add_f32_e32 v132, 1.0, v132
	v_add_f32_e32 v133, 1.0, v133
	v_rcp_f32_e32 v130, v130
	v_rcp_f32_e32 v131, v131
	v_rcp_f32_e32 v132, v132
	v_rcp_f32_e32 v133, v133
	s_nop 0
	v_mul_f32_e32 v22, v22, v130
	v_mul_f32_e32 v23, v23, v131
	v_mul_f32_e32 v24, v24, v132
	v_mul_f32_e32 v25, v25, v133
	v_mul_f32_e32 v134, 0x3d372713, v18
	v_mul_f32_e32 v135, 0x3d372713, v19
	v_mul_f32_e32 v136, 0x3d372713, v20
	v_mul_f32_e32 v137, 0x3d372713, v21
	v_mul_f32_e32 v134, v18, v134
	v_mul_f32_e32 v135, v19, v135
	v_mul_f32_e32 v136, v20, v136
	v_mul_f32_e32 v137, v21, v137
	v_fma_f32 v134, v18, v134, v18
	v_fma_f32 v135, v19, v135, v19
	v_fma_f32 v136, v20, v136, v20
	v_fma_f32 v137, v21, v137, v21
	v_mul_f32_e32 v134, 0x3f4c422a, v134
	v_mul_f32_e32 v135, 0x3f4c422a, v135
	v_mul_f32_e32 v136, 0x3f4c422a, v136
	v_mul_f32_e32 v137, 0x3f4c422a, v137
	v_mul_f32_e32 v134, -2.0, v134
	v_mul_f32_e32 v135, -2.0, v135
	v_mul_f32_e32 v136, -2.0, v136
	v_mul_f32_e32 v137, -2.0, v137
	v_mul_f32_e32 v134, 0x3fb8aa3b, v134
	v_mul_f32_e32 v135, 0x3fb8aa3b, v135
	v_mul_f32_e32 v136, 0x3fb8aa3b, v136
	v_mul_f32_e32 v137, 0x3fb8aa3b, v137
	v_exp_f32_e32 v134, v134
	v_exp_f32_e32 v135, v135
	v_exp_f32_e32 v136, v136
	v_exp_f32_e32 v137, v137
	v_add_f32_e32 v134, 1.0, v134
	v_add_f32_e32 v135, 1.0, v135
	v_add_f32_e32 v136, 1.0, v136
	v_add_f32_e32 v137, 1.0, v137
	v_rcp_f32_e32 v134, v134
	v_rcp_f32_e32 v135, v135
	v_rcp_f32_e32 v136, v136
	v_rcp_f32_e32 v137, v137
	s_nop 0
	v_mul_f32_e32 v18, v18, v134
	v_mul_f32_e32 v19, v19, v135
	v_mul_f32_e32 v20, v20, v136
	v_mul_f32_e32 v21, v21, v137
	v_pk_mul_f32 v[136:137], v[30:31], v[30:31]
	v_pk_mul_f32 v[138:139], v[32:33], v[32:33]
	v_add_f32_e32 v140, 0, v136
	v_add_f32_e32 v140, v137, v140
	v_add_f32_e32 v140, v138, v140
	v_add_f32_e32 v140, v139, v140
	v_pk_mul_f32 v[136:137], v[26:27], v[26:27]
	v_pk_mul_f32 v[138:139], v[28:29], v[28:29]
	v_add_f32_e32 v140, v136, v140
	v_add_f32_e32 v140, v137, v140
	v_add_f32_e32 v140, v138, v140
	v_add_f32_e32 v140, v139, v140
	v_pk_mul_f32 v[136:137], v[22:23], v[22:23]
	v_pk_mul_f32 v[138:139], v[24:25], v[24:25]
	v_add_f32_e32 v140, v136, v140
	v_add_f32_e32 v140, v137, v140
	v_add_f32_e32 v140, v138, v140
	v_add_f32_e32 v140, v139, v140
	v_pk_mul_f32 v[136:137], v[18:19], v[18:19]
	v_pk_mul_f32 v[138:139], v[20:21], v[20:21]
	v_add_f32_e32 v140, v136, v140
	v_add_f32_e32 v140, v137, v140
	v_add_f32_e32 v140, v138, v140
	v_add_f32_e32 v140, v139, v140
	ds_bpermute_b32 v141, v186, v140
	s_waitcnt lgkmcnt(0)
	v_add_f32_e32 v140, v140, v141
	ds_bpermute_b32 v141, v185, v140
	s_waitcnt lgkmcnt(0)
	v_add_f32_e32 v140, v140, v141
	v_mov_b32_e32 v141, 0x358637bd
	v_fmamk_f32 v140, v140, 0x3c800000, v141
	v_mul_f32_e32 v141, 0x4b800000, v140
	v_cmp_gt_f32_e32 vcc, 0x800000, v140
	s_nop 1
	v_cndmask_b32_e32 v140, v140, v141, vcc
	v_rsq_f32_e32 v140, v140
	s_nop 0
	v_mul_f32_e32 v141, 0x45800000, v140
	v_cndmask_b32_e32 v150, v140, v141, vcc
	v_mul_f32_e32 v130, 0x3d372713, v14
	v_mul_f32_e32 v131, 0x3d372713, v15
	v_mul_f32_e32 v132, 0x3d372713, v16
	v_mul_f32_e32 v133, 0x3d372713, v17
	v_mul_f32_e32 v130, v14, v130
	v_mul_f32_e32 v131, v15, v131
	v_mul_f32_e32 v132, v16, v132
	v_mul_f32_e32 v133, v17, v133
	v_fma_f32 v130, v14, v130, v14
	v_fma_f32 v131, v15, v131, v15
	v_fma_f32 v132, v16, v132, v16
	v_fma_f32 v133, v17, v133, v17
	v_mul_f32_e32 v130, 0x3f4c422a, v130
	v_mul_f32_e32 v131, 0x3f4c422a, v131
	v_mul_f32_e32 v132, 0x3f4c422a, v132
	v_mul_f32_e32 v133, 0x3f4c422a, v133
	v_mul_f32_e32 v130, -2.0, v130
	v_mul_f32_e32 v131, -2.0, v131
	v_mul_f32_e32 v132, -2.0, v132
	v_mul_f32_e32 v133, -2.0, v133
	v_mul_f32_e32 v130, 0x3fb8aa3b, v130
	v_mul_f32_e32 v131, 0x3fb8aa3b, v131
	v_mul_f32_e32 v132, 0x3fb8aa3b, v132
	v_mul_f32_e32 v133, 0x3fb8aa3b, v133
	v_exp_f32_e32 v130, v130
	v_exp_f32_e32 v131, v131
	v_exp_f32_e32 v132, v132
	v_exp_f32_e32 v133, v133
	v_add_f32_e32 v130, 1.0, v130
	v_add_f32_e32 v131, 1.0, v131
	v_add_f32_e32 v132, 1.0, v132
	v_add_f32_e32 v133, 1.0, v133
	v_rcp_f32_e32 v130, v130
	v_rcp_f32_e32 v131, v131
	v_rcp_f32_e32 v132, v132
	v_rcp_f32_e32 v133, v133
	s_nop 0
	v_mul_f32_e32 v14, v14, v130
	v_mul_f32_e32 v15, v15, v131
	v_mul_f32_e32 v16, v16, v132
	v_mul_f32_e32 v17, v17, v133
	v_mul_f32_e32 v134, 0x3d372713, v10
	v_mul_f32_e32 v135, 0x3d372713, v11
	v_mul_f32_e32 v136, 0x3d372713, v12
	v_mul_f32_e32 v137, 0x3d372713, v13
	v_mul_f32_e32 v134, v10, v134
	v_mul_f32_e32 v135, v11, v135
	v_mul_f32_e32 v136, v12, v136
	v_mul_f32_e32 v137, v13, v137
	v_fma_f32 v134, v10, v134, v10
	v_fma_f32 v135, v11, v135, v11
	v_fma_f32 v136, v12, v136, v12
	v_fma_f32 v137, v13, v137, v13
	v_mul_f32_e32 v134, 0x3f4c422a, v134
	v_mul_f32_e32 v135, 0x3f4c422a, v135
	v_mul_f32_e32 v136, 0x3f4c422a, v136
	v_mul_f32_e32 v137, 0x3f4c422a, v137
	v_mul_f32_e32 v134, -2.0, v134
	v_mul_f32_e32 v135, -2.0, v135
	v_mul_f32_e32 v136, -2.0, v136
	v_mul_f32_e32 v137, -2.0, v137
	v_mul_f32_e32 v134, 0x3fb8aa3b, v134
	v_mul_f32_e32 v135, 0x3fb8aa3b, v135
	v_mul_f32_e32 v136, 0x3fb8aa3b, v136
	v_mul_f32_e32 v137, 0x3fb8aa3b, v137
	v_exp_f32_e32 v134, v134
	v_exp_f32_e32 v135, v135
	v_exp_f32_e32 v136, v136
	v_exp_f32_e32 v137, v137
	v_add_f32_e32 v134, 1.0, v134
	v_add_f32_e32 v135, 1.0, v135
	v_add_f32_e32 v136, 1.0, v136
	v_add_f32_e32 v137, 1.0, v137
	v_rcp_f32_e32 v134, v134
	v_rcp_f32_e32 v135, v135
	v_rcp_f32_e32 v136, v136
	v_rcp_f32_e32 v137, v137
	s_nop 0
	v_mul_f32_e32 v10, v10, v134
	v_mul_f32_e32 v11, v11, v135
	v_mul_f32_e32 v12, v12, v136
	v_mul_f32_e32 v13, v13, v137
	v_mul_f32_e32 v130, 0x3d372713, v6
	v_mul_f32_e32 v131, 0x3d372713, v7
	v_mul_f32_e32 v132, 0x3d372713, v8
	v_mul_f32_e32 v133, 0x3d372713, v9
	v_mul_f32_e32 v130, v6, v130
	v_mul_f32_e32 v131, v7, v131
	v_mul_f32_e32 v132, v8, v132
	v_mul_f32_e32 v133, v9, v133
	v_fma_f32 v130, v6, v130, v6
	v_fma_f32 v131, v7, v131, v7
	v_fma_f32 v132, v8, v132, v8
	v_fma_f32 v133, v9, v133, v9
	v_mul_f32_e32 v130, 0x3f4c422a, v130
	v_mul_f32_e32 v131, 0x3f4c422a, v131
	v_mul_f32_e32 v132, 0x3f4c422a, v132
	v_mul_f32_e32 v133, 0x3f4c422a, v133
	v_mul_f32_e32 v130, -2.0, v130
	v_mul_f32_e32 v131, -2.0, v131
	v_mul_f32_e32 v132, -2.0, v132
	v_mul_f32_e32 v133, -2.0, v133
	v_mul_f32_e32 v130, 0x3fb8aa3b, v130
	v_mul_f32_e32 v131, 0x3fb8aa3b, v131
	v_mul_f32_e32 v132, 0x3fb8aa3b, v132
	v_mul_f32_e32 v133, 0x3fb8aa3b, v133
	v_exp_f32_e32 v130, v130
	v_exp_f32_e32 v131, v131
	v_exp_f32_e32 v132, v132
	v_exp_f32_e32 v133, v133
	v_add_f32_e32 v130, 1.0, v130
	v_add_f32_e32 v131, 1.0, v131
	v_add_f32_e32 v132, 1.0, v132
	v_add_f32_e32 v133, 1.0, v133
	v_rcp_f32_e32 v130, v130
	v_rcp_f32_e32 v131, v131
	v_rcp_f32_e32 v132, v132
	v_rcp_f32_e32 v133, v133
	s_nop 0
	v_mul_f32_e32 v6, v6, v130
	v_mul_f32_e32 v7, v7, v131
	v_mul_f32_e32 v8, v8, v132
	v_mul_f32_e32 v9, v9, v133
	v_mul_f32_e32 v134, 0x3d372713, v2
	v_mul_f32_e32 v135, 0x3d372713, v3
	v_mul_f32_e32 v136, 0x3d372713, v4
	v_mul_f32_e32 v137, 0x3d372713, v5
	v_mul_f32_e32 v134, v2, v134
	v_mul_f32_e32 v135, v3, v135
	v_mul_f32_e32 v136, v4, v136
	v_mul_f32_e32 v137, v5, v137
	v_fma_f32 v134, v2, v134, v2
	v_fma_f32 v135, v3, v135, v3
	v_fma_f32 v136, v4, v136, v4
	v_fma_f32 v137, v5, v137, v5
	v_mul_f32_e32 v134, 0x3f4c422a, v134
	v_mul_f32_e32 v135, 0x3f4c422a, v135
	v_mul_f32_e32 v136, 0x3f4c422a, v136
	v_mul_f32_e32 v137, 0x3f4c422a, v137
	v_mul_f32_e32 v134, -2.0, v134
	v_mul_f32_e32 v135, -2.0, v135
	v_mul_f32_e32 v136, -2.0, v136
	v_mul_f32_e32 v137, -2.0, v137
	v_mul_f32_e32 v134, 0x3fb8aa3b, v134
	v_mul_f32_e32 v135, 0x3fb8aa3b, v135
	v_mul_f32_e32 v136, 0x3fb8aa3b, v136
	v_mul_f32_e32 v137, 0x3fb8aa3b, v137
	v_exp_f32_e32 v134, v134
	v_exp_f32_e32 v135, v135
	v_exp_f32_e32 v136, v136
	v_exp_f32_e32 v137, v137
	v_add_f32_e32 v134, 1.0, v134
	v_add_f32_e32 v135, 1.0, v135
	v_add_f32_e32 v136, 1.0, v136
	v_add_f32_e32 v137, 1.0, v137
	v_rcp_f32_e32 v134, v134
	v_rcp_f32_e32 v135, v135
	v_rcp_f32_e32 v136, v136
	v_rcp_f32_e32 v137, v137
	s_nop 0
	v_mul_f32_e32 v2, v2, v134
	v_mul_f32_e32 v3, v3, v135
	v_mul_f32_e32 v4, v4, v136
	v_mul_f32_e32 v5, v5, v137
	v_pk_mul_f32 v[136:137], v[14:15], v[14:15]
	v_pk_mul_f32 v[138:139], v[16:17], v[16:17]
	v_add_f32_e32 v140, 0, v136
	v_add_f32_e32 v140, v137, v140
	v_add_f32_e32 v140, v138, v140
	v_add_f32_e32 v140, v139, v140
	v_pk_mul_f32 v[136:137], v[10:11], v[10:11]
	v_pk_mul_f32 v[138:139], v[12:13], v[12:13]
	v_add_f32_e32 v140, v136, v140
	v_add_f32_e32 v140, v137, v140
	v_add_f32_e32 v140, v138, v140
	v_add_f32_e32 v140, v139, v140
	v_pk_mul_f32 v[136:137], v[6:7], v[6:7]
	v_pk_mul_f32 v[138:139], v[8:9], v[8:9]
	v_add_f32_e32 v140, v136, v140
	v_add_f32_e32 v140, v137, v140
	v_add_f32_e32 v140, v138, v140
	v_add_f32_e32 v140, v139, v140
	v_pk_mul_f32 v[136:137], v[2:3], v[2:3]
	v_pk_mul_f32 v[138:139], v[4:5], v[4:5]
	v_add_f32_e32 v140, v136, v140
	v_add_f32_e32 v140, v137, v140
	v_add_f32_e32 v140, v138, v140
	v_add_f32_e32 v140, v139, v140
	ds_bpermute_b32 v141, v186, v140
	s_waitcnt lgkmcnt(0)
	v_add_f32_e32 v140, v140, v141
	ds_bpermute_b32 v141, v185, v140
	s_waitcnt lgkmcnt(0)
	v_add_f32_e32 v140, v140, v141
	v_mov_b32_e32 v141, 0x358637bd
	v_fmamk_f32 v140, v140, 0x3c800000, v141
	v_mul_f32_e32 v141, 0x4b800000, v140
	v_cmp_gt_f32_e32 vcc, 0x800000, v140
	s_nop 1
	v_cndmask_b32_e32 v140, v140, v141, vcc
	v_rsq_f32_e32 v140, v140
	s_nop 0
	v_mul_f32_e32 v141, 0x45800000, v140
	v_cndmask_b32_e32 v151, v140, v141, vcc
	v_fma_mixlo_f16 v130, v126, v144, 0
	v_fma_mixhi_f16 v130, v127, v144, 0
	ds_write_b16 v187, v130 offset:0
	ds_write_b16_d16_hi v187, v130 offset:144
	v_fma_mixlo_f16 v131, v128, v144, 0
	v_fma_mixhi_f16 v131, v129, v144, 0
	ds_write_b16 v187, v131 offset:288
	ds_write_b16_d16_hi v187, v131 offset:432
	v_fma_mixlo_f16 v132, v122, v144, 0
	v_fma_mixhi_f16 v132, v123, v144, 0
	ds_write_b16 v187, v132 offset:2304
	ds_write_b16_d16_hi v187, v132 offset:2448
	v_fma_mixlo_f16 v133, v124, v144, 0
	v_fma_mixhi_f16 v133, v125, v144, 0
	ds_write_b16 v187, v133 offset:2592
	ds_write_b16_d16_hi v187, v133 offset:2736
	v_fma_mixlo_f16 v134, v118, v144, 0
	v_fma_mixhi_f16 v134, v119, v144, 0
	ds_write_b16 v187, v134 offset:4608
	ds_write_b16_d16_hi v187, v134 offset:4752
	v_fma_mixlo_f16 v135, v120, v144, 0
	v_fma_mixhi_f16 v135, v121, v144, 0
	ds_write_b16 v187, v135 offset:4896
	ds_write_b16_d16_hi v187, v135 offset:5040
	v_fma_mixlo_f16 v136, v114, v144, 0
	v_fma_mixhi_f16 v136, v115, v144, 0
	ds_write_b16 v187, v136 offset:6912
	ds_write_b16_d16_hi v187, v136 offset:7056
	v_fma_mixlo_f16 v137, v116, v144, 0
	v_fma_mixhi_f16 v137, v117, v144, 0
	ds_write_b16 v187, v137 offset:7200
	ds_write_b16_d16_hi v187, v137 offset:7344
	v_fma_mixlo_f16 v130, v110, v145, 0
	v_fma_mixhi_f16 v130, v111, v145, 0
	ds_write_b16 v187, v130 offset:32
	ds_write_b16_d16_hi v187, v130 offset:176
	v_fma_mixlo_f16 v131, v112, v145, 0
	v_fma_mixhi_f16 v131, v113, v145, 0
	ds_write_b16 v187, v131 offset:320
	ds_write_b16_d16_hi v187, v131 offset:464
	v_fma_mixlo_f16 v132, v106, v145, 0
	v_fma_mixhi_f16 v132, v107, v145, 0
	ds_write_b16 v187, v132 offset:2336
	ds_write_b16_d16_hi v187, v132 offset:2480
	v_fma_mixlo_f16 v133, v108, v145, 0
	v_fma_mixhi_f16 v133, v109, v145, 0
	ds_write_b16 v187, v133 offset:2624
	ds_write_b16_d16_hi v187, v133 offset:2768
	v_fma_mixlo_f16 v134, v102, v145, 0
	v_fma_mixhi_f16 v134, v103, v145, 0
	ds_write_b16 v187, v134 offset:4640
	ds_write_b16_d16_hi v187, v134 offset:4784
	v_fma_mixlo_f16 v135, v104, v145, 0
	v_fma_mixhi_f16 v135, v105, v145, 0
	ds_write_b16 v187, v135 offset:4928
	ds_write_b16_d16_hi v187, v135 offset:5072
	v_fma_mixlo_f16 v136, v98, v145, 0
	v_fma_mixhi_f16 v136, v99, v145, 0
	ds_write_b16 v187, v136 offset:6944
	ds_write_b16_d16_hi v187, v136 offset:7088
	v_fma_mixlo_f16 v137, v100, v145, 0
	v_fma_mixhi_f16 v137, v101, v145, 0
	ds_write_b16 v187, v137 offset:7232
	ds_write_b16_d16_hi v187, v137 offset:7376
	v_fma_mixlo_f16 v130, v94, v146, 0
	v_fma_mixhi_f16 v130, v95, v146, 0
	ds_write_b16 v187, v130 offset:64
	ds_write_b16_d16_hi v187, v130 offset:208
	v_fma_mixlo_f16 v131, v96, v146, 0
	v_fma_mixhi_f16 v131, v97, v146, 0
	ds_write_b16 v187, v131 offset:352
	ds_write_b16_d16_hi v187, v131 offset:496
	v_fma_mixlo_f16 v132, v90, v146, 0
	v_fma_mixhi_f16 v132, v91, v146, 0
	ds_write_b16 v187, v132 offset:2368
	ds_write_b16_d16_hi v187, v132 offset:2512
	v_fma_mixlo_f16 v133, v92, v146, 0
	v_fma_mixhi_f16 v133, v93, v146, 0
	ds_write_b16 v187, v133 offset:2656
	ds_write_b16_d16_hi v187, v133 offset:2800
	v_fma_mixlo_f16 v134, v86, v146, 0
	v_fma_mixhi_f16 v134, v87, v146, 0
	ds_write_b16 v187, v134 offset:4672
	ds_write_b16_d16_hi v187, v134 offset:4816
	v_fma_mixlo_f16 v135, v88, v146, 0
	v_fma_mixhi_f16 v135, v89, v146, 0
	ds_write_b16 v187, v135 offset:4960
	ds_write_b16_d16_hi v187, v135 offset:5104
	v_fma_mixlo_f16 v136, v82, v146, 0
	v_fma_mixhi_f16 v136, v83, v146, 0
	ds_write_b16 v187, v136 offset:6976
	ds_write_b16_d16_hi v187, v136 offset:7120
	v_fma_mixlo_f16 v137, v84, v146, 0
	v_fma_mixhi_f16 v137, v85, v146, 0
	ds_write_b16 v187, v137 offset:7264
	ds_write_b16_d16_hi v187, v137 offset:7408
	v_fma_mixlo_f16 v130, v78, v147, 0
	v_fma_mixhi_f16 v130, v79, v147, 0
	ds_write_b16 v187, v130 offset:96
	ds_write_b16_d16_hi v187, v130 offset:240
	v_fma_mixlo_f16 v131, v80, v147, 0
	v_fma_mixhi_f16 v131, v81, v147, 0
	ds_write_b16 v187, v131 offset:384
	ds_write_b16_d16_hi v187, v131 offset:528
	v_fma_mixlo_f16 v132, v74, v147, 0
	v_fma_mixhi_f16 v132, v75, v147, 0
	ds_write_b16 v187, v132 offset:2400
	ds_write_b16_d16_hi v187, v132 offset:2544
	v_fma_mixlo_f16 v133, v76, v147, 0
	v_fma_mixhi_f16 v133, v77, v147, 0
	ds_write_b16 v187, v133 offset:2688
	ds_write_b16_d16_hi v187, v133 offset:2832
	v_fma_mixlo_f16 v134, v70, v147, 0
	v_fma_mixhi_f16 v134, v71, v147, 0
	ds_write_b16 v187, v134 offset:4704
	ds_write_b16_d16_hi v187, v134 offset:4848
	v_fma_mixlo_f16 v135, v72, v147, 0
	v_fma_mixhi_f16 v135, v73, v147, 0
	ds_write_b16 v187, v135 offset:4992
	ds_write_b16_d16_hi v187, v135 offset:5136
	v_fma_mixlo_f16 v136, v66, v147, 0
	v_fma_mixhi_f16 v136, v67, v147, 0
	ds_write_b16 v187, v136 offset:7008
	ds_write_b16_d16_hi v187, v136 offset:7152
	v_fma_mixlo_f16 v137, v68, v147, 0
	v_fma_mixhi_f16 v137, v69, v147, 0
	ds_write_b16 v187, v137 offset:7296
	ds_write_b16_d16_hi v187, v137 offset:7440
	s_waitcnt lgkmcnt(0)
	ds_read_b128 v[152:155], v189 offset:0
	ds_read_b128 v[156:159], v189 offset:1152
	ds_read_b128 v[160:163], v189 offset:2304
	ds_read_b128 v[164:167], v189 offset:3456
	ds_read_b128 v[168:171], v189 offset:4608
	ds_read_b128 v[172:175], v189 offset:5760
	ds_read_b128 v[176:179], v189 offset:6912
	ds_read_b128 v[180:183], v189 offset:8064
	s_waitcnt lgkmcnt(7)
	global_store_dwordx4 v193, v[152:155], s[22:23]
	v_add_u32_e32 v193, s3, v193
	s_waitcnt lgkmcnt(6)
	global_store_dwordx4 v193, v[156:159], s[22:23]
	v_add_u32_e32 v193, s3, v193
	s_waitcnt lgkmcnt(5)
	global_store_dwordx4 v193, v[160:163], s[22:23]
	v_add_u32_e32 v193, s3, v193
	s_waitcnt lgkmcnt(4)
	global_store_dwordx4 v193, v[164:167], s[22:23]
	v_add_u32_e32 v193, s3, v193
	s_waitcnt lgkmcnt(3)
	global_store_dwordx4 v193, v[168:171], s[22:23]
	v_add_u32_e32 v193, s3, v193
	s_waitcnt lgkmcnt(2)
	global_store_dwordx4 v193, v[172:175], s[22:23]
	v_add_u32_e32 v193, s3, v193
	s_waitcnt lgkmcnt(1)
	global_store_dwordx4 v193, v[176:179], s[22:23]
	v_add_u32_e32 v193, s3, v193
	s_waitcnt lgkmcnt(0)
	global_store_dwordx4 v193, v[180:183], s[22:23]
	s_lshl_b32 s2, s3, 3
	s_sub_i32 s2, 0x80, s2
	s_add_i32 s2, s2, s3
	v_add_u32_e32 v193, s2, v193
	v_fma_mixlo_f16 v130, v62, v148, 0
	v_fma_mixhi_f16 v130, v63, v148, 0
	ds_write_b16 v187, v130 offset:0
	ds_write_b16_d16_hi v187, v130 offset:144
	v_fma_mixlo_f16 v131, v64, v148, 0
	v_fma_mixhi_f16 v131, v65, v148, 0
	ds_write_b16 v187, v131 offset:288
	ds_write_b16_d16_hi v187, v131 offset:432
	v_fma_mixlo_f16 v132, v58, v148, 0
	v_fma_mixhi_f16 v132, v59, v148, 0
	ds_write_b16 v187, v132 offset:2304
	ds_write_b16_d16_hi v187, v132 offset:2448
	v_fma_mixlo_f16 v133, v60, v148, 0
	v_fma_mixhi_f16 v133, v61, v148, 0
	ds_write_b16 v187, v133 offset:2592
	ds_write_b16_d16_hi v187, v133 offset:2736
	v_fma_mixlo_f16 v134, v54, v148, 0
	v_fma_mixhi_f16 v134, v55, v148, 0
	ds_write_b16 v187, v134 offset:4608
	ds_write_b16_d16_hi v187, v134 offset:4752
	v_fma_mixlo_f16 v135, v56, v148, 0
	v_fma_mixhi_f16 v135, v57, v148, 0
	ds_write_b16 v187, v135 offset:4896
	ds_write_b16_d16_hi v187, v135 offset:5040
	v_fma_mixlo_f16 v136, v50, v148, 0
	v_fma_mixhi_f16 v136, v51, v148, 0
	ds_write_b16 v187, v136 offset:6912
	ds_write_b16_d16_hi v187, v136 offset:7056
	v_fma_mixlo_f16 v137, v52, v148, 0
	v_fma_mixhi_f16 v137, v53, v148, 0
	ds_write_b16 v187, v137 offset:7200
	ds_write_b16_d16_hi v187, v137 offset:7344
	v_fma_mixlo_f16 v130, v46, v149, 0
	v_fma_mixhi_f16 v130, v47, v149, 0
	ds_write_b16 v187, v130 offset:32
	ds_write_b16_d16_hi v187, v130 offset:176
	v_fma_mixlo_f16 v131, v48, v149, 0
	v_fma_mixhi_f16 v131, v49, v149, 0
	ds_write_b16 v187, v131 offset:320
	ds_write_b16_d16_hi v187, v131 offset:464
	v_fma_mixlo_f16 v132, v42, v149, 0
	v_fma_mixhi_f16 v132, v43, v149, 0
	ds_write_b16 v187, v132 offset:2336
	ds_write_b16_d16_hi v187, v132 offset:2480
	v_fma_mixlo_f16 v133, v44, v149, 0
	v_fma_mixhi_f16 v133, v45, v149, 0
	ds_write_b16 v187, v133 offset:2624
	ds_write_b16_d16_hi v187, v133 offset:2768
	v_fma_mixlo_f16 v134, v38, v149, 0
	v_fma_mixhi_f16 v134, v39, v149, 0
	ds_write_b16 v187, v134 offset:4640
	ds_write_b16_d16_hi v187, v134 offset:4784
	v_fma_mixlo_f16 v135, v40, v149, 0
	v_fma_mixhi_f16 v135, v41, v149, 0
	ds_write_b16 v187, v135 offset:4928
	ds_write_b16_d16_hi v187, v135 offset:5072
	v_fma_mixlo_f16 v136, v34, v149, 0
	v_fma_mixhi_f16 v136, v35, v149, 0
	ds_write_b16 v187, v136 offset:6944
	ds_write_b16_d16_hi v187, v136 offset:7088
	v_fma_mixlo_f16 v137, v36, v149, 0
	v_fma_mixhi_f16 v137, v37, v149, 0
	ds_write_b16 v187, v137 offset:7232
	ds_write_b16_d16_hi v187, v137 offset:7376
	v_fma_mixlo_f16 v130, v30, v150, 0
	v_fma_mixhi_f16 v130, v31, v150, 0
	ds_write_b16 v187, v130 offset:64
	ds_write_b16_d16_hi v187, v130 offset:208
	v_fma_mixlo_f16 v131, v32, v150, 0
	v_fma_mixhi_f16 v131, v33, v150, 0
	ds_write_b16 v187, v131 offset:352
	ds_write_b16_d16_hi v187, v131 offset:496
	v_fma_mixlo_f16 v132, v26, v150, 0
	v_fma_mixhi_f16 v132, v27, v150, 0
	ds_write_b16 v187, v132 offset:2368
	ds_write_b16_d16_hi v187, v132 offset:2512
	v_fma_mixlo_f16 v133, v28, v150, 0
	v_fma_mixhi_f16 v133, v29, v150, 0
	ds_write_b16 v187, v133 offset:2656
	ds_write_b16_d16_hi v187, v133 offset:2800
	v_fma_mixlo_f16 v134, v22, v150, 0
	v_fma_mixhi_f16 v134, v23, v150, 0
	ds_write_b16 v187, v134 offset:4672
	ds_write_b16_d16_hi v187, v134 offset:4816
	v_fma_mixlo_f16 v135, v24, v150, 0
	v_fma_mixhi_f16 v135, v25, v150, 0
	ds_write_b16 v187, v135 offset:4960
	ds_write_b16_d16_hi v187, v135 offset:5104
	v_fma_mixlo_f16 v136, v18, v150, 0
	v_fma_mixhi_f16 v136, v19, v150, 0
	ds_write_b16 v187, v136 offset:6976
	ds_write_b16_d16_hi v187, v136 offset:7120
	v_fma_mixlo_f16 v137, v20, v150, 0
	v_fma_mixhi_f16 v137, v21, v150, 0
	ds_write_b16 v187, v137 offset:7264
	ds_write_b16_d16_hi v187, v137 offset:7408
	v_fma_mixlo_f16 v130, v14, v151, 0
	v_fma_mixhi_f16 v130, v15, v151, 0
	ds_write_b16 v187, v130 offset:96
	ds_write_b16_d16_hi v187, v130 offset:240
	v_fma_mixlo_f16 v131, v16, v151, 0
	v_fma_mixhi_f16 v131, v17, v151, 0
	ds_write_b16 v187, v131 offset:384
	ds_write_b16_d16_hi v187, v131 offset:528
	v_fma_mixlo_f16 v132, v10, v151, 0
	v_fma_mixhi_f16 v132, v11, v151, 0
	ds_write_b16 v187, v132 offset:2400
	ds_write_b16_d16_hi v187, v132 offset:2544
	v_fma_mixlo_f16 v133, v12, v151, 0
	v_fma_mixhi_f16 v133, v13, v151, 0
	ds_write_b16 v187, v133 offset:2688
	ds_write_b16_d16_hi v187, v133 offset:2832
	v_fma_mixlo_f16 v134, v6, v151, 0
	v_fma_mixhi_f16 v134, v7, v151, 0
	ds_write_b16 v187, v134 offset:4704
	ds_write_b16_d16_hi v187, v134 offset:4848
	v_fma_mixlo_f16 v135, v8, v151, 0
	v_fma_mixhi_f16 v135, v9, v151, 0
	ds_write_b16 v187, v135 offset:4992
	ds_write_b16_d16_hi v187, v135 offset:5136
	v_fma_mixlo_f16 v136, v2, v151, 0
	v_fma_mixhi_f16 v136, v3, v151, 0
	ds_write_b16 v187, v136 offset:7008
	ds_write_b16_d16_hi v187, v136 offset:7152
	v_fma_mixlo_f16 v137, v4, v151, 0
	v_fma_mixhi_f16 v137, v5, v151, 0
	ds_write_b16 v187, v137 offset:7296
	ds_write_b16_d16_hi v187, v137 offset:7440
	s_waitcnt lgkmcnt(0)
	ds_read_b128 v[152:155], v189 offset:0
	ds_read_b128 v[156:159], v189 offset:1152
	ds_read_b128 v[160:163], v189 offset:2304
	ds_read_b128 v[164:167], v189 offset:3456
	ds_read_b128 v[168:171], v189 offset:4608
	ds_read_b128 v[172:175], v189 offset:5760
	ds_read_b128 v[176:179], v189 offset:6912
	ds_read_b128 v[180:183], v189 offset:8064
	s_waitcnt lgkmcnt(7)
	global_store_dwordx4 v193, v[152:155], s[22:23]
	v_add_u32_e32 v193, s3, v193
	s_waitcnt lgkmcnt(6)
	global_store_dwordx4 v193, v[156:159], s[22:23]
	v_add_u32_e32 v193, s3, v193
	s_waitcnt lgkmcnt(5)
	global_store_dwordx4 v193, v[160:163], s[22:23]
	v_add_u32_e32 v193, s3, v193
	s_waitcnt lgkmcnt(4)
	global_store_dwordx4 v193, v[164:167], s[22:23]
	v_add_u32_e32 v193, s3, v193
	s_waitcnt lgkmcnt(3)
	global_store_dwordx4 v193, v[168:171], s[22:23]
	v_add_u32_e32 v193, s3, v193
	s_waitcnt lgkmcnt(2)
	global_store_dwordx4 v193, v[172:175], s[22:23]
	v_add_u32_e32 v193, s3, v193
	s_waitcnt lgkmcnt(1)
	global_store_dwordx4 v193, v[176:179], s[22:23]
	v_add_u32_e32 v193, s3, v193
	s_waitcnt lgkmcnt(0)
	global_store_dwordx4 v193, v[180:183], s[22:23]
	s_waitcnt vmcnt(16)
	s_branch .Lp1_join
.Lp1_e_plain:
	v_and_b32_e32 v194, 15, v222
	v_bfe_u32 v195, v222, 4, 2
	v_bfe_u32 v196, v222, 6, 2
	v_lshrrev_b32_e32 v197, 8, v222
	v_lshl_or_b32 v198, v197, 7, v194
	v_lshlrev_b32_e32 v199, 2, v195
	v_lshl_or_b32 v199, v196, 6, v199
	v_readlane_b32 s22, v254, 14
	v_readlane_b32 s23, v254, 15
	s_nop 3
	s_add_u32 s22, s22, 0xbcae500
	s_addc_u32 s23, s23, 0
	s_mul_i32 s2, s4, 0x60000
	s_add_i32 s3, s5, -2
	s_lshl_b32 s3, s3, 9
	s_add_i32 s2, s2, s3
	s_add_u32 s22, s22, s2
	s_addc_u32 s23, s23, 0
	v_mul_u32_u24_e32 v193, 0x600, v198
	v_lshl_add_u32 v193, v199, 1, v193
	s_add_i32 s2, s53, s95
	s_cmp_lt_i32 s2, s9
	s_cselect_b32 s21, 1, 0
	s_cselect_b32 s53, s2, s53
	s_lshr_b32 s2, s53, 5
	s_mul_hi_u32 s2, s2, 0xcccccccd
	s_lshr_b32 s2, s2, 2
	s_lshl_b32 s3, s2, 4
	s_mul_i32 s2, s2, 0xa0
	s_sub_i32 s2, s53, s2
	s_lshr_b32 s2, s2, 4
	s_and_b32 s6, s53, 15
	s_add_i32 s3, s3, s6
	s_sub_i32 s28, s53, s58
	s_lshr_b32 s28, s28, 4
	s_add_i32 s28, s28, 8
	s_or_b32 s6, s6, 0x80
	s_cmp_ge_i32 s53, s58
	s_cselect_b32 s6, s6, s3
	s_cselect_b32 s28, s28, s2
	s_lshl_b32 s2, s6, 19
	s_add_u32 s12, s64, s2
	s_addc_u32 s13, s65, 0
	s_lshl_b32 s2, s28, 19
	s_add_u32 s14, s34, s2
	s_addc_u32 s15, s35, 0
	s_mov_b32 m0, s18
	s_nop 0
	global_load_lds_dwordx4 v1, s[12:13]
	s_add_i32 m0, s18, 0x2000
	s_add_u32 s16, s12, 0x20000
	s_addc_u32 s17, s13, 0
	global_load_lds_dwordx4 v1, s[16:17]
	s_add_i32 m0, s18, 0x4000
	s_add_u32 s16, s12, 0x40000
	s_addc_u32 s17, s13, 0
	global_load_lds_dwordx4 v1, s[16:17]
	s_add_i32 m0, s18, 0x6000
	s_add_u32 s16, s12, 0x60000
	s_addc_u32 s17, s13, 0
	global_load_lds_dwordx4 v1, s[16:17]
	s_add_i32 m0, s18, 0x8000
	s_nop 0
	global_load_lds_dwordx4 v1, s[14:15]
	s_add_i32 m0, s18, 0xa000
	s_add_u32 s16, s14, 0x20000
	s_addc_u32 s17, s15, 0
	global_load_lds_dwordx4 v1, s[16:17]
	s_add_i32 m0, s18, 0xc000
	s_add_u32 s16, s14, 0x40000
	s_addc_u32 s17, s15, 0
	global_load_lds_dwordx4 v1, s[16:17]
	s_add_i32 m0, s18, 0xe000
	s_add_u32 s16, s14, 0x60000
	s_addc_u32 s17, s15, 0
	global_load_lds_dwordx4 v1, s[16:17]
	v_cvt_pk_f16_f32 v126, v126, v127
	v_cvt_pk_f16_f32 v127, v128, v129
	global_store_dwordx2 v193, v[126:127], s[22:23] offset:0
	v_cvt_pk_f16_f32 v122, v122, v123
	v_cvt_pk_f16_f32 v123, v124, v125
	global_store_dwordx2 v193, v[122:123], s[22:23] offset:32
	v_cvt_pk_f16_f32 v118, v118, v119
	v_cvt_pk_f16_f32 v119, v120, v121
	global_store_dwordx2 v193, v[118:119], s[22:23] offset:64
	v_cvt_pk_f16_f32 v114, v114, v115
	v_cvt_pk_f16_f32 v115, v116, v117
	global_store_dwordx2 v193, v[114:115], s[22:23] offset:96
	v_add_u32_e32 v193, 0x6000, v193
	v_cvt_pk_f16_f32 v110, v110, v111
	v_cvt_pk_f16_f32 v111, v112, v113
	global_store_dwordx2 v193, v[110:111], s[22:23] offset:0
	v_cvt_pk_f16_f32 v106, v106, v107
	v_cvt_pk_f16_f32 v107, v108, v109
	global_store_dwordx2 v193, v[106:107], s[22:23] offset:32
	v_cvt_pk_f16_f32 v102, v102, v103
	v_cvt_pk_f16_f32 v103, v104, v105
	global_store_dwordx2 v193, v[102:103], s[22:23] offset:64
	v_cvt_pk_f16_f32 v98, v98, v99
	v_cvt_pk_f16_f32 v99, v100, v101
	global_store_dwordx2 v193, v[98:99], s[22:23] offset:96
	v_add_u32_e32 v193, 0x6000, v193
	v_cvt_pk_f16_f32 v94, v94, v95
	v_cvt_pk_f16_f32 v95, v96, v97
	global_store_dwordx2 v193, v[94:95], s[22:23] offset:0
	v_cvt_pk_f16_f32 v90, v90, v91
	v_cvt_pk_f16_f32 v91, v92, v93
	global_store_dwordx2 v193, v[90:91], s[22:23] offset:32
	v_cvt_pk_f16_f32 v86, v86, v87
	v_cvt_pk_f16_f32 v87, v88, v89
	global_store_dwordx2 v193, v[86:87], s[22:23] offset:64
	v_cvt_pk_f16_f32 v82, v82, v83
	v_cvt_pk_f16_f32 v83, v84, v85
	global_store_dwordx2 v193, v[82:83], s[22:23] offset:96
	v_add_u32_e32 v193, 0x6000, v193
	v_cvt_pk_f16_f32 v78, v78, v79
	v_cvt_pk_f16_f32 v79, v80, v81
	global_store_dwordx2 v193, v[78:79], s[22:23] offset:0
	v_cvt_pk_f16_f32 v74, v74, v75
	v_cvt_pk_f16_f32 v75, v76, v77
	global_store_dwordx2 v193, v[74:75], s[22:23] offset:32
	v_cvt_pk_f16_f32 v70, v70, v71
	v_cvt_pk_f16_f32 v71, v72, v73
	global_store_dwordx2 v193, v[70:71], s[22:23] offset:64
	v_cvt_pk_f16_f32 v66, v66, v67
	v_cvt_pk_f16_f32 v67, v68, v69
	global_store_dwordx2 v193, v[66:67], s[22:23] offset:96
	v_add_u32_e32 v193, 0x6000, v193
	v_cvt_pk_f16_f32 v62, v62, v63
	v_cvt_pk_f16_f32 v63, v64, v65
	global_store_dwordx2 v193, v[62:63], s[22:23] offset:0
	v_cvt_pk_f16_f32 v58, v58, v59
	v_cvt_pk_f16_f32 v59, v60, v61
	global_store_dwordx2 v193, v[58:59], s[22:23] offset:32
	v_cvt_pk_f16_f32 v54, v54, v55
	v_cvt_pk_f16_f32 v55, v56, v57
	global_store_dwordx2 v193, v[54:55], s[22:23] offset:64
	v_cvt_pk_f16_f32 v50, v50, v51
	v_cvt_pk_f16_f32 v51, v52, v53
	global_store_dwordx2 v193, v[50:51], s[22:23] offset:96
	v_add_u32_e32 v193, 0x6000, v193
	v_cvt_pk_f16_f32 v46, v46, v47
	v_cvt_pk_f16_f32 v47, v48, v49
	global_store_dwordx2 v193, v[46:47], s[22:23] offset:0
	v_cvt_pk_f16_f32 v42, v42, v43
	v_cvt_pk_f16_f32 v43, v44, v45
	global_store_dwordx2 v193, v[42:43], s[22:23] offset:32
	v_cvt_pk_f16_f32 v38, v38, v39
	v_cvt_pk_f16_f32 v39, v40, v41
	global_store_dwordx2 v193, v[38:39], s[22:23] offset:64
	v_cvt_pk_f16_f32 v34, v34, v35
	v_cvt_pk_f16_f32 v35, v36, v37
	global_store_dwordx2 v193, v[34:35], s[22:23] offset:96
	v_add_u32_e32 v193, 0x6000, v193
	v_cvt_pk_f16_f32 v30, v30, v31
	v_cvt_pk_f16_f32 v31, v32, v33
	global_store_dwordx2 v193, v[30:31], s[22:23] offset:0
	v_cvt_pk_f16_f32 v26, v26, v27
	v_cvt_pk_f16_f32 v27, v28, v29
	global_store_dwordx2 v193, v[26:27], s[22:23] offset:32
	v_cvt_pk_f16_f32 v22, v22, v23
	v_cvt_pk_f16_f32 v23, v24, v25
	global_store_dwordx2 v193, v[22:23], s[22:23] offset:64
	v_cvt_pk_f16_f32 v18, v18, v19
	v_cvt_pk_f16_f32 v19, v20, v21
	global_store_dwordx2 v193, v[18:19], s[22:23] offset:96
	v_add_u32_e32 v193, 0x6000, v193
	v_cvt_pk_f16_f32 v14, v14, v15
	v_cvt_pk_f16_f32 v15, v16, v17
	global_store_dwordx2 v193, v[14:15], s[22:23] offset:0
	v_cvt_pk_f16_f32 v10, v10, v11
	v_cvt_pk_f16_f32 v11, v12, v13
	global_store_dwordx2 v193, v[10:11], s[22:23] offset:32
	v_cvt_pk_f16_f32 v6, v6, v7
	v_cvt_pk_f16_f32 v7, v8, v9
	global_store_dwordx2 v193, v[6:7], s[22:23] offset:64
	v_cvt_pk_f16_f32 v2, v2, v3
	v_cvt_pk_f16_f32 v3, v4, v5
	global_store_dwordx2 v193, v[2:3], s[22:23] offset:96
	s_waitcnt vmcnt(32)
	s_branch .Lp1_join
.Lp1_e_gelu:
	v_and_b32_e32 v194, 15, v222
	v_bfe_u32 v195, v222, 4, 2
	v_bfe_u32 v196, v222, 6, 2
	v_lshrrev_b32_e32 v197, 8, v222
	v_lshl_or_b32 v198, v197, 7, v194
	v_lshlrev_b32_e32 v199, 2, v195
	v_lshl_or_b32 v199, v196, 6, v199
	v_readlane_b32 s22, v254, 14
	v_readlane_b32 s23, v254, 15
	s_nop 3
	s_add_u32 s22, s22, 0x98ae500
	s_addc_u32 s23, s23, 0
	s_lshl_b32 s2, s4, 17
	s_add_u32 s22, s22, s2
	s_addc_u32 s23, s23, 0
	v_lshlrev_b32_e32 v193, 9, v198
	v_lshl_add_u32 v193, v199, 1, v193
	s_add_i32 s2, s53, s95
	s_cmp_lt_i32 s2, s9
	s_cselect_b32 s21, 1, 0
	s_cselect_b32 s53, s2, s53
	s_lshr_b32 s2, s53, 5
	s_mul_hi_u32 s2, s2, 0xcccccccd
	s_lshr_b32 s2, s2, 2
	s_lshl_b32 s3, s2, 4
	s_mul_i32 s2, s2, 0xa0
	s_sub_i32 s2, s53, s2
	s_lshr_b32 s2, s2, 4
	s_and_b32 s6, s53, 15
	s_add_i32 s3, s3, s6
	s_sub_i32 s28, s53, s58
	s_lshr_b32 s28, s28, 4
	s_add_i32 s28, s28, 8
	s_or_b32 s6, s6, 0x80
	s_cmp_ge_i32 s53, s58
	s_cselect_b32 s6, s6, s3
	s_cselect_b32 s28, s28, s2
	s_lshl_b32 s2, s6, 19
	s_add_u32 s12, s64, s2
	s_addc_u32 s13, s65, 0
	s_lshl_b32 s2, s28, 19
	s_add_u32 s14, s34, s2
	s_addc_u32 s15, s35, 0
	s_mov_b32 m0, s18
	s_nop 0
	global_load_lds_dwordx4 v1, s[12:13]
	s_add_i32 m0, s18, 0x2000
	s_add_u32 s16, s12, 0x20000
	s_addc_u32 s17, s13, 0
	global_load_lds_dwordx4 v1, s[16:17]
	s_add_i32 m0, s18, 0x4000
	s_add_u32 s16, s12, 0x40000
	s_addc_u32 s17, s13, 0
	global_load_lds_dwordx4 v1, s[16:17]
	s_add_i32 m0, s18, 0x6000
	s_add_u32 s16, s12, 0x60000
	s_addc_u32 s17, s13, 0
	global_load_lds_dwordx4 v1, s[16:17]
	s_add_i32 m0, s18, 0x8000
	s_nop 0
	global_load_lds_dwordx4 v1, s[14:15]
	s_add_i32 m0, s18, 0xa000
	s_add_u32 s16, s14, 0x20000
	s_addc_u32 s17, s15, 0
	global_load_lds_dwordx4 v1, s[16:17]
	s_add_i32 m0, s18, 0xc000
	s_add_u32 s16, s14, 0x40000
	s_addc_u32 s17, s15, 0
	global_load_lds_dwordx4 v1, s[16:17]
	s_add_i32 m0, s18, 0xe000
	s_add_u32 s16, s14, 0x60000
	s_addc_u32 s17, s15, 0
	global_load_lds_dwordx4 v1, s[16:17]
	v_mul_f32_e32 v130, 0x3d372713, v126
	v_mul_f32_e32 v131, 0x3d372713, v127
	v_mul_f32_e32 v132, 0x3d372713, v128
	v_mul_f32_e32 v133, 0x3d372713, v129
	v_mul_f32_e32 v130, v126, v130
	v_mul_f32_e32 v131, v127, v131
	v_mul_f32_e32 v132, v128, v132
	v_mul_f32_e32 v133, v129, v133
	v_fma_f32 v130, v126, v130, v126
	v_fma_f32 v131, v127, v131, v127
	v_fma_f32 v132, v128, v132, v128
	v_fma_f32 v133, v129, v133, v129
	v_mul_f32_e32 v130, 0x3f4c422a, v130
	v_mul_f32_e32 v131, 0x3f4c422a, v131
	v_mul_f32_e32 v132, 0x3f4c422a, v132
	v_mul_f32_e32 v133, 0x3f4c422a, v133
	v_mul_f32_e32 v130, -2.0, v130
	v_mul_f32_e32 v131, -2.0, v131
	v_mul_f32_e32 v132, -2.0, v132
	v_mul_f32_e32 v133, -2.0, v133
	v_mul_f32_e32 v130, 0x3fb8aa3b, v130
	v_mul_f32_e32 v131, 0x3fb8aa3b, v131
	v_mul_f32_e32 v132, 0x3fb8aa3b, v132
	v_mul_f32_e32 v133, 0x3fb8aa3b, v133
	v_exp_f32_e32 v130, v130
	v_exp_f32_e32 v131, v131
	v_exp_f32_e32 v132, v132
	v_exp_f32_e32 v133, v133
	v_add_f32_e32 v130, 1.0, v130
	v_add_f32_e32 v131, 1.0, v131
	v_add_f32_e32 v132, 1.0, v132
	v_add_f32_e32 v133, 1.0, v133
	v_rcp_f32_e32 v130, v130
	v_rcp_f32_e32 v131, v131
	v_rcp_f32_e32 v132, v132
	v_rcp_f32_e32 v133, v133
	s_nop 0
	v_mul_f32_e32 v126, v126, v130
	v_mul_f32_e32 v127, v127, v131
	v_mul_f32_e32 v128, v128, v132
	v_mul_f32_e32 v129, v129, v133
	v_cvt_pk_f16_f32 v126, v126, v127
	v_cvt_pk_f16_f32 v127, v128, v129
	global_store_dwordx2 v193, v[126:127], s[22:23] offset:0
	v_mul_f32_e32 v134, 0x3d372713, v122
	v_mul_f32_e32 v135, 0x3d372713, v123
	v_mul_f32_e32 v136, 0x3d372713, v124
	v_mul_f32_e32 v137, 0x3d372713, v125
	v_mul_f32_e32 v134, v122, v134
	v_mul_f32_e32 v135, v123, v135
	v_mul_f32_e32 v136, v124, v136
	v_mul_f32_e32 v137, v125, v137
	v_fma_f32 v134, v122, v134, v122
	v_fma_f32 v135, v123, v135, v123
	v_fma_f32 v136, v124, v136, v124
	v_fma_f32 v137, v125, v137, v125
	v_mul_f32_e32 v134, 0x3f4c422a, v134
	v_mul_f32_e32 v135, 0x3f4c422a, v135
	v_mul_f32_e32 v136, 0x3f4c422a, v136
	v_mul_f32_e32 v137, 0x3f4c422a, v137
	v_mul_f32_e32 v134, -2.0, v134
	v_mul_f32_e32 v135, -2.0, v135
	v_mul_f32_e32 v136, -2.0, v136
	v_mul_f32_e32 v137, -2.0, v137
	v_mul_f32_e32 v134, 0x3fb8aa3b, v134
	v_mul_f32_e32 v135, 0x3fb8aa3b, v135
	v_mul_f32_e32 v136, 0x3fb8aa3b, v136
	v_mul_f32_e32 v137, 0x3fb8aa3b, v137
	v_exp_f32_e32 v134, v134
	v_exp_f32_e32 v135, v135
	v_exp_f32_e32 v136, v136
	v_exp_f32_e32 v137, v137
	v_add_f32_e32 v134, 1.0, v134
	v_add_f32_e32 v135, 1.0, v135
	v_add_f32_e32 v136, 1.0, v136
	v_add_f32_e32 v137, 1.0, v137
	v_rcp_f32_e32 v134, v134
	v_rcp_f32_e32 v135, v135
	v_rcp_f32_e32 v136, v136
	v_rcp_f32_e32 v137, v137
	s_nop 0
	v_mul_f32_e32 v122, v122, v134
	v_mul_f32_e32 v123, v123, v135
	v_mul_f32_e32 v124, v124, v136
	v_mul_f32_e32 v125, v125, v137
	v_cvt_pk_f16_f32 v122, v122, v123
	v_cvt_pk_f16_f32 v123, v124, v125
	global_store_dwordx2 v193, v[122:123], s[22:23] offset:32
	v_mul_f32_e32 v130, 0x3d372713, v118
	v_mul_f32_e32 v131, 0x3d372713, v119
	v_mul_f32_e32 v132, 0x3d372713, v120
	v_mul_f32_e32 v133, 0x3d372713, v121
	v_mul_f32_e32 v130, v118, v130
	v_mul_f32_e32 v131, v119, v131
	v_mul_f32_e32 v132, v120, v132
	v_mul_f32_e32 v133, v121, v133
	v_fma_f32 v130, v118, v130, v118
	v_fma_f32 v131, v119, v131, v119
	v_fma_f32 v132, v120, v132, v120
	v_fma_f32 v133, v121, v133, v121
	v_mul_f32_e32 v130, 0x3f4c422a, v130
	v_mul_f32_e32 v131, 0x3f4c422a, v131
	v_mul_f32_e32 v132, 0x3f4c422a, v132
	v_mul_f32_e32 v133, 0x3f4c422a, v133
	v_mul_f32_e32 v130, -2.0, v130
	v_mul_f32_e32 v131, -2.0, v131
	v_mul_f32_e32 v132, -2.0, v132
	v_mul_f32_e32 v133, -2.0, v133
	v_mul_f32_e32 v130, 0x3fb8aa3b, v130
	v_mul_f32_e32 v131, 0x3fb8aa3b, v131
	v_mul_f32_e32 v132, 0x3fb8aa3b, v132
	v_mul_f32_e32 v133, 0x3fb8aa3b, v133
	v_exp_f32_e32 v130, v130
	v_exp_f32_e32 v131, v131
	v_exp_f32_e32 v132, v132
	v_exp_f32_e32 v133, v133
	v_add_f32_e32 v130, 1.0, v130
	v_add_f32_e32 v131, 1.0, v131
	v_add_f32_e32 v132, 1.0, v132
	v_add_f32_e32 v133, 1.0, v133
	v_rcp_f32_e32 v130, v130
	v_rcp_f32_e32 v131, v131
	v_rcp_f32_e32 v132, v132
	v_rcp_f32_e32 v133, v133
	s_nop 0
	v_mul_f32_e32 v118, v118, v130
	v_mul_f32_e32 v119, v119, v131
	v_mul_f32_e32 v120, v120, v132
	v_mul_f32_e32 v121, v121, v133
	v_cvt_pk_f16_f32 v118, v118, v119
	v_cvt_pk_f16_f32 v119, v120, v121
	global_store_dwordx2 v193, v[118:119], s[22:23] offset:64
	v_mul_f32_e32 v134, 0x3d372713, v114
	v_mul_f32_e32 v135, 0x3d372713, v115
	v_mul_f32_e32 v136, 0x3d372713, v116
	v_mul_f32_e32 v137, 0x3d372713, v117
	v_mul_f32_e32 v134, v114, v134
	v_mul_f32_e32 v135, v115, v135
	v_mul_f32_e32 v136, v116, v136
	v_mul_f32_e32 v137, v117, v137
	v_fma_f32 v134, v114, v134, v114
	v_fma_f32 v135, v115, v135, v115
	v_fma_f32 v136, v116, v136, v116
	v_fma_f32 v137, v117, v137, v117
	v_mul_f32_e32 v134, 0x3f4c422a, v134
	v_mul_f32_e32 v135, 0x3f4c422a, v135
	v_mul_f32_e32 v136, 0x3f4c422a, v136
	v_mul_f32_e32 v137, 0x3f4c422a, v137
	v_mul_f32_e32 v134, -2.0, v134
	v_mul_f32_e32 v135, -2.0, v135
	v_mul_f32_e32 v136, -2.0, v136
	v_mul_f32_e32 v137, -2.0, v137
	v_mul_f32_e32 v134, 0x3fb8aa3b, v134
	v_mul_f32_e32 v135, 0x3fb8aa3b, v135
	v_mul_f32_e32 v136, 0x3fb8aa3b, v136
	v_mul_f32_e32 v137, 0x3fb8aa3b, v137
	v_exp_f32_e32 v134, v134
	v_exp_f32_e32 v135, v135
	v_exp_f32_e32 v136, v136
	v_exp_f32_e32 v137, v137
	v_add_f32_e32 v134, 1.0, v134
	v_add_f32_e32 v135, 1.0, v135
	v_add_f32_e32 v136, 1.0, v136
	v_add_f32_e32 v137, 1.0, v137
	v_rcp_f32_e32 v134, v134
	v_rcp_f32_e32 v135, v135
	v_rcp_f32_e32 v136, v136
	v_rcp_f32_e32 v137, v137
	s_nop 0
	v_mul_f32_e32 v114, v114, v134
	v_mul_f32_e32 v115, v115, v135
	v_mul_f32_e32 v116, v116, v136
	v_mul_f32_e32 v117, v117, v137
	v_cvt_pk_f16_f32 v114, v114, v115
	v_cvt_pk_f16_f32 v115, v116, v117
	global_store_dwordx2 v193, v[114:115], s[22:23] offset:96
	v_add_u32_e32 v193, 0x2000, v193
	v_mul_f32_e32 v130, 0x3d372713, v110
	v_mul_f32_e32 v131, 0x3d372713, v111
	v_mul_f32_e32 v132, 0x3d372713, v112
	v_mul_f32_e32 v133, 0x3d372713, v113
	v_mul_f32_e32 v130, v110, v130
	v_mul_f32_e32 v131, v111, v131
	v_mul_f32_e32 v132, v112, v132
	v_mul_f32_e32 v133, v113, v133
	v_fma_f32 v130, v110, v130, v110
	v_fma_f32 v131, v111, v131, v111
	v_fma_f32 v132, v112, v132, v112
	v_fma_f32 v133, v113, v133, v113
	v_mul_f32_e32 v130, 0x3f4c422a, v130
	v_mul_f32_e32 v131, 0x3f4c422a, v131
	v_mul_f32_e32 v132, 0x3f4c422a, v132
	v_mul_f32_e32 v133, 0x3f4c422a, v133
	v_mul_f32_e32 v130, -2.0, v130
	v_mul_f32_e32 v131, -2.0, v131
	v_mul_f32_e32 v132, -2.0, v132
	v_mul_f32_e32 v133, -2.0, v133
	v_mul_f32_e32 v130, 0x3fb8aa3b, v130
	v_mul_f32_e32 v131, 0x3fb8aa3b, v131
	v_mul_f32_e32 v132, 0x3fb8aa3b, v132
	v_mul_f32_e32 v133, 0x3fb8aa3b, v133
	v_exp_f32_e32 v130, v130
	v_exp_f32_e32 v131, v131
	v_exp_f32_e32 v132, v132
	v_exp_f32_e32 v133, v133
	v_add_f32_e32 v130, 1.0, v130
	v_add_f32_e32 v131, 1.0, v131
	v_add_f32_e32 v132, 1.0, v132
	v_add_f32_e32 v133, 1.0, v133
	v_rcp_f32_e32 v130, v130
	v_rcp_f32_e32 v131, v131
	v_rcp_f32_e32 v132, v132
	v_rcp_f32_e32 v133, v133
	s_nop 0
	v_mul_f32_e32 v110, v110, v130
	v_mul_f32_e32 v111, v111, v131
	v_mul_f32_e32 v112, v112, v132
	v_mul_f32_e32 v113, v113, v133
	v_cvt_pk_f16_f32 v110, v110, v111
	v_cvt_pk_f16_f32 v111, v112, v113
	global_store_dwordx2 v193, v[110:111], s[22:23] offset:0
	v_mul_f32_e32 v134, 0x3d372713, v106
	v_mul_f32_e32 v135, 0x3d372713, v107
	v_mul_f32_e32 v136, 0x3d372713, v108
	v_mul_f32_e32 v137, 0x3d372713, v109
	v_mul_f32_e32 v134, v106, v134
	v_mul_f32_e32 v135, v107, v135
	v_mul_f32_e32 v136, v108, v136
	v_mul_f32_e32 v137, v109, v137
	v_fma_f32 v134, v106, v134, v106
	v_fma_f32 v135, v107, v135, v107
	v_fma_f32 v136, v108, v136, v108
	v_fma_f32 v137, v109, v137, v109
	v_mul_f32_e32 v134, 0x3f4c422a, v134
	v_mul_f32_e32 v135, 0x3f4c422a, v135
	v_mul_f32_e32 v136, 0x3f4c422a, v136
	v_mul_f32_e32 v137, 0x3f4c422a, v137
	v_mul_f32_e32 v134, -2.0, v134
	v_mul_f32_e32 v135, -2.0, v135
	v_mul_f32_e32 v136, -2.0, v136
	v_mul_f32_e32 v137, -2.0, v137
	v_mul_f32_e32 v134, 0x3fb8aa3b, v134
	v_mul_f32_e32 v135, 0x3fb8aa3b, v135
	v_mul_f32_e32 v136, 0x3fb8aa3b, v136
	v_mul_f32_e32 v137, 0x3fb8aa3b, v137
	v_exp_f32_e32 v134, v134
	v_exp_f32_e32 v135, v135
	v_exp_f32_e32 v136, v136
	v_exp_f32_e32 v137, v137
	v_add_f32_e32 v134, 1.0, v134
	v_add_f32_e32 v135, 1.0, v135
	v_add_f32_e32 v136, 1.0, v136
	v_add_f32_e32 v137, 1.0, v137
	v_rcp_f32_e32 v134, v134
	v_rcp_f32_e32 v135, v135
	v_rcp_f32_e32 v136, v136
	v_rcp_f32_e32 v137, v137
	s_nop 0
	v_mul_f32_e32 v106, v106, v134
	v_mul_f32_e32 v107, v107, v135
	v_mul_f32_e32 v108, v108, v136
	v_mul_f32_e32 v109, v109, v137
	v_cvt_pk_f16_f32 v106, v106, v107
	v_cvt_pk_f16_f32 v107, v108, v109
	global_store_dwordx2 v193, v[106:107], s[22:23] offset:32
	v_mul_f32_e32 v130, 0x3d372713, v102
	v_mul_f32_e32 v131, 0x3d372713, v103
	v_mul_f32_e32 v132, 0x3d372713, v104
	v_mul_f32_e32 v133, 0x3d372713, v105
	v_mul_f32_e32 v130, v102, v130
	v_mul_f32_e32 v131, v103, v131
	v_mul_f32_e32 v132, v104, v132
	v_mul_f32_e32 v133, v105, v133
	v_fma_f32 v130, v102, v130, v102
	v_fma_f32 v131, v103, v131, v103
	v_fma_f32 v132, v104, v132, v104
	v_fma_f32 v133, v105, v133, v105
	v_mul_f32_e32 v130, 0x3f4c422a, v130
	v_mul_f32_e32 v131, 0x3f4c422a, v131
	v_mul_f32_e32 v132, 0x3f4c422a, v132
	v_mul_f32_e32 v133, 0x3f4c422a, v133
	v_mul_f32_e32 v130, -2.0, v130
	v_mul_f32_e32 v131, -2.0, v131
	v_mul_f32_e32 v132, -2.0, v132
	v_mul_f32_e32 v133, -2.0, v133
	v_mul_f32_e32 v130, 0x3fb8aa3b, v130
	v_mul_f32_e32 v131, 0x3fb8aa3b, v131
	v_mul_f32_e32 v132, 0x3fb8aa3b, v132
	v_mul_f32_e32 v133, 0x3fb8aa3b, v133
	v_exp_f32_e32 v130, v130
	v_exp_f32_e32 v131, v131
	v_exp_f32_e32 v132, v132
	v_exp_f32_e32 v133, v133
	v_add_f32_e32 v130, 1.0, v130
	v_add_f32_e32 v131, 1.0, v131
	v_add_f32_e32 v132, 1.0, v132
	v_add_f32_e32 v133, 1.0, v133
	v_rcp_f32_e32 v130, v130
	v_rcp_f32_e32 v131, v131
	v_rcp_f32_e32 v132, v132
	v_rcp_f32_e32 v133, v133
	s_nop 0
	v_mul_f32_e32 v102, v102, v130
	v_mul_f32_e32 v103, v103, v131
	v_mul_f32_e32 v104, v104, v132
	v_mul_f32_e32 v105, v105, v133
	v_cvt_pk_f16_f32 v102, v102, v103
	v_cvt_pk_f16_f32 v103, v104, v105
	global_store_dwordx2 v193, v[102:103], s[22:23] offset:64
	v_mul_f32_e32 v134, 0x3d372713, v98
	v_mul_f32_e32 v135, 0x3d372713, v99
	v_mul_f32_e32 v136, 0x3d372713, v100
	v_mul_f32_e32 v137, 0x3d372713, v101
	v_mul_f32_e32 v134, v98, v134
	v_mul_f32_e32 v135, v99, v135
	v_mul_f32_e32 v136, v100, v136
	v_mul_f32_e32 v137, v101, v137
	v_fma_f32 v134, v98, v134, v98
	v_fma_f32 v135, v99, v135, v99
	v_fma_f32 v136, v100, v136, v100
	v_fma_f32 v137, v101, v137, v101
	v_mul_f32_e32 v134, 0x3f4c422a, v134
	v_mul_f32_e32 v135, 0x3f4c422a, v135
	v_mul_f32_e32 v136, 0x3f4c422a, v136
	v_mul_f32_e32 v137, 0x3f4c422a, v137
	v_mul_f32_e32 v134, -2.0, v134
	v_mul_f32_e32 v135, -2.0, v135
	v_mul_f32_e32 v136, -2.0, v136
	v_mul_f32_e32 v137, -2.0, v137
	v_mul_f32_e32 v134, 0x3fb8aa3b, v134
	v_mul_f32_e32 v135, 0x3fb8aa3b, v135
	v_mul_f32_e32 v136, 0x3fb8aa3b, v136
	v_mul_f32_e32 v137, 0x3fb8aa3b, v137
	v_exp_f32_e32 v134, v134
	v_exp_f32_e32 v135, v135
	v_exp_f32_e32 v136, v136
	v_exp_f32_e32 v137, v137
	v_add_f32_e32 v134, 1.0, v134
	v_add_f32_e32 v135, 1.0, v135
	v_add_f32_e32 v136, 1.0, v136
	v_add_f32_e32 v137, 1.0, v137
	v_rcp_f32_e32 v134, v134
	v_rcp_f32_e32 v135, v135
	v_rcp_f32_e32 v136, v136
	v_rcp_f32_e32 v137, v137
	s_nop 0
	v_mul_f32_e32 v98, v98, v134
	v_mul_f32_e32 v99, v99, v135
	v_mul_f32_e32 v100, v100, v136
	v_mul_f32_e32 v101, v101, v137
	v_cvt_pk_f16_f32 v98, v98, v99
	v_cvt_pk_f16_f32 v99, v100, v101
	global_store_dwordx2 v193, v[98:99], s[22:23] offset:96
	v_add_u32_e32 v193, 0x2000, v193
	v_mul_f32_e32 v130, 0x3d372713, v94
	v_mul_f32_e32 v131, 0x3d372713, v95
	v_mul_f32_e32 v132, 0x3d372713, v96
	v_mul_f32_e32 v133, 0x3d372713, v97
	v_mul_f32_e32 v130, v94, v130
	v_mul_f32_e32 v131, v95, v131
	v_mul_f32_e32 v132, v96, v132
	v_mul_f32_e32 v133, v97, v133
	v_fma_f32 v130, v94, v130, v94
	v_fma_f32 v131, v95, v131, v95
	v_fma_f32 v132, v96, v132, v96
	v_fma_f32 v133, v97, v133, v97
	v_mul_f32_e32 v130, 0x3f4c422a, v130
	v_mul_f32_e32 v131, 0x3f4c422a, v131
	v_mul_f32_e32 v132, 0x3f4c422a, v132
	v_mul_f32_e32 v133, 0x3f4c422a, v133
	v_mul_f32_e32 v130, -2.0, v130
	v_mul_f32_e32 v131, -2.0, v131
	v_mul_f32_e32 v132, -2.0, v132
	v_mul_f32_e32 v133, -2.0, v133
	v_mul_f32_e32 v130, 0x3fb8aa3b, v130
	v_mul_f32_e32 v131, 0x3fb8aa3b, v131
	v_mul_f32_e32 v132, 0x3fb8aa3b, v132
	v_mul_f32_e32 v133, 0x3fb8aa3b, v133
	v_exp_f32_e32 v130, v130
	v_exp_f32_e32 v131, v131
	v_exp_f32_e32 v132, v132
	v_exp_f32_e32 v133, v133
	v_add_f32_e32 v130, 1.0, v130
	v_add_f32_e32 v131, 1.0, v131
	v_add_f32_e32 v132, 1.0, v132
	v_add_f32_e32 v133, 1.0, v133
	v_rcp_f32_e32 v130, v130
	v_rcp_f32_e32 v131, v131
	v_rcp_f32_e32 v132, v132
	v_rcp_f32_e32 v133, v133
	s_nop 0
	v_mul_f32_e32 v94, v94, v130
	v_mul_f32_e32 v95, v95, v131
	v_mul_f32_e32 v96, v96, v132
	v_mul_f32_e32 v97, v97, v133
	v_cvt_pk_f16_f32 v94, v94, v95
	v_cvt_pk_f16_f32 v95, v96, v97
	global_store_dwordx2 v193, v[94:95], s[22:23] offset:0
	v_mul_f32_e32 v134, 0x3d372713, v90
	v_mul_f32_e32 v135, 0x3d372713, v91
	v_mul_f32_e32 v136, 0x3d372713, v92
	v_mul_f32_e32 v137, 0x3d372713, v93
	v_mul_f32_e32 v134, v90, v134
	v_mul_f32_e32 v135, v91, v135
	v_mul_f32_e32 v136, v92, v136
	v_mul_f32_e32 v137, v93, v137
	v_fma_f32 v134, v90, v134, v90
	v_fma_f32 v135, v91, v135, v91
	v_fma_f32 v136, v92, v136, v92
	v_fma_f32 v137, v93, v137, v93
	v_mul_f32_e32 v134, 0x3f4c422a, v134
	v_mul_f32_e32 v135, 0x3f4c422a, v135
	v_mul_f32_e32 v136, 0x3f4c422a, v136
	v_mul_f32_e32 v137, 0x3f4c422a, v137
	v_mul_f32_e32 v134, -2.0, v134
	v_mul_f32_e32 v135, -2.0, v135
	v_mul_f32_e32 v136, -2.0, v136
	v_mul_f32_e32 v137, -2.0, v137
	v_mul_f32_e32 v134, 0x3fb8aa3b, v134
	v_mul_f32_e32 v135, 0x3fb8aa3b, v135
	v_mul_f32_e32 v136, 0x3fb8aa3b, v136
	v_mul_f32_e32 v137, 0x3fb8aa3b, v137
	v_exp_f32_e32 v134, v134
	v_exp_f32_e32 v135, v135
	v_exp_f32_e32 v136, v136
	v_exp_f32_e32 v137, v137
	v_add_f32_e32 v134, 1.0, v134
	v_add_f32_e32 v135, 1.0, v135
	v_add_f32_e32 v136, 1.0, v136
	v_add_f32_e32 v137, 1.0, v137
	v_rcp_f32_e32 v134, v134
	v_rcp_f32_e32 v135, v135
	v_rcp_f32_e32 v136, v136
	v_rcp_f32_e32 v137, v137
	s_nop 0
	v_mul_f32_e32 v90, v90, v134
	v_mul_f32_e32 v91, v91, v135
	v_mul_f32_e32 v92, v92, v136
	v_mul_f32_e32 v93, v93, v137
	v_cvt_pk_f16_f32 v90, v90, v91
	v_cvt_pk_f16_f32 v91, v92, v93
	global_store_dwordx2 v193, v[90:91], s[22:23] offset:32
	v_mul_f32_e32 v130, 0x3d372713, v86
	v_mul_f32_e32 v131, 0x3d372713, v87
	v_mul_f32_e32 v132, 0x3d372713, v88
	v_mul_f32_e32 v133, 0x3d372713, v89
	v_mul_f32_e32 v130, v86, v130
	v_mul_f32_e32 v131, v87, v131
	v_mul_f32_e32 v132, v88, v132
	v_mul_f32_e32 v133, v89, v133
	v_fma_f32 v130, v86, v130, v86
	v_fma_f32 v131, v87, v131, v87
	v_fma_f32 v132, v88, v132, v88
	v_fma_f32 v133, v89, v133, v89
	v_mul_f32_e32 v130, 0x3f4c422a, v130
	v_mul_f32_e32 v131, 0x3f4c422a, v131
	v_mul_f32_e32 v132, 0x3f4c422a, v132
	v_mul_f32_e32 v133, 0x3f4c422a, v133
	v_mul_f32_e32 v130, -2.0, v130
	v_mul_f32_e32 v131, -2.0, v131
	v_mul_f32_e32 v132, -2.0, v132
	v_mul_f32_e32 v133, -2.0, v133
	v_mul_f32_e32 v130, 0x3fb8aa3b, v130
	v_mul_f32_e32 v131, 0x3fb8aa3b, v131
	v_mul_f32_e32 v132, 0x3fb8aa3b, v132
	v_mul_f32_e32 v133, 0x3fb8aa3b, v133
	v_exp_f32_e32 v130, v130
	v_exp_f32_e32 v131, v131
	v_exp_f32_e32 v132, v132
	v_exp_f32_e32 v133, v133
	v_add_f32_e32 v130, 1.0, v130
	v_add_f32_e32 v131, 1.0, v131
	v_add_f32_e32 v132, 1.0, v132
	v_add_f32_e32 v133, 1.0, v133
	v_rcp_f32_e32 v130, v130
	v_rcp_f32_e32 v131, v131
	v_rcp_f32_e32 v132, v132
	v_rcp_f32_e32 v133, v133
	s_nop 0
	v_mul_f32_e32 v86, v86, v130
	v_mul_f32_e32 v87, v87, v131
	v_mul_f32_e32 v88, v88, v132
	v_mul_f32_e32 v89, v89, v133
	v_cvt_pk_f16_f32 v86, v86, v87
	v_cvt_pk_f16_f32 v87, v88, v89
	global_store_dwordx2 v193, v[86:87], s[22:23] offset:64
	v_mul_f32_e32 v134, 0x3d372713, v82
	v_mul_f32_e32 v135, 0x3d372713, v83
	v_mul_f32_e32 v136, 0x3d372713, v84
	v_mul_f32_e32 v137, 0x3d372713, v85
	v_mul_f32_e32 v134, v82, v134
	v_mul_f32_e32 v135, v83, v135
	v_mul_f32_e32 v136, v84, v136
	v_mul_f32_e32 v137, v85, v137
	v_fma_f32 v134, v82, v134, v82
	v_fma_f32 v135, v83, v135, v83
	v_fma_f32 v136, v84, v136, v84
	v_fma_f32 v137, v85, v137, v85
	v_mul_f32_e32 v134, 0x3f4c422a, v134
	v_mul_f32_e32 v135, 0x3f4c422a, v135
	v_mul_f32_e32 v136, 0x3f4c422a, v136
	v_mul_f32_e32 v137, 0x3f4c422a, v137
	v_mul_f32_e32 v134, -2.0, v134
	v_mul_f32_e32 v135, -2.0, v135
	v_mul_f32_e32 v136, -2.0, v136
	v_mul_f32_e32 v137, -2.0, v137
	v_mul_f32_e32 v134, 0x3fb8aa3b, v134
	v_mul_f32_e32 v135, 0x3fb8aa3b, v135
	v_mul_f32_e32 v136, 0x3fb8aa3b, v136
	v_mul_f32_e32 v137, 0x3fb8aa3b, v137
	v_exp_f32_e32 v134, v134
	v_exp_f32_e32 v135, v135
	v_exp_f32_e32 v136, v136
	v_exp_f32_e32 v137, v137
	v_add_f32_e32 v134, 1.0, v134
	v_add_f32_e32 v135, 1.0, v135
	v_add_f32_e32 v136, 1.0, v136
	v_add_f32_e32 v137, 1.0, v137
	v_rcp_f32_e32 v134, v134
	v_rcp_f32_e32 v135, v135
	v_rcp_f32_e32 v136, v136
	v_rcp_f32_e32 v137, v137
	s_nop 0
	v_mul_f32_e32 v82, v82, v134
	v_mul_f32_e32 v83, v83, v135
	v_mul_f32_e32 v84, v84, v136
	v_mul_f32_e32 v85, v85, v137
	v_cvt_pk_f16_f32 v82, v82, v83
	v_cvt_pk_f16_f32 v83, v84, v85
	global_store_dwordx2 v193, v[82:83], s[22:23] offset:96
	v_add_u32_e32 v193, 0x2000, v193
	v_mul_f32_e32 v130, 0x3d372713, v78
	v_mul_f32_e32 v131, 0x3d372713, v79
	v_mul_f32_e32 v132, 0x3d372713, v80
	v_mul_f32_e32 v133, 0x3d372713, v81
	v_mul_f32_e32 v130, v78, v130
	v_mul_f32_e32 v131, v79, v131
	v_mul_f32_e32 v132, v80, v132
	v_mul_f32_e32 v133, v81, v133
	v_fma_f32 v130, v78, v130, v78
	v_fma_f32 v131, v79, v131, v79
	v_fma_f32 v132, v80, v132, v80
	v_fma_f32 v133, v81, v133, v81
	v_mul_f32_e32 v130, 0x3f4c422a, v130
	v_mul_f32_e32 v131, 0x3f4c422a, v131
	v_mul_f32_e32 v132, 0x3f4c422a, v132
	v_mul_f32_e32 v133, 0x3f4c422a, v133
	v_mul_f32_e32 v130, -2.0, v130
	v_mul_f32_e32 v131, -2.0, v131
	v_mul_f32_e32 v132, -2.0, v132
	v_mul_f32_e32 v133, -2.0, v133
	v_mul_f32_e32 v130, 0x3fb8aa3b, v130
	v_mul_f32_e32 v131, 0x3fb8aa3b, v131
	v_mul_f32_e32 v132, 0x3fb8aa3b, v132
	v_mul_f32_e32 v133, 0x3fb8aa3b, v133
	v_exp_f32_e32 v130, v130
	v_exp_f32_e32 v131, v131
	v_exp_f32_e32 v132, v132
	v_exp_f32_e32 v133, v133
	v_add_f32_e32 v130, 1.0, v130
	v_add_f32_e32 v131, 1.0, v131
	v_add_f32_e32 v132, 1.0, v132
	v_add_f32_e32 v133, 1.0, v133
	v_rcp_f32_e32 v130, v130
	v_rcp_f32_e32 v131, v131
	v_rcp_f32_e32 v132, v132
	v_rcp_f32_e32 v133, v133
	s_nop 0
	v_mul_f32_e32 v78, v78, v130
	v_mul_f32_e32 v79, v79, v131
	v_mul_f32_e32 v80, v80, v132
	v_mul_f32_e32 v81, v81, v133
	v_cvt_pk_f16_f32 v78, v78, v79
	v_cvt_pk_f16_f32 v79, v80, v81
	global_store_dwordx2 v193, v[78:79], s[22:23] offset:0
	v_mul_f32_e32 v134, 0x3d372713, v74
	v_mul_f32_e32 v135, 0x3d372713, v75
	v_mul_f32_e32 v136, 0x3d372713, v76
	v_mul_f32_e32 v137, 0x3d372713, v77
	v_mul_f32_e32 v134, v74, v134
	v_mul_f32_e32 v135, v75, v135
	v_mul_f32_e32 v136, v76, v136
	v_mul_f32_e32 v137, v77, v137
	v_fma_f32 v134, v74, v134, v74
	v_fma_f32 v135, v75, v135, v75
	v_fma_f32 v136, v76, v136, v76
	v_fma_f32 v137, v77, v137, v77
	v_mul_f32_e32 v134, 0x3f4c422a, v134
	v_mul_f32_e32 v135, 0x3f4c422a, v135
	v_mul_f32_e32 v136, 0x3f4c422a, v136
	v_mul_f32_e32 v137, 0x3f4c422a, v137
	v_mul_f32_e32 v134, -2.0, v134
	v_mul_f32_e32 v135, -2.0, v135
	v_mul_f32_e32 v136, -2.0, v136
	v_mul_f32_e32 v137, -2.0, v137
	v_mul_f32_e32 v134, 0x3fb8aa3b, v134
	v_mul_f32_e32 v135, 0x3fb8aa3b, v135
	v_mul_f32_e32 v136, 0x3fb8aa3b, v136
	v_mul_f32_e32 v137, 0x3fb8aa3b, v137
	v_exp_f32_e32 v134, v134
	v_exp_f32_e32 v135, v135
	v_exp_f32_e32 v136, v136
	v_exp_f32_e32 v137, v137
	v_add_f32_e32 v134, 1.0, v134
	v_add_f32_e32 v135, 1.0, v135
	v_add_f32_e32 v136, 1.0, v136
	v_add_f32_e32 v137, 1.0, v137
	v_rcp_f32_e32 v134, v134
	v_rcp_f32_e32 v135, v135
	v_rcp_f32_e32 v136, v136
	v_rcp_f32_e32 v137, v137
	s_nop 0
	v_mul_f32_e32 v74, v74, v134
	v_mul_f32_e32 v75, v75, v135
	v_mul_f32_e32 v76, v76, v136
	v_mul_f32_e32 v77, v77, v137
	v_cvt_pk_f16_f32 v74, v74, v75
	v_cvt_pk_f16_f32 v75, v76, v77
	global_store_dwordx2 v193, v[74:75], s[22:23] offset:32
	v_mul_f32_e32 v130, 0x3d372713, v70
	v_mul_f32_e32 v131, 0x3d372713, v71
	v_mul_f32_e32 v132, 0x3d372713, v72
	v_mul_f32_e32 v133, 0x3d372713, v73
	v_mul_f32_e32 v130, v70, v130
	v_mul_f32_e32 v131, v71, v131
	v_mul_f32_e32 v132, v72, v132
	v_mul_f32_e32 v133, v73, v133
	v_fma_f32 v130, v70, v130, v70
	v_fma_f32 v131, v71, v131, v71
	v_fma_f32 v132, v72, v132, v72
	v_fma_f32 v133, v73, v133, v73
	v_mul_f32_e32 v130, 0x3f4c422a, v130
	v_mul_f32_e32 v131, 0x3f4c422a, v131
	v_mul_f32_e32 v132, 0x3f4c422a, v132
	v_mul_f32_e32 v133, 0x3f4c422a, v133
	v_mul_f32_e32 v130, -2.0, v130
	v_mul_f32_e32 v131, -2.0, v131
	v_mul_f32_e32 v132, -2.0, v132
	v_mul_f32_e32 v133, -2.0, v133
	v_mul_f32_e32 v130, 0x3fb8aa3b, v130
	v_mul_f32_e32 v131, 0x3fb8aa3b, v131
	v_mul_f32_e32 v132, 0x3fb8aa3b, v132
	v_mul_f32_e32 v133, 0x3fb8aa3b, v133
	v_exp_f32_e32 v130, v130
	v_exp_f32_e32 v131, v131
	v_exp_f32_e32 v132, v132
	v_exp_f32_e32 v133, v133
	v_add_f32_e32 v130, 1.0, v130
	v_add_f32_e32 v131, 1.0, v131
	v_add_f32_e32 v132, 1.0, v132
	v_add_f32_e32 v133, 1.0, v133
	v_rcp_f32_e32 v130, v130
	v_rcp_f32_e32 v131, v131
	v_rcp_f32_e32 v132, v132
	v_rcp_f32_e32 v133, v133
	s_nop 0
	v_mul_f32_e32 v70, v70, v130
	v_mul_f32_e32 v71, v71, v131
	v_mul_f32_e32 v72, v72, v132
	v_mul_f32_e32 v73, v73, v133
	v_cvt_pk_f16_f32 v70, v70, v71
	v_cvt_pk_f16_f32 v71, v72, v73
	global_store_dwordx2 v193, v[70:71], s[22:23] offset:64
	v_mul_f32_e32 v134, 0x3d372713, v66
	v_mul_f32_e32 v135, 0x3d372713, v67
	v_mul_f32_e32 v136, 0x3d372713, v68
	v_mul_f32_e32 v137, 0x3d372713, v69
	v_mul_f32_e32 v134, v66, v134
	v_mul_f32_e32 v135, v67, v135
	v_mul_f32_e32 v136, v68, v136
	v_mul_f32_e32 v137, v69, v137
	v_fma_f32 v134, v66, v134, v66
	v_fma_f32 v135, v67, v135, v67
	v_fma_f32 v136, v68, v136, v68
	v_fma_f32 v137, v69, v137, v69
	v_mul_f32_e32 v134, 0x3f4c422a, v134
	v_mul_f32_e32 v135, 0x3f4c422a, v135
	v_mul_f32_e32 v136, 0x3f4c422a, v136
	v_mul_f32_e32 v137, 0x3f4c422a, v137
	v_mul_f32_e32 v134, -2.0, v134
	v_mul_f32_e32 v135, -2.0, v135
	v_mul_f32_e32 v136, -2.0, v136
	v_mul_f32_e32 v137, -2.0, v137
	v_mul_f32_e32 v134, 0x3fb8aa3b, v134
	v_mul_f32_e32 v135, 0x3fb8aa3b, v135
	v_mul_f32_e32 v136, 0x3fb8aa3b, v136
	v_mul_f32_e32 v137, 0x3fb8aa3b, v137
	v_exp_f32_e32 v134, v134
	v_exp_f32_e32 v135, v135
	v_exp_f32_e32 v136, v136
	v_exp_f32_e32 v137, v137
	v_add_f32_e32 v134, 1.0, v134
	v_add_f32_e32 v135, 1.0, v135
	v_add_f32_e32 v136, 1.0, v136
	v_add_f32_e32 v137, 1.0, v137
	v_rcp_f32_e32 v134, v134
	v_rcp_f32_e32 v135, v135
	v_rcp_f32_e32 v136, v136
	v_rcp_f32_e32 v137, v137
	s_nop 0
	v_mul_f32_e32 v66, v66, v134
	v_mul_f32_e32 v67, v67, v135
	v_mul_f32_e32 v68, v68, v136
	v_mul_f32_e32 v69, v69, v137
	v_cvt_pk_f16_f32 v66, v66, v67
	v_cvt_pk_f16_f32 v67, v68, v69
	global_store_dwordx2 v193, v[66:67], s[22:23] offset:96
	v_add_u32_e32 v193, 0x2000, v193
	v_mul_f32_e32 v130, 0x3d372713, v62
	v_mul_f32_e32 v131, 0x3d372713, v63
	v_mul_f32_e32 v132, 0x3d372713, v64
	v_mul_f32_e32 v133, 0x3d372713, v65
	v_mul_f32_e32 v130, v62, v130
	v_mul_f32_e32 v131, v63, v131
	v_mul_f32_e32 v132, v64, v132
	v_mul_f32_e32 v133, v65, v133
	v_fma_f32 v130, v62, v130, v62
	v_fma_f32 v131, v63, v131, v63
	v_fma_f32 v132, v64, v132, v64
	v_fma_f32 v133, v65, v133, v65
	v_mul_f32_e32 v130, 0x3f4c422a, v130
	v_mul_f32_e32 v131, 0x3f4c422a, v131
	v_mul_f32_e32 v132, 0x3f4c422a, v132
	v_mul_f32_e32 v133, 0x3f4c422a, v133
	v_mul_f32_e32 v130, -2.0, v130
	v_mul_f32_e32 v131, -2.0, v131
	v_mul_f32_e32 v132, -2.0, v132
	v_mul_f32_e32 v133, -2.0, v133
	v_mul_f32_e32 v130, 0x3fb8aa3b, v130
	v_mul_f32_e32 v131, 0x3fb8aa3b, v131
	v_mul_f32_e32 v132, 0x3fb8aa3b, v132
	v_mul_f32_e32 v133, 0x3fb8aa3b, v133
	v_exp_f32_e32 v130, v130
	v_exp_f32_e32 v131, v131
	v_exp_f32_e32 v132, v132
	v_exp_f32_e32 v133, v133
	v_add_f32_e32 v130, 1.0, v130
	v_add_f32_e32 v131, 1.0, v131
	v_add_f32_e32 v132, 1.0, v132
	v_add_f32_e32 v133, 1.0, v133
	v_rcp_f32_e32 v130, v130
	v_rcp_f32_e32 v131, v131
	v_rcp_f32_e32 v132, v132
	v_rcp_f32_e32 v133, v133
	s_nop 0
	v_mul_f32_e32 v62, v62, v130
	v_mul_f32_e32 v63, v63, v131
	v_mul_f32_e32 v64, v64, v132
	v_mul_f32_e32 v65, v65, v133
	v_cvt_pk_f16_f32 v62, v62, v63
	v_cvt_pk_f16_f32 v63, v64, v65
	global_store_dwordx2 v193, v[62:63], s[22:23] offset:0
	v_mul_f32_e32 v134, 0x3d372713, v58
	v_mul_f32_e32 v135, 0x3d372713, v59
	v_mul_f32_e32 v136, 0x3d372713, v60
	v_mul_f32_e32 v137, 0x3d372713, v61
	v_mul_f32_e32 v134, v58, v134
	v_mul_f32_e32 v135, v59, v135
	v_mul_f32_e32 v136, v60, v136
	v_mul_f32_e32 v137, v61, v137
	v_fma_f32 v134, v58, v134, v58
	v_fma_f32 v135, v59, v135, v59
	v_fma_f32 v136, v60, v136, v60
	v_fma_f32 v137, v61, v137, v61
	v_mul_f32_e32 v134, 0x3f4c422a, v134
	v_mul_f32_e32 v135, 0x3f4c422a, v135
	v_mul_f32_e32 v136, 0x3f4c422a, v136
	v_mul_f32_e32 v137, 0x3f4c422a, v137
	v_mul_f32_e32 v134, -2.0, v134
	v_mul_f32_e32 v135, -2.0, v135
	v_mul_f32_e32 v136, -2.0, v136
	v_mul_f32_e32 v137, -2.0, v137
	v_mul_f32_e32 v134, 0x3fb8aa3b, v134
	v_mul_f32_e32 v135, 0x3fb8aa3b, v135
	v_mul_f32_e32 v136, 0x3fb8aa3b, v136
	v_mul_f32_e32 v137, 0x3fb8aa3b, v137
	v_exp_f32_e32 v134, v134
	v_exp_f32_e32 v135, v135
	v_exp_f32_e32 v136, v136
	v_exp_f32_e32 v137, v137
	v_add_f32_e32 v134, 1.0, v134
	v_add_f32_e32 v135, 1.0, v135
	v_add_f32_e32 v136, 1.0, v136
	v_add_f32_e32 v137, 1.0, v137
	v_rcp_f32_e32 v134, v134
	v_rcp_f32_e32 v135, v135
	v_rcp_f32_e32 v136, v136
	v_rcp_f32_e32 v137, v137
	s_nop 0
	v_mul_f32_e32 v58, v58, v134
	v_mul_f32_e32 v59, v59, v135
	v_mul_f32_e32 v60, v60, v136
	v_mul_f32_e32 v61, v61, v137
	v_cvt_pk_f16_f32 v58, v58, v59
	v_cvt_pk_f16_f32 v59, v60, v61
	global_store_dwordx2 v193, v[58:59], s[22:23] offset:32
	v_mul_f32_e32 v130, 0x3d372713, v54
	v_mul_f32_e32 v131, 0x3d372713, v55
	v_mul_f32_e32 v132, 0x3d372713, v56
	v_mul_f32_e32 v133, 0x3d372713, v57
	v_mul_f32_e32 v130, v54, v130
	v_mul_f32_e32 v131, v55, v131
	v_mul_f32_e32 v132, v56, v132
	v_mul_f32_e32 v133, v57, v133
	v_fma_f32 v130, v54, v130, v54
	v_fma_f32 v131, v55, v131, v55
	v_fma_f32 v132, v56, v132, v56
	v_fma_f32 v133, v57, v133, v57
	v_mul_f32_e32 v130, 0x3f4c422a, v130
	v_mul_f32_e32 v131, 0x3f4c422a, v131
	v_mul_f32_e32 v132, 0x3f4c422a, v132
	v_mul_f32_e32 v133, 0x3f4c422a, v133
	v_mul_f32_e32 v130, -2.0, v130
	v_mul_f32_e32 v131, -2.0, v131
	v_mul_f32_e32 v132, -2.0, v132
	v_mul_f32_e32 v133, -2.0, v133
	v_mul_f32_e32 v130, 0x3fb8aa3b, v130
	v_mul_f32_e32 v131, 0x3fb8aa3b, v131
	v_mul_f32_e32 v132, 0x3fb8aa3b, v132
	v_mul_f32_e32 v133, 0x3fb8aa3b, v133
	v_exp_f32_e32 v130, v130
	v_exp_f32_e32 v131, v131
	v_exp_f32_e32 v132, v132
	v_exp_f32_e32 v133, v133
	v_add_f32_e32 v130, 1.0, v130
	v_add_f32_e32 v131, 1.0, v131
	v_add_f32_e32 v132, 1.0, v132
	v_add_f32_e32 v133, 1.0, v133
	v_rcp_f32_e32 v130, v130
	v_rcp_f32_e32 v131, v131
	v_rcp_f32_e32 v132, v132
	v_rcp_f32_e32 v133, v133
	s_nop 0
	v_mul_f32_e32 v54, v54, v130
	v_mul_f32_e32 v55, v55, v131
	v_mul_f32_e32 v56, v56, v132
	v_mul_f32_e32 v57, v57, v133
	v_cvt_pk_f16_f32 v54, v54, v55
	v_cvt_pk_f16_f32 v55, v56, v57
	global_store_dwordx2 v193, v[54:55], s[22:23] offset:64
	v_mul_f32_e32 v134, 0x3d372713, v50
	v_mul_f32_e32 v135, 0x3d372713, v51
	v_mul_f32_e32 v136, 0x3d372713, v52
	v_mul_f32_e32 v137, 0x3d372713, v53
	v_mul_f32_e32 v134, v50, v134
	v_mul_f32_e32 v135, v51, v135
	v_mul_f32_e32 v136, v52, v136
	v_mul_f32_e32 v137, v53, v137
	v_fma_f32 v134, v50, v134, v50
	v_fma_f32 v135, v51, v135, v51
	v_fma_f32 v136, v52, v136, v52
	v_fma_f32 v137, v53, v137, v53
	v_mul_f32_e32 v134, 0x3f4c422a, v134
	v_mul_f32_e32 v135, 0x3f4c422a, v135
	v_mul_f32_e32 v136, 0x3f4c422a, v136
	v_mul_f32_e32 v137, 0x3f4c422a, v137
	v_mul_f32_e32 v134, -2.0, v134
	v_mul_f32_e32 v135, -2.0, v135
	v_mul_f32_e32 v136, -2.0, v136
	v_mul_f32_e32 v137, -2.0, v137
	v_mul_f32_e32 v134, 0x3fb8aa3b, v134
	v_mul_f32_e32 v135, 0x3fb8aa3b, v135
	v_mul_f32_e32 v136, 0x3fb8aa3b, v136
	v_mul_f32_e32 v137, 0x3fb8aa3b, v137
	v_exp_f32_e32 v134, v134
	v_exp_f32_e32 v135, v135
	v_exp_f32_e32 v136, v136
	v_exp_f32_e32 v137, v137
	v_add_f32_e32 v134, 1.0, v134
	v_add_f32_e32 v135, 1.0, v135
	v_add_f32_e32 v136, 1.0, v136
	v_add_f32_e32 v137, 1.0, v137
	v_rcp_f32_e32 v134, v134
	v_rcp_f32_e32 v135, v135
	v_rcp_f32_e32 v136, v136
	v_rcp_f32_e32 v137, v137
	s_nop 0
	v_mul_f32_e32 v50, v50, v134
	v_mul_f32_e32 v51, v51, v135
	v_mul_f32_e32 v52, v52, v136
	v_mul_f32_e32 v53, v53, v137
	v_cvt_pk_f16_f32 v50, v50, v51
	v_cvt_pk_f16_f32 v51, v52, v53
	global_store_dwordx2 v193, v[50:51], s[22:23] offset:96
	v_add_u32_e32 v193, 0x2000, v193
	v_mul_f32_e32 v130, 0x3d372713, v46
	v_mul_f32_e32 v131, 0x3d372713, v47
	v_mul_f32_e32 v132, 0x3d372713, v48
	v_mul_f32_e32 v133, 0x3d372713, v49
	v_mul_f32_e32 v130, v46, v130
	v_mul_f32_e32 v131, v47, v131
	v_mul_f32_e32 v132, v48, v132
	v_mul_f32_e32 v133, v49, v133
	v_fma_f32 v130, v46, v130, v46
	v_fma_f32 v131, v47, v131, v47
	v_fma_f32 v132, v48, v132, v48
	v_fma_f32 v133, v49, v133, v49
	v_mul_f32_e32 v130, 0x3f4c422a, v130
	v_mul_f32_e32 v131, 0x3f4c422a, v131
	v_mul_f32_e32 v132, 0x3f4c422a, v132
	v_mul_f32_e32 v133, 0x3f4c422a, v133
	v_mul_f32_e32 v130, -2.0, v130
	v_mul_f32_e32 v131, -2.0, v131
	v_mul_f32_e32 v132, -2.0, v132
	v_mul_f32_e32 v133, -2.0, v133
	v_mul_f32_e32 v130, 0x3fb8aa3b, v130
	v_mul_f32_e32 v131, 0x3fb8aa3b, v131
	v_mul_f32_e32 v132, 0x3fb8aa3b, v132
	v_mul_f32_e32 v133, 0x3fb8aa3b, v133
	v_exp_f32_e32 v130, v130
	v_exp_f32_e32 v131, v131
	v_exp_f32_e32 v132, v132
	v_exp_f32_e32 v133, v133
	v_add_f32_e32 v130, 1.0, v130
	v_add_f32_e32 v131, 1.0, v131
	v_add_f32_e32 v132, 1.0, v132
	v_add_f32_e32 v133, 1.0, v133
	v_rcp_f32_e32 v130, v130
	v_rcp_f32_e32 v131, v131
	v_rcp_f32_e32 v132, v132
	v_rcp_f32_e32 v133, v133
	s_nop 0
	v_mul_f32_e32 v46, v46, v130
	v_mul_f32_e32 v47, v47, v131
	v_mul_f32_e32 v48, v48, v132
	v_mul_f32_e32 v49, v49, v133
	v_cvt_pk_f16_f32 v46, v46, v47
	v_cvt_pk_f16_f32 v47, v48, v49
	global_store_dwordx2 v193, v[46:47], s[22:23] offset:0
	v_mul_f32_e32 v134, 0x3d372713, v42
	v_mul_f32_e32 v135, 0x3d372713, v43
	v_mul_f32_e32 v136, 0x3d372713, v44
	v_mul_f32_e32 v137, 0x3d372713, v45
	v_mul_f32_e32 v134, v42, v134
	v_mul_f32_e32 v135, v43, v135
	v_mul_f32_e32 v136, v44, v136
	v_mul_f32_e32 v137, v45, v137
	v_fma_f32 v134, v42, v134, v42
	v_fma_f32 v135, v43, v135, v43
	v_fma_f32 v136, v44, v136, v44
	v_fma_f32 v137, v45, v137, v45
	v_mul_f32_e32 v134, 0x3f4c422a, v134
	v_mul_f32_e32 v135, 0x3f4c422a, v135
	v_mul_f32_e32 v136, 0x3f4c422a, v136
	v_mul_f32_e32 v137, 0x3f4c422a, v137
	v_mul_f32_e32 v134, -2.0, v134
	v_mul_f32_e32 v135, -2.0, v135
	v_mul_f32_e32 v136, -2.0, v136
	v_mul_f32_e32 v137, -2.0, v137
	v_mul_f32_e32 v134, 0x3fb8aa3b, v134
	v_mul_f32_e32 v135, 0x3fb8aa3b, v135
	v_mul_f32_e32 v136, 0x3fb8aa3b, v136
	v_mul_f32_e32 v137, 0x3fb8aa3b, v137
	v_exp_f32_e32 v134, v134
	v_exp_f32_e32 v135, v135
	v_exp_f32_e32 v136, v136
	v_exp_f32_e32 v137, v137
	v_add_f32_e32 v134, 1.0, v134
	v_add_f32_e32 v135, 1.0, v135
	v_add_f32_e32 v136, 1.0, v136
	v_add_f32_e32 v137, 1.0, v137
	v_rcp_f32_e32 v134, v134
	v_rcp_f32_e32 v135, v135
	v_rcp_f32_e32 v136, v136
	v_rcp_f32_e32 v137, v137
	s_nop 0
	v_mul_f32_e32 v42, v42, v134
	v_mul_f32_e32 v43, v43, v135
	v_mul_f32_e32 v44, v44, v136
	v_mul_f32_e32 v45, v45, v137
	v_cvt_pk_f16_f32 v42, v42, v43
	v_cvt_pk_f16_f32 v43, v44, v45
	global_store_dwordx2 v193, v[42:43], s[22:23] offset:32
	v_mul_f32_e32 v130, 0x3d372713, v38
	v_mul_f32_e32 v131, 0x3d372713, v39
	v_mul_f32_e32 v132, 0x3d372713, v40
	v_mul_f32_e32 v133, 0x3d372713, v41
	v_mul_f32_e32 v130, v38, v130
	v_mul_f32_e32 v131, v39, v131
	v_mul_f32_e32 v132, v40, v132
	v_mul_f32_e32 v133, v41, v133
	v_fma_f32 v130, v38, v130, v38
	v_fma_f32 v131, v39, v131, v39
	v_fma_f32 v132, v40, v132, v40
	v_fma_f32 v133, v41, v133, v41
	v_mul_f32_e32 v130, 0x3f4c422a, v130
	v_mul_f32_e32 v131, 0x3f4c422a, v131
	v_mul_f32_e32 v132, 0x3f4c422a, v132
	v_mul_f32_e32 v133, 0x3f4c422a, v133
	v_mul_f32_e32 v130, -2.0, v130
	v_mul_f32_e32 v131, -2.0, v131
	v_mul_f32_e32 v132, -2.0, v132
	v_mul_f32_e32 v133, -2.0, v133
	v_mul_f32_e32 v130, 0x3fb8aa3b, v130
	v_mul_f32_e32 v131, 0x3fb8aa3b, v131
	v_mul_f32_e32 v132, 0x3fb8aa3b, v132
	v_mul_f32_e32 v133, 0x3fb8aa3b, v133
	v_exp_f32_e32 v130, v130
	v_exp_f32_e32 v131, v131
	v_exp_f32_e32 v132, v132
	v_exp_f32_e32 v133, v133
	v_add_f32_e32 v130, 1.0, v130
	v_add_f32_e32 v131, 1.0, v131
	v_add_f32_e32 v132, 1.0, v132
	v_add_f32_e32 v133, 1.0, v133
	v_rcp_f32_e32 v130, v130
	v_rcp_f32_e32 v131, v131
	v_rcp_f32_e32 v132, v132
	v_rcp_f32_e32 v133, v133
	s_nop 0
	v_mul_f32_e32 v38, v38, v130
	v_mul_f32_e32 v39, v39, v131
	v_mul_f32_e32 v40, v40, v132
	v_mul_f32_e32 v41, v41, v133
	v_cvt_pk_f16_f32 v38, v38, v39
	v_cvt_pk_f16_f32 v39, v40, v41
	global_store_dwordx2 v193, v[38:39], s[22:23] offset:64
	v_mul_f32_e32 v134, 0x3d372713, v34
	v_mul_f32_e32 v135, 0x3d372713, v35
	v_mul_f32_e32 v136, 0x3d372713, v36
	v_mul_f32_e32 v137, 0x3d372713, v37
	v_mul_f32_e32 v134, v34, v134
	v_mul_f32_e32 v135, v35, v135
	v_mul_f32_e32 v136, v36, v136
	v_mul_f32_e32 v137, v37, v137
	v_fma_f32 v134, v34, v134, v34
	v_fma_f32 v135, v35, v135, v35
	v_fma_f32 v136, v36, v136, v36
	v_fma_f32 v137, v37, v137, v37
	v_mul_f32_e32 v134, 0x3f4c422a, v134
	v_mul_f32_e32 v135, 0x3f4c422a, v135
	v_mul_f32_e32 v136, 0x3f4c422a, v136
	v_mul_f32_e32 v137, 0x3f4c422a, v137
	v_mul_f32_e32 v134, -2.0, v134
	v_mul_f32_e32 v135, -2.0, v135
	v_mul_f32_e32 v136, -2.0, v136
	v_mul_f32_e32 v137, -2.0, v137
	v_mul_f32_e32 v134, 0x3fb8aa3b, v134
	v_mul_f32_e32 v135, 0x3fb8aa3b, v135
	v_mul_f32_e32 v136, 0x3fb8aa3b, v136
	v_mul_f32_e32 v137, 0x3fb8aa3b, v137
	v_exp_f32_e32 v134, v134
	v_exp_f32_e32 v135, v135
	v_exp_f32_e32 v136, v136
	v_exp_f32_e32 v137, v137
	v_add_f32_e32 v134, 1.0, v134
	v_add_f32_e32 v135, 1.0, v135
	v_add_f32_e32 v136, 1.0, v136
	v_add_f32_e32 v137, 1.0, v137
	v_rcp_f32_e32 v134, v134
	v_rcp_f32_e32 v135, v135
	v_rcp_f32_e32 v136, v136
	v_rcp_f32_e32 v137, v137
	s_nop 0
	v_mul_f32_e32 v34, v34, v134
	v_mul_f32_e32 v35, v35, v135
	v_mul_f32_e32 v36, v36, v136
	v_mul_f32_e32 v37, v37, v137
	v_cvt_pk_f16_f32 v34, v34, v35
	v_cvt_pk_f16_f32 v35, v36, v37
	global_store_dwordx2 v193, v[34:35], s[22:23] offset:96
	v_add_u32_e32 v193, 0x2000, v193
	v_mul_f32_e32 v130, 0x3d372713, v30
	v_mul_f32_e32 v131, 0x3d372713, v31
	v_mul_f32_e32 v132, 0x3d372713, v32
	v_mul_f32_e32 v133, 0x3d372713, v33
	v_mul_f32_e32 v130, v30, v130
	v_mul_f32_e32 v131, v31, v131
	v_mul_f32_e32 v132, v32, v132
	v_mul_f32_e32 v133, v33, v133
	v_fma_f32 v130, v30, v130, v30
	v_fma_f32 v131, v31, v131, v31
	v_fma_f32 v132, v32, v132, v32
	v_fma_f32 v133, v33, v133, v33
	v_mul_f32_e32 v130, 0x3f4c422a, v130
	v_mul_f32_e32 v131, 0x3f4c422a, v131
	v_mul_f32_e32 v132, 0x3f4c422a, v132
	v_mul_f32_e32 v133, 0x3f4c422a, v133
	v_mul_f32_e32 v130, -2.0, v130
	v_mul_f32_e32 v131, -2.0, v131
	v_mul_f32_e32 v132, -2.0, v132
	v_mul_f32_e32 v133, -2.0, v133
	v_mul_f32_e32 v130, 0x3fb8aa3b, v130
	v_mul_f32_e32 v131, 0x3fb8aa3b, v131
	v_mul_f32_e32 v132, 0x3fb8aa3b, v132
	v_mul_f32_e32 v133, 0x3fb8aa3b, v133
	v_exp_f32_e32 v130, v130
	v_exp_f32_e32 v131, v131
	v_exp_f32_e32 v132, v132
	v_exp_f32_e32 v133, v133
	v_add_f32_e32 v130, 1.0, v130
	v_add_f32_e32 v131, 1.0, v131
	v_add_f32_e32 v132, 1.0, v132
	v_add_f32_e32 v133, 1.0, v133
	v_rcp_f32_e32 v130, v130
	v_rcp_f32_e32 v131, v131
	v_rcp_f32_e32 v132, v132
	v_rcp_f32_e32 v133, v133
	s_nop 0
	v_mul_f32_e32 v30, v30, v130
	v_mul_f32_e32 v31, v31, v131
	v_mul_f32_e32 v32, v32, v132
	v_mul_f32_e32 v33, v33, v133
	v_cvt_pk_f16_f32 v30, v30, v31
	v_cvt_pk_f16_f32 v31, v32, v33
	global_store_dwordx2 v193, v[30:31], s[22:23] offset:0
	v_mul_f32_e32 v134, 0x3d372713, v26
	v_mul_f32_e32 v135, 0x3d372713, v27
	v_mul_f32_e32 v136, 0x3d372713, v28
	v_mul_f32_e32 v137, 0x3d372713, v29
	v_mul_f32_e32 v134, v26, v134
	v_mul_f32_e32 v135, v27, v135
	v_mul_f32_e32 v136, v28, v136
	v_mul_f32_e32 v137, v29, v137
	v_fma_f32 v134, v26, v134, v26
	v_fma_f32 v135, v27, v135, v27
	v_fma_f32 v136, v28, v136, v28
	v_fma_f32 v137, v29, v137, v29
	v_mul_f32_e32 v134, 0x3f4c422a, v134
	v_mul_f32_e32 v135, 0x3f4c422a, v135
	v_mul_f32_e32 v136, 0x3f4c422a, v136
	v_mul_f32_e32 v137, 0x3f4c422a, v137
	v_mul_f32_e32 v134, -2.0, v134
	v_mul_f32_e32 v135, -2.0, v135
	v_mul_f32_e32 v136, -2.0, v136
	v_mul_f32_e32 v137, -2.0, v137
	v_mul_f32_e32 v134, 0x3fb8aa3b, v134
	v_mul_f32_e32 v135, 0x3fb8aa3b, v135
	v_mul_f32_e32 v136, 0x3fb8aa3b, v136
	v_mul_f32_e32 v137, 0x3fb8aa3b, v137
	v_exp_f32_e32 v134, v134
	v_exp_f32_e32 v135, v135
	v_exp_f32_e32 v136, v136
	v_exp_f32_e32 v137, v137
	v_add_f32_e32 v134, 1.0, v134
	v_add_f32_e32 v135, 1.0, v135
	v_add_f32_e32 v136, 1.0, v136
	v_add_f32_e32 v137, 1.0, v137
	v_rcp_f32_e32 v134, v134
	v_rcp_f32_e32 v135, v135
	v_rcp_f32_e32 v136, v136
	v_rcp_f32_e32 v137, v137
	s_nop 0
	v_mul_f32_e32 v26, v26, v134
	v_mul_f32_e32 v27, v27, v135
	v_mul_f32_e32 v28, v28, v136
	v_mul_f32_e32 v29, v29, v137
	v_cvt_pk_f16_f32 v26, v26, v27
	v_cvt_pk_f16_f32 v27, v28, v29
	global_store_dwordx2 v193, v[26:27], s[22:23] offset:32
	v_mul_f32_e32 v130, 0x3d372713, v22
	v_mul_f32_e32 v131, 0x3d372713, v23
	v_mul_f32_e32 v132, 0x3d372713, v24
	v_mul_f32_e32 v133, 0x3d372713, v25
	v_mul_f32_e32 v130, v22, v130
	v_mul_f32_e32 v131, v23, v131
	v_mul_f32_e32 v132, v24, v132
	v_mul_f32_e32 v133, v25, v133
	v_fma_f32 v130, v22, v130, v22
	v_fma_f32 v131, v23, v131, v23
	v_fma_f32 v132, v24, v132, v24
	v_fma_f32 v133, v25, v133, v25
	v_mul_f32_e32 v130, 0x3f4c422a, v130
	v_mul_f32_e32 v131, 0x3f4c422a, v131
	v_mul_f32_e32 v132, 0x3f4c422a, v132
	v_mul_f32_e32 v133, 0x3f4c422a, v133
	v_mul_f32_e32 v130, -2.0, v130
	v_mul_f32_e32 v131, -2.0, v131
	v_mul_f32_e32 v132, -2.0, v132
	v_mul_f32_e32 v133, -2.0, v133
	v_mul_f32_e32 v130, 0x3fb8aa3b, v130
	v_mul_f32_e32 v131, 0x3fb8aa3b, v131
	v_mul_f32_e32 v132, 0x3fb8aa3b, v132
	v_mul_f32_e32 v133, 0x3fb8aa3b, v133
	v_exp_f32_e32 v130, v130
	v_exp_f32_e32 v131, v131
	v_exp_f32_e32 v132, v132
	v_exp_f32_e32 v133, v133
	v_add_f32_e32 v130, 1.0, v130
	v_add_f32_e32 v131, 1.0, v131
	v_add_f32_e32 v132, 1.0, v132
	v_add_f32_e32 v133, 1.0, v133
	v_rcp_f32_e32 v130, v130
	v_rcp_f32_e32 v131, v131
	v_rcp_f32_e32 v132, v132
	v_rcp_f32_e32 v133, v133
	s_nop 0
	v_mul_f32_e32 v22, v22, v130
	v_mul_f32_e32 v23, v23, v131
	v_mul_f32_e32 v24, v24, v132
	v_mul_f32_e32 v25, v25, v133
	v_cvt_pk_f16_f32 v22, v22, v23
	v_cvt_pk_f16_f32 v23, v24, v25
	global_store_dwordx2 v193, v[22:23], s[22:23] offset:64
	v_mul_f32_e32 v134, 0x3d372713, v18
	v_mul_f32_e32 v135, 0x3d372713, v19
	v_mul_f32_e32 v136, 0x3d372713, v20
	v_mul_f32_e32 v137, 0x3d372713, v21
	v_mul_f32_e32 v134, v18, v134
	v_mul_f32_e32 v135, v19, v135
	v_mul_f32_e32 v136, v20, v136
	v_mul_f32_e32 v137, v21, v137
	v_fma_f32 v134, v18, v134, v18
	v_fma_f32 v135, v19, v135, v19
	v_fma_f32 v136, v20, v136, v20
	v_fma_f32 v137, v21, v137, v21
	v_mul_f32_e32 v134, 0x3f4c422a, v134
	v_mul_f32_e32 v135, 0x3f4c422a, v135
	v_mul_f32_e32 v136, 0x3f4c422a, v136
	v_mul_f32_e32 v137, 0x3f4c422a, v137
	v_mul_f32_e32 v134, -2.0, v134
	v_mul_f32_e32 v135, -2.0, v135
	v_mul_f32_e32 v136, -2.0, v136
	v_mul_f32_e32 v137, -2.0, v137
	v_mul_f32_e32 v134, 0x3fb8aa3b, v134
	v_mul_f32_e32 v135, 0x3fb8aa3b, v135
	v_mul_f32_e32 v136, 0x3fb8aa3b, v136
	v_mul_f32_e32 v137, 0x3fb8aa3b, v137
	v_exp_f32_e32 v134, v134
	v_exp_f32_e32 v135, v135
	v_exp_f32_e32 v136, v136
	v_exp_f32_e32 v137, v137
	v_add_f32_e32 v134, 1.0, v134
	v_add_f32_e32 v135, 1.0, v135
	v_add_f32_e32 v136, 1.0, v136
	v_add_f32_e32 v137, 1.0, v137
	v_rcp_f32_e32 v134, v134
	v_rcp_f32_e32 v135, v135
	v_rcp_f32_e32 v136, v136
	v_rcp_f32_e32 v137, v137
	s_nop 0
	v_mul_f32_e32 v18, v18, v134
	v_mul_f32_e32 v19, v19, v135
	v_mul_f32_e32 v20, v20, v136
	v_mul_f32_e32 v21, v21, v137
	v_cvt_pk_f16_f32 v18, v18, v19
	v_cvt_pk_f16_f32 v19, v20, v21
	global_store_dwordx2 v193, v[18:19], s[22:23] offset:96
	v_add_u32_e32 v193, 0x2000, v193
	v_mul_f32_e32 v130, 0x3d372713, v14
	v_mul_f32_e32 v131, 0x3d372713, v15
	v_mul_f32_e32 v132, 0x3d372713, v16
	v_mul_f32_e32 v133, 0x3d372713, v17
	v_mul_f32_e32 v130, v14, v130
	v_mul_f32_e32 v131, v15, v131
	v_mul_f32_e32 v132, v16, v132
	v_mul_f32_e32 v133, v17, v133
	v_fma_f32 v130, v14, v130, v14
	v_fma_f32 v131, v15, v131, v15
	v_fma_f32 v132, v16, v132, v16
	v_fma_f32 v133, v17, v133, v17
	v_mul_f32_e32 v130, 0x3f4c422a, v130
	v_mul_f32_e32 v131, 0x3f4c422a, v131
	v_mul_f32_e32 v132, 0x3f4c422a, v132
	v_mul_f32_e32 v133, 0x3f4c422a, v133
	v_mul_f32_e32 v130, -2.0, v130
	v_mul_f32_e32 v131, -2.0, v131
	v_mul_f32_e32 v132, -2.0, v132
	v_mul_f32_e32 v133, -2.0, v133
	v_mul_f32_e32 v130, 0x3fb8aa3b, v130
	v_mul_f32_e32 v131, 0x3fb8aa3b, v131
	v_mul_f32_e32 v132, 0x3fb8aa3b, v132
	v_mul_f32_e32 v133, 0x3fb8aa3b, v133
	v_exp_f32_e32 v130, v130
	v_exp_f32_e32 v131, v131
	v_exp_f32_e32 v132, v132
	v_exp_f32_e32 v133, v133
	v_add_f32_e32 v130, 1.0, v130
	v_add_f32_e32 v131, 1.0, v131
	v_add_f32_e32 v132, 1.0, v132
	v_add_f32_e32 v133, 1.0, v133
	v_rcp_f32_e32 v130, v130
	v_rcp_f32_e32 v131, v131
	v_rcp_f32_e32 v132, v132
	v_rcp_f32_e32 v133, v133
	s_nop 0
	v_mul_f32_e32 v14, v14, v130
	v_mul_f32_e32 v15, v15, v131
	v_mul_f32_e32 v16, v16, v132
	v_mul_f32_e32 v17, v17, v133
	v_cvt_pk_f16_f32 v14, v14, v15
	v_cvt_pk_f16_f32 v15, v16, v17
	global_store_dwordx2 v193, v[14:15], s[22:23] offset:0
	v_mul_f32_e32 v134, 0x3d372713, v10
	v_mul_f32_e32 v135, 0x3d372713, v11
	v_mul_f32_e32 v136, 0x3d372713, v12
	v_mul_f32_e32 v137, 0x3d372713, v13
	v_mul_f32_e32 v134, v10, v134
	v_mul_f32_e32 v135, v11, v135
	v_mul_f32_e32 v136, v12, v136
	v_mul_f32_e32 v137, v13, v137
	v_fma_f32 v134, v10, v134, v10
	v_fma_f32 v135, v11, v135, v11
	v_fma_f32 v136, v12, v136, v12
	v_fma_f32 v137, v13, v137, v13
	v_mul_f32_e32 v134, 0x3f4c422a, v134
	v_mul_f32_e32 v135, 0x3f4c422a, v135
	v_mul_f32_e32 v136, 0x3f4c422a, v136
	v_mul_f32_e32 v137, 0x3f4c422a, v137
	v_mul_f32_e32 v134, -2.0, v134
	v_mul_f32_e32 v135, -2.0, v135
	v_mul_f32_e32 v136, -2.0, v136
	v_mul_f32_e32 v137, -2.0, v137
	v_mul_f32_e32 v134, 0x3fb8aa3b, v134
	v_mul_f32_e32 v135, 0x3fb8aa3b, v135
	v_mul_f32_e32 v136, 0x3fb8aa3b, v136
	v_mul_f32_e32 v137, 0x3fb8aa3b, v137
	v_exp_f32_e32 v134, v134
	v_exp_f32_e32 v135, v135
	v_exp_f32_e32 v136, v136
	v_exp_f32_e32 v137, v137
	v_add_f32_e32 v134, 1.0, v134
	v_add_f32_e32 v135, 1.0, v135
	v_add_f32_e32 v136, 1.0, v136
	v_add_f32_e32 v137, 1.0, v137
	v_rcp_f32_e32 v134, v134
	v_rcp_f32_e32 v135, v135
	v_rcp_f32_e32 v136, v136
	v_rcp_f32_e32 v137, v137
	s_nop 0
	v_mul_f32_e32 v10, v10, v134
	v_mul_f32_e32 v11, v11, v135
	v_mul_f32_e32 v12, v12, v136
	v_mul_f32_e32 v13, v13, v137
	v_cvt_pk_f16_f32 v10, v10, v11
	v_cvt_pk_f16_f32 v11, v12, v13
	global_store_dwordx2 v193, v[10:11], s[22:23] offset:32
	v_mul_f32_e32 v130, 0x3d372713, v6
	v_mul_f32_e32 v131, 0x3d372713, v7
	v_mul_f32_e32 v132, 0x3d372713, v8
	v_mul_f32_e32 v133, 0x3d372713, v9
	v_mul_f32_e32 v130, v6, v130
	v_mul_f32_e32 v131, v7, v131
	v_mul_f32_e32 v132, v8, v132
	v_mul_f32_e32 v133, v9, v133
	v_fma_f32 v130, v6, v130, v6
	v_fma_f32 v131, v7, v131, v7
	v_fma_f32 v132, v8, v132, v8
	v_fma_f32 v133, v9, v133, v9
	v_mul_f32_e32 v130, 0x3f4c422a, v130
	v_mul_f32_e32 v131, 0x3f4c422a, v131
	v_mul_f32_e32 v132, 0x3f4c422a, v132
	v_mul_f32_e32 v133, 0x3f4c422a, v133
	v_mul_f32_e32 v130, -2.0, v130
	v_mul_f32_e32 v131, -2.0, v131
	v_mul_f32_e32 v132, -2.0, v132
	v_mul_f32_e32 v133, -2.0, v133
	v_mul_f32_e32 v130, 0x3fb8aa3b, v130
	v_mul_f32_e32 v131, 0x3fb8aa3b, v131
	v_mul_f32_e32 v132, 0x3fb8aa3b, v132
	v_mul_f32_e32 v133, 0x3fb8aa3b, v133
	v_exp_f32_e32 v130, v130
	v_exp_f32_e32 v131, v131
	v_exp_f32_e32 v132, v132
	v_exp_f32_e32 v133, v133
	v_add_f32_e32 v130, 1.0, v130
	v_add_f32_e32 v131, 1.0, v131
	v_add_f32_e32 v132, 1.0, v132
	v_add_f32_e32 v133, 1.0, v133
	v_rcp_f32_e32 v130, v130
	v_rcp_f32_e32 v131, v131
	v_rcp_f32_e32 v132, v132
	v_rcp_f32_e32 v133, v133
	s_nop 0
	v_mul_f32_e32 v6, v6, v130
	v_mul_f32_e32 v7, v7, v131
	v_mul_f32_e32 v8, v8, v132
	v_mul_f32_e32 v9, v9, v133
	v_cvt_pk_f16_f32 v6, v6, v7
	v_cvt_pk_f16_f32 v7, v8, v9
	global_store_dwordx2 v193, v[6:7], s[22:23] offset:64
	v_mul_f32_e32 v134, 0x3d372713, v2
	v_mul_f32_e32 v135, 0x3d372713, v3
	v_mul_f32_e32 v136, 0x3d372713, v4
	v_mul_f32_e32 v137, 0x3d372713, v5
	v_mul_f32_e32 v134, v2, v134
	v_mul_f32_e32 v135, v3, v135
	v_mul_f32_e32 v136, v4, v136
	v_mul_f32_e32 v137, v5, v137
	v_fma_f32 v134, v2, v134, v2
	v_fma_f32 v135, v3, v135, v3
	v_fma_f32 v136, v4, v136, v4
	v_fma_f32 v137, v5, v137, v5
	v_mul_f32_e32 v134, 0x3f4c422a, v134
	v_mul_f32_e32 v135, 0x3f4c422a, v135
	v_mul_f32_e32 v136, 0x3f4c422a, v136
	v_mul_f32_e32 v137, 0x3f4c422a, v137
	v_mul_f32_e32 v134, -2.0, v134
	v_mul_f32_e32 v135, -2.0, v135
	v_mul_f32_e32 v136, -2.0, v136
	v_mul_f32_e32 v137, -2.0, v137
	v_mul_f32_e32 v134, 0x3fb8aa3b, v134
	v_mul_f32_e32 v135, 0x3fb8aa3b, v135
	v_mul_f32_e32 v136, 0x3fb8aa3b, v136
	v_mul_f32_e32 v137, 0x3fb8aa3b, v137
	v_exp_f32_e32 v134, v134
	v_exp_f32_e32 v135, v135
	v_exp_f32_e32 v136, v136
	v_exp_f32_e32 v137, v137
	v_add_f32_e32 v134, 1.0, v134
	v_add_f32_e32 v135, 1.0, v135
	v_add_f32_e32 v136, 1.0, v136
	v_add_f32_e32 v137, 1.0, v137
	v_rcp_f32_e32 v134, v134
	v_rcp_f32_e32 v135, v135
	v_rcp_f32_e32 v136, v136
	v_rcp_f32_e32 v137, v137
	s_nop 0
	v_mul_f32_e32 v2, v2, v134
	v_mul_f32_e32 v3, v3, v135
	v_mul_f32_e32 v4, v4, v136
	v_mul_f32_e32 v5, v5, v137
	v_cvt_pk_f16_f32 v2, v2, v3
	v_cvt_pk_f16_f32 v3, v4, v5
	global_store_dwordx2 v193, v[2:3], s[22:23] offset:96
	s_waitcnt vmcnt(32)
	s_branch .Lp1_join
.Lp1_e_rope:
	v_and_b32_e32 v194, 15, v222
	v_bfe_u32 v195, v222, 4, 2
	v_bfe_u32 v196, v222, 6, 2
	v_lshrrev_b32_e32 v197, 8, v222
	v_lshl_or_b32 v198, v197, 7, v194
	v_lshlrev_b32_e32 v199, 2, v195
	v_lshl_or_b32 v199, v196, 6, v199
	s_cmp_lt_u32 s4, 0x80
	s_cselect_b32 s3, 1, 0
	s_cmp_eq_u32 s5, 7
	s_cbranch_scc0 .Lp1_rope_k
	v_readlane_b32 s22, v254, 14
	v_readlane_b32 s23, v254, 15
	s_nop 3
	s_add_u32 s22, s22, 0x116ae500
	s_addc_u32 s23, s23, 0
	s_lshl_b32 s2, s4, 17
	s_add_u32 s22, s22, s2
	s_addc_u32 s23, s23, 0
	s_mov_b32 s7, 0x3e8293ee
	s_branch .Lp1_rope_j
.Lp1_rope_k:
	v_readlane_b32 s22, v254, 14
	v_readlane_b32 s23, v254, 15
	s_nop 3
	s_add_u32 s22, s22, 0x128ae500
	s_addc_u32 s23, s23, 0
	s_lshr_b32 s2, s4, 3
	s_mul_i32 s2, s2, 0x900
	s_and_b32 s7, s4, 7
	s_lshl_b32 s7, s7, 8
	s_add_i32 s2, s2, s7
	s_addk_i32 s2, 0x100
	s_add_i32 s7, s4, 0xffffff80
	s_mul_i32 s7, s7, 0x900
	s_cmp_lg_u32 s3, 0
	s_cselect_b32 s2, s2, s7
	s_lshl_b32 s2, s2, 9
	s_add_u32 s22, s22, s2
	s_addc_u32 s23, s23, 0
	s_mov_b32 s7, 1.0
.Lp1_rope_j:
	v_lshlrev_b32_e32 v193, 9, v198
	v_lshl_add_u32 v193, v199, 1, v193
	s_cmp_lg_u32 s3, 0
	s_cbranch_scc0 .Lp1_rope_ctx
	v_readlane_b32 s2, v254, 18
	v_readlane_b32 s3, v254, 19
	s_and_b32 s4, s4, 7
	s_lshl_b32 s4, s4, 15
	s_add_u32 s4, s2, s4
	s_addc_u32 s5, s3, 0
	v_and_b32_e32 v192, 1, v195
	v_lshlrev_b32_e32 v192, 4, v192
	v_lshl_or_b32 v192, v198, 7, v192
	v_cmp_gt_u32_e32 vcc, 2, v195
	v_bfrev_b32_e32 v191, 1
	s_nop 0
	v_cndmask_b32_e32 v191, 0, v191, vcc
	v_xor_b32_e32 v190, 32, v222
	v_and_b32_e32 v190, 63, v190
	v_lshlrev_b32_e32 v190, 2, v190
	global_load_dwordx4 v[130:133], v192, s[4:5] offset:0
	global_load_dwordx4 v[134:137], v192, s[4:5] offset:32
	global_load_dwordx4 v[138:141], v192, s[4:5] offset:64
	global_load_dwordx4 v[142:145], v192, s[4:5] offset:96
	v_add_u32_e32 v192, 0x800, v192
	global_load_dwordx4 v[146:149], v192, s[4:5] offset:0
	global_load_dwordx4 v[150:153], v192, s[4:5] offset:32
	global_load_dwordx4 v[154:157], v192, s[4:5] offset:64
	global_load_dwordx4 v[158:161], v192, s[4:5] offset:96
	v_add_u32_e32 v192, 0x800, v192
	s_add_i32 s2, s53, s95
	s_cmp_lt_i32 s2, s9
	s_cselect_b32 s21, 1, 0
	s_cselect_b32 s53, s2, s53
	s_lshr_b32 s2, s53, 5
	s_mul_hi_u32 s2, s2, 0xcccccccd
	s_lshr_b32 s2, s2, 2
	s_lshl_b32 s3, s2, 4
	s_mul_i32 s2, s2, 0xa0
	s_sub_i32 s2, s53, s2
	s_lshr_b32 s2, s2, 4
	s_and_b32 s6, s53, 15
	s_add_i32 s3, s3, s6
	s_sub_i32 s28, s53, s58
	s_lshr_b32 s28, s28, 4
	s_add_i32 s28, s28, 8
	s_or_b32 s6, s6, 0x80
	s_cmp_ge_i32 s53, s58
	s_cselect_b32 s6, s6, s3
	s_cselect_b32 s28, s28, s2
	s_lshl_b32 s2, s6, 19
	s_add_u32 s12, s64, s2
	s_addc_u32 s13, s65, 0
	s_lshl_b32 s2, s28, 19
	s_add_u32 s14, s34, s2
	s_addc_u32 s15, s35, 0
	s_mov_b32 m0, s18
	s_nop 0
	global_load_lds_dwordx4 v1, s[12:13]
	s_add_i32 m0, s18, 0x2000
	s_add_u32 s16, s12, 0x20000
	s_addc_u32 s17, s13, 0
	global_load_lds_dwordx4 v1, s[16:17]
	s_add_i32 m0, s18, 0x4000
	s_add_u32 s16, s12, 0x40000
	s_addc_u32 s17, s13, 0
	global_load_lds_dwordx4 v1, s[16:17]
	s_add_i32 m0, s18, 0x6000
	s_add_u32 s16, s12, 0x60000
	s_addc_u32 s17, s13, 0
	global_load_lds_dwordx4 v1, s[16:17]
	s_add_i32 m0, s18, 0x8000
	s_nop 0
	global_load_lds_dwordx4 v1, s[14:15]
	s_add_i32 m0, s18, 0xa000
	s_add_u32 s16, s14, 0x20000
	s_addc_u32 s17, s15, 0
	global_load_lds_dwordx4 v1, s[16:17]
	s_add_i32 m0, s18, 0xc000
	s_add_u32 s16, s14, 0x40000
	s_addc_u32 s17, s15, 0
	global_load_lds_dwordx4 v1, s[16:17]
	s_add_i32 m0, s18, 0xe000
	s_add_u32 s16, s14, 0x60000
	s_addc_u32 s17, s15, 0
	global_load_lds_dwordx4 v1, s[16:17]
	ds_bpermute_b32 v162, v190, v126
	ds_bpermute_b32 v163, v190, v127
	ds_bpermute_b32 v164, v190, v128
	ds_bpermute_b32 v165, v190, v129
	ds_bpermute_b32 v166, v190, v122
	ds_bpermute_b32 v167, v190, v123
	ds_bpermute_b32 v168, v190, v124
	ds_bpermute_b32 v169, v190, v125
	ds_bpermute_b32 v170, v190, v118
	ds_bpermute_b32 v171, v190, v119
	ds_bpermute_b32 v172, v190, v120
	ds_bpermute_b32 v173, v190, v121
	ds_bpermute_b32 v174, v190, v114
	ds_bpermute_b32 v175, v190, v115
	ds_bpermute_b32 v176, v190, v116
	ds_bpermute_b32 v177, v190, v117
	s_waitcnt vmcnt(12)
	v_xor_b32_e32 v134, v191, v134
	v_xor_b32_e32 v142, v191, v142
	v_xor_b32_e32 v135, v191, v135
	v_xor_b32_e32 v143, v191, v143
	v_xor_b32_e32 v136, v191, v136
	v_xor_b32_e32 v144, v191, v144
	v_xor_b32_e32 v137, v191, v137
	v_xor_b32_e32 v145, v191, v145
	s_waitcnt lgkmcnt(0)
	v_pk_mul_f32 v[162:163], v[134:135], v[162:163]
	v_pk_mul_f32 v[164:165], v[136:137], v[164:165]
	v_pk_fma_f32 v[126:127], v[126:127], v[130:131], v[162:163]
	v_pk_fma_f32 v[128:129], v[128:129], v[132:133], v[164:165]
	v_pk_mul_f32 v[166:167], v[142:143], v[166:167]
	v_pk_mul_f32 v[168:169], v[144:145], v[168:169]
	v_pk_fma_f32 v[122:123], v[122:123], v[138:139], v[166:167]
	v_pk_fma_f32 v[124:125], v[124:125], v[140:141], v[168:169]
	v_pk_mul_f32 v[170:171], v[134:135], v[170:171]
	v_pk_mul_f32 v[172:173], v[136:137], v[172:173]
	v_pk_fma_f32 v[118:119], v[118:119], v[130:131], v[170:171]
	v_pk_fma_f32 v[120:121], v[120:121], v[132:133], v[172:173]
	v_pk_mul_f32 v[174:175], v[142:143], v[174:175]
	v_pk_mul_f32 v[176:177], v[144:145], v[176:177]
	v_pk_fma_f32 v[114:115], v[114:115], v[138:139], v[174:175]
	v_pk_fma_f32 v[116:117], v[116:117], v[140:141], v[176:177]
	global_load_dwordx4 v[130:133], v192, s[4:5] offset:0
	global_load_dwordx4 v[134:137], v192, s[4:5] offset:32
	global_load_dwordx4 v[138:141], v192, s[4:5] offset:64
	global_load_dwordx4 v[142:145], v192, s[4:5] offset:96
	v_add_u32_e32 v192, 0x800, v192
	v_mul_f32_e32 v126, s7, v126
	v_mul_f32_e32 v127, s7, v127
	v_mul_f32_e32 v128, s7, v128
	v_mul_f32_e32 v129, s7, v129
	v_cvt_pk_f16_f32 v126, v126, v127
	v_cvt_pk_f16_f32 v127, v128, v129
	global_store_dwordx2 v193, v[126:127], s[22:23] offset:0
	v_mul_f32_e32 v122, s7, v122
	v_mul_f32_e32 v123, s7, v123
	v_mul_f32_e32 v124, s7, v124
	v_mul_f32_e32 v125, s7, v125
	v_cvt_pk_f16_f32 v122, v122, v123
	v_cvt_pk_f16_f32 v123, v124, v125
	global_store_dwordx2 v193, v[122:123], s[22:23] offset:32
	v_mul_f32_e32 v118, s7, v118
	v_mul_f32_e32 v119, s7, v119
	v_mul_f32_e32 v120, s7, v120
	v_mul_f32_e32 v121, s7, v121
	v_cvt_pk_f16_f32 v118, v118, v119
	v_cvt_pk_f16_f32 v119, v120, v121
	global_store_dwordx2 v193, v[118:119], s[22:23] offset:64
	v_mul_f32_e32 v114, s7, v114
	v_mul_f32_e32 v115, s7, v115
	v_mul_f32_e32 v116, s7, v116
	v_mul_f32_e32 v117, s7, v117
	v_cvt_pk_f16_f32 v114, v114, v115
	v_cvt_pk_f16_f32 v115, v116, v117
	global_store_dwordx2 v193, v[114:115], s[22:23] offset:96
	v_add_u32_e32 v193, 0x2000, v193
	ds_bpermute_b32 v162, v190, v110
	ds_bpermute_b32 v163, v190, v111
	ds_bpermute_b32 v164, v190, v112
	ds_bpermute_b32 v165, v190, v113
	ds_bpermute_b32 v166, v190, v106
	ds_bpermute_b32 v167, v190, v107
	ds_bpermute_b32 v168, v190, v108
	ds_bpermute_b32 v169, v190, v109
	ds_bpermute_b32 v170, v190, v102
	ds_bpermute_b32 v171, v190, v103
	ds_bpermute_b32 v172, v190, v104
	ds_bpermute_b32 v173, v190, v105
	ds_bpermute_b32 v174, v190, v98
	ds_bpermute_b32 v175, v190, v99
	ds_bpermute_b32 v176, v190, v100
	ds_bpermute_b32 v177, v190, v101
	s_waitcnt vmcnt(16)
	v_xor_b32_e32 v150, v191, v150
	v_xor_b32_e32 v158, v191, v158
	v_xor_b32_e32 v151, v191, v151
	v_xor_b32_e32 v159, v191, v159
	v_xor_b32_e32 v152, v191, v152
	v_xor_b32_e32 v160, v191, v160
	v_xor_b32_e32 v153, v191, v153
	v_xor_b32_e32 v161, v191, v161
	s_waitcnt lgkmcnt(0)
	v_pk_mul_f32 v[162:163], v[150:151], v[162:163]
	v_pk_mul_f32 v[164:165], v[152:153], v[164:165]
	v_pk_fma_f32 v[110:111], v[110:111], v[146:147], v[162:163]
	v_pk_fma_f32 v[112:113], v[112:113], v[148:149], v[164:165]
	v_pk_mul_f32 v[166:167], v[158:159], v[166:167]
	v_pk_mul_f32 v[168:169], v[160:161], v[168:169]
	v_pk_fma_f32 v[106:107], v[106:107], v[154:155], v[166:167]
	v_pk_fma_f32 v[108:109], v[108:109], v[156:157], v[168:169]
	v_pk_mul_f32 v[170:171], v[150:151], v[170:171]
	v_pk_mul_f32 v[172:173], v[152:153], v[172:173]
	v_pk_fma_f32 v[102:103], v[102:103], v[146:147], v[170:171]
	v_pk_fma_f32 v[104:105], v[104:105], v[148:149], v[172:173]
	v_pk_mul_f32 v[174:175], v[158:159], v[174:175]
	v_pk_mul_f32 v[176:177], v[160:161], v[176:177]
	v_pk_fma_f32 v[98:99], v[98:99], v[154:155], v[174:175]
	v_pk_fma_f32 v[100:101], v[100:101], v[156:157], v[176:177]
	global_load_dwordx4 v[146:149], v192, s[4:5] offset:0
	global_load_dwordx4 v[150:153], v192, s[4:5] offset:32
	global_load_dwordx4 v[154:157], v192, s[4:5] offset:64
	global_load_dwordx4 v[158:161], v192, s[4:5] offset:96
	v_add_u32_e32 v192, 0x800, v192
	v_mul_f32_e32 v110, s7, v110
	v_mul_f32_e32 v111, s7, v111
	v_mul_f32_e32 v112, s7, v112
	v_mul_f32_e32 v113, s7, v113
	v_cvt_pk_f16_f32 v110, v110, v111
	v_cvt_pk_f16_f32 v111, v112, v113
	global_store_dwordx2 v193, v[110:111], s[22:23] offset:0
	v_mul_f32_e32 v106, s7, v106
	v_mul_f32_e32 v107, s7, v107
	v_mul_f32_e32 v108, s7, v108
	v_mul_f32_e32 v109, s7, v109
	v_cvt_pk_f16_f32 v106, v106, v107
	v_cvt_pk_f16_f32 v107, v108, v109
	global_store_dwordx2 v193, v[106:107], s[22:23] offset:32
	v_mul_f32_e32 v102, s7, v102
	v_mul_f32_e32 v103, s7, v103
	v_mul_f32_e32 v104, s7, v104
	v_mul_f32_e32 v105, s7, v105
	v_cvt_pk_f16_f32 v102, v102, v103
	v_cvt_pk_f16_f32 v103, v104, v105
	global_store_dwordx2 v193, v[102:103], s[22:23] offset:64
	v_mul_f32_e32 v98, s7, v98
	v_mul_f32_e32 v99, s7, v99
	v_mul_f32_e32 v100, s7, v100
	v_mul_f32_e32 v101, s7, v101
	v_cvt_pk_f16_f32 v98, v98, v99
	v_cvt_pk_f16_f32 v99, v100, v101
	global_store_dwordx2 v193, v[98:99], s[22:23] offset:96
	v_add_u32_e32 v193, 0x2000, v193
	ds_bpermute_b32 v162, v190, v94
	ds_bpermute_b32 v163, v190, v95
	ds_bpermute_b32 v164, v190, v96
	ds_bpermute_b32 v165, v190, v97
	ds_bpermute_b32 v166, v190, v90
	ds_bpermute_b32 v167, v190, v91
	ds_bpermute_b32 v168, v190, v92
	ds_bpermute_b32 v169, v190, v93
	ds_bpermute_b32 v170, v190, v86
	ds_bpermute_b32 v171, v190, v87
	ds_bpermute_b32 v172, v190, v88
	ds_bpermute_b32 v173, v190, v89
	ds_bpermute_b32 v174, v190, v82
	ds_bpermute_b32 v175, v190, v83
	ds_bpermute_b32 v176, v190, v84
	ds_bpermute_b32 v177, v190, v85
	s_waitcnt vmcnt(12)
	v_xor_b32_e32 v134, v191, v134
	v_xor_b32_e32 v142, v191, v142
	v_xor_b32_e32 v135, v191, v135
	v_xor_b32_e32 v143, v191, v143
	v_xor_b32_e32 v136, v191, v136
	v_xor_b32_e32 v144, v191, v144
	v_xor_b32_e32 v137, v191, v137
	v_xor_b32_e32 v145, v191, v145
	s_waitcnt lgkmcnt(0)
	v_pk_mul_f32 v[162:163], v[134:135], v[162:163]
	v_pk_mul_f32 v[164:165], v[136:137], v[164:165]
	v_pk_fma_f32 v[94:95], v[94:95], v[130:131], v[162:163]
	v_pk_fma_f32 v[96:97], v[96:97], v[132:133], v[164:165]
	v_pk_mul_f32 v[166:167], v[142:143], v[166:167]
	v_pk_mul_f32 v[168:169], v[144:145], v[168:169]
	v_pk_fma_f32 v[90:91], v[90:91], v[138:139], v[166:167]
	v_pk_fma_f32 v[92:93], v[92:93], v[140:141], v[168:169]
	v_pk_mul_f32 v[170:171], v[134:135], v[170:171]
	v_pk_mul_f32 v[172:173], v[136:137], v[172:173]
	v_pk_fma_f32 v[86:87], v[86:87], v[130:131], v[170:171]
	v_pk_fma_f32 v[88:89], v[88:89], v[132:133], v[172:173]
	v_pk_mul_f32 v[174:175], v[142:143], v[174:175]
	v_pk_mul_f32 v[176:177], v[144:145], v[176:177]
	v_pk_fma_f32 v[82:83], v[82:83], v[138:139], v[174:175]
	v_pk_fma_f32 v[84:85], v[84:85], v[140:141], v[176:177]
	global_load_dwordx4 v[130:133], v192, s[4:5] offset:0
	global_load_dwordx4 v[134:137], v192, s[4:5] offset:32
	global_load_dwordx4 v[138:141], v192, s[4:5] offset:64
	global_load_dwordx4 v[142:145], v192, s[4:5] offset:96
	v_add_u32_e32 v192, 0x800, v192
	v_mul_f32_e32 v94, s7, v94
	v_mul_f32_e32 v95, s7, v95
	v_mul_f32_e32 v96, s7, v96
	v_mul_f32_e32 v97, s7, v97
	v_cvt_pk_f16_f32 v94, v94, v95
	v_cvt_pk_f16_f32 v95, v96, v97
	global_store_dwordx2 v193, v[94:95], s[22:23] offset:0
	v_mul_f32_e32 v90, s7, v90
	v_mul_f32_e32 v91, s7, v91
	v_mul_f32_e32 v92, s7, v92
	v_mul_f32_e32 v93, s7, v93
	v_cvt_pk_f16_f32 v90, v90, v91
	v_cvt_pk_f16_f32 v91, v92, v93
	global_store_dwordx2 v193, v[90:91], s[22:23] offset:32
	v_mul_f32_e32 v86, s7, v86
	v_mul_f32_e32 v87, s7, v87
	v_mul_f32_e32 v88, s7, v88
	v_mul_f32_e32 v89, s7, v89
	v_cvt_pk_f16_f32 v86, v86, v87
	v_cvt_pk_f16_f32 v87, v88, v89
	global_store_dwordx2 v193, v[86:87], s[22:23] offset:64
	v_mul_f32_e32 v82, s7, v82
	v_mul_f32_e32 v83, s7, v83
	v_mul_f32_e32 v84, s7, v84
	v_mul_f32_e32 v85, s7, v85
	v_cvt_pk_f16_f32 v82, v82, v83
	v_cvt_pk_f16_f32 v83, v84, v85
	global_store_dwordx2 v193, v[82:83], s[22:23] offset:96
	v_add_u32_e32 v193, 0x2000, v193
	ds_bpermute_b32 v162, v190, v78
	ds_bpermute_b32 v163, v190, v79
	ds_bpermute_b32 v164, v190, v80
	ds_bpermute_b32 v165, v190, v81
	ds_bpermute_b32 v166, v190, v74
	ds_bpermute_b32 v167, v190, v75
	ds_bpermute_b32 v168, v190, v76
	ds_bpermute_b32 v169, v190, v77
	ds_bpermute_b32 v170, v190, v70
	ds_bpermute_b32 v171, v190, v71
	ds_bpermute_b32 v172, v190, v72
	ds_bpermute_b32 v173, v190, v73
	ds_bpermute_b32 v174, v190, v66
	ds_bpermute_b32 v175, v190, v67
	ds_bpermute_b32 v176, v190, v68
	ds_bpermute_b32 v177, v190, v69
	s_waitcnt vmcnt(12)
	v_xor_b32_e32 v150, v191, v150
	v_xor_b32_e32 v158, v191, v158
	v_xor_b32_e32 v151, v191, v151
	v_xor_b32_e32 v159, v191, v159
	v_xor_b32_e32 v152, v191, v152
	v_xor_b32_e32 v160, v191, v160
	v_xor_b32_e32 v153, v191, v153
	v_xor_b32_e32 v161, v191, v161
	s_waitcnt lgkmcnt(0)
	v_pk_mul_f32 v[162:163], v[150:151], v[162:163]
	v_pk_mul_f32 v[164:165], v[152:153], v[164:165]
	v_pk_fma_f32 v[78:79], v[78:79], v[146:147], v[162:163]
	v_pk_fma_f32 v[80:81], v[80:81], v[148:149], v[164:165]
	v_pk_mul_f32 v[166:167], v[158:159], v[166:167]
	v_pk_mul_f32 v[168:169], v[160:161], v[168:169]
	v_pk_fma_f32 v[74:75], v[74:75], v[154:155], v[166:167]
	v_pk_fma_f32 v[76:77], v[76:77], v[156:157], v[168:169]
	v_pk_mul_f32 v[170:171], v[150:151], v[170:171]
	v_pk_mul_f32 v[172:173], v[152:153], v[172:173]
	v_pk_fma_f32 v[70:71], v[70:71], v[146:147], v[170:171]
	v_pk_fma_f32 v[72:73], v[72:73], v[148:149], v[172:173]
	v_pk_mul_f32 v[174:175], v[158:159], v[174:175]
	v_pk_mul_f32 v[176:177], v[160:161], v[176:177]
	v_pk_fma_f32 v[66:67], v[66:67], v[154:155], v[174:175]
	v_pk_fma_f32 v[68:69], v[68:69], v[156:157], v[176:177]
	global_load_dwordx4 v[146:149], v192, s[4:5] offset:0
	global_load_dwordx4 v[150:153], v192, s[4:5] offset:32
	global_load_dwordx4 v[154:157], v192, s[4:5] offset:64
	global_load_dwordx4 v[158:161], v192, s[4:5] offset:96
	v_add_u32_e32 v192, 0x800, v192
	v_mul_f32_e32 v78, s7, v78
	v_mul_f32_e32 v79, s7, v79
	v_mul_f32_e32 v80, s7, v80
	v_mul_f32_e32 v81, s7, v81
	v_cvt_pk_f16_f32 v78, v78, v79
	v_cvt_pk_f16_f32 v79, v80, v81
	global_store_dwordx2 v193, v[78:79], s[22:23] offset:0
	v_mul_f32_e32 v74, s7, v74
	v_mul_f32_e32 v75, s7, v75
	v_mul_f32_e32 v76, s7, v76
	v_mul_f32_e32 v77, s7, v77
	v_cvt_pk_f16_f32 v74, v74, v75
	v_cvt_pk_f16_f32 v75, v76, v77
	global_store_dwordx2 v193, v[74:75], s[22:23] offset:32
	v_mul_f32_e32 v70, s7, v70
	v_mul_f32_e32 v71, s7, v71
	v_mul_f32_e32 v72, s7, v72
	v_mul_f32_e32 v73, s7, v73
	v_cvt_pk_f16_f32 v70, v70, v71
	v_cvt_pk_f16_f32 v71, v72, v73
	global_store_dwordx2 v193, v[70:71], s[22:23] offset:64
	v_mul_f32_e32 v66, s7, v66
	v_mul_f32_e32 v67, s7, v67
	v_mul_f32_e32 v68, s7, v68
	v_mul_f32_e32 v69, s7, v69
	v_cvt_pk_f16_f32 v66, v66, v67
	v_cvt_pk_f16_f32 v67, v68, v69
	global_store_dwordx2 v193, v[66:67], s[22:23] offset:96
	v_add_u32_e32 v193, 0x2000, v193
	ds_bpermute_b32 v162, v190, v62
	ds_bpermute_b32 v163, v190, v63
	ds_bpermute_b32 v164, v190, v64
	ds_bpermute_b32 v165, v190, v65
	ds_bpermute_b32 v166, v190, v58
	ds_bpermute_b32 v167, v190, v59
	ds_bpermute_b32 v168, v190, v60
	ds_bpermute_b32 v169, v190, v61
	ds_bpermute_b32 v170, v190, v54
	ds_bpermute_b32 v171, v190, v55
	ds_bpermute_b32 v172, v190, v56
	ds_bpermute_b32 v173, v190, v57
	ds_bpermute_b32 v174, v190, v50
	ds_bpermute_b32 v175, v190, v51
	ds_bpermute_b32 v176, v190, v52
	ds_bpermute_b32 v177, v190, v53
	s_waitcnt vmcnt(12)
	v_xor_b32_e32 v134, v191, v134
	v_xor_b32_e32 v142, v191, v142
	v_xor_b32_e32 v135, v191, v135
	v_xor_b32_e32 v143, v191, v143
	v_xor_b32_e32 v136, v191, v136
	v_xor_b32_e32 v144, v191, v144
	v_xor_b32_e32 v137, v191, v137
	v_xor_b32_e32 v145, v191, v145
	s_waitcnt lgkmcnt(0)
	v_pk_mul_f32 v[162:163], v[134:135], v[162:163]
	v_pk_mul_f32 v[164:165], v[136:137], v[164:165]
	v_pk_fma_f32 v[62:63], v[62:63], v[130:131], v[162:163]
	v_pk_fma_f32 v[64:65], v[64:65], v[132:133], v[164:165]
	v_pk_mul_f32 v[166:167], v[142:143], v[166:167]
	v_pk_mul_f32 v[168:169], v[144:145], v[168:169]
	v_pk_fma_f32 v[58:59], v[58:59], v[138:139], v[166:167]
	v_pk_fma_f32 v[60:61], v[60:61], v[140:141], v[168:169]
	v_pk_mul_f32 v[170:171], v[134:135], v[170:171]
	v_pk_mul_f32 v[172:173], v[136:137], v[172:173]
	v_pk_fma_f32 v[54:55], v[54:55], v[130:131], v[170:171]
	v_pk_fma_f32 v[56:57], v[56:57], v[132:133], v[172:173]
	v_pk_mul_f32 v[174:175], v[142:143], v[174:175]
	v_pk_mul_f32 v[176:177], v[144:145], v[176:177]
	v_pk_fma_f32 v[50:51], v[50:51], v[138:139], v[174:175]
	v_pk_fma_f32 v[52:53], v[52:53], v[140:141], v[176:177]
	global_load_dwordx4 v[130:133], v192, s[4:5] offset:0
	global_load_dwordx4 v[134:137], v192, s[4:5] offset:32
	global_load_dwordx4 v[138:141], v192, s[4:5] offset:64
	global_load_dwordx4 v[142:145], v192, s[4:5] offset:96
	v_add_u32_e32 v192, 0x800, v192
	v_mul_f32_e32 v62, s7, v62
	v_mul_f32_e32 v63, s7, v63
	v_mul_f32_e32 v64, s7, v64
	v_mul_f32_e32 v65, s7, v65
	v_cvt_pk_f16_f32 v62, v62, v63
	v_cvt_pk_f16_f32 v63, v64, v65
	global_store_dwordx2 v193, v[62:63], s[22:23] offset:0
	v_mul_f32_e32 v58, s7, v58
	v_mul_f32_e32 v59, s7, v59
	v_mul_f32_e32 v60, s7, v60
	v_mul_f32_e32 v61, s7, v61
	v_cvt_pk_f16_f32 v58, v58, v59
	v_cvt_pk_f16_f32 v59, v60, v61
	global_store_dwordx2 v193, v[58:59], s[22:23] offset:32
	v_mul_f32_e32 v54, s7, v54
	v_mul_f32_e32 v55, s7, v55
	v_mul_f32_e32 v56, s7, v56
	v_mul_f32_e32 v57, s7, v57
	v_cvt_pk_f16_f32 v54, v54, v55
	v_cvt_pk_f16_f32 v55, v56, v57
	global_store_dwordx2 v193, v[54:55], s[22:23] offset:64
	v_mul_f32_e32 v50, s7, v50
	v_mul_f32_e32 v51, s7, v51
	v_mul_f32_e32 v52, s7, v52
	v_mul_f32_e32 v53, s7, v53
	v_cvt_pk_f16_f32 v50, v50, v51
	v_cvt_pk_f16_f32 v51, v52, v53
	global_store_dwordx2 v193, v[50:51], s[22:23] offset:96
	v_add_u32_e32 v193, 0x2000, v193
	ds_bpermute_b32 v162, v190, v46
	ds_bpermute_b32 v163, v190, v47
	ds_bpermute_b32 v164, v190, v48
	ds_bpermute_b32 v165, v190, v49
	ds_bpermute_b32 v166, v190, v42
	ds_bpermute_b32 v167, v190, v43
	ds_bpermute_b32 v168, v190, v44
	ds_bpermute_b32 v169, v190, v45
	ds_bpermute_b32 v170, v190, v38
	ds_bpermute_b32 v171, v190, v39
	ds_bpermute_b32 v172, v190, v40
	ds_bpermute_b32 v173, v190, v41
	ds_bpermute_b32 v174, v190, v34
	ds_bpermute_b32 v175, v190, v35
	ds_bpermute_b32 v176, v190, v36
	ds_bpermute_b32 v177, v190, v37
	s_waitcnt vmcnt(12)
	v_xor_b32_e32 v150, v191, v150
	v_xor_b32_e32 v158, v191, v158
	v_xor_b32_e32 v151, v191, v151
	v_xor_b32_e32 v159, v191, v159
	v_xor_b32_e32 v152, v191, v152
	v_xor_b32_e32 v160, v191, v160
	v_xor_b32_e32 v153, v191, v153
	v_xor_b32_e32 v161, v191, v161
	s_waitcnt lgkmcnt(0)
	v_pk_mul_f32 v[162:163], v[150:151], v[162:163]
	v_pk_mul_f32 v[164:165], v[152:153], v[164:165]
	v_pk_fma_f32 v[46:47], v[46:47], v[146:147], v[162:163]
	v_pk_fma_f32 v[48:49], v[48:49], v[148:149], v[164:165]
	v_pk_mul_f32 v[166:167], v[158:159], v[166:167]
	v_pk_mul_f32 v[168:169], v[160:161], v[168:169]
	v_pk_fma_f32 v[42:43], v[42:43], v[154:155], v[166:167]
	v_pk_fma_f32 v[44:45], v[44:45], v[156:157], v[168:169]
	v_pk_mul_f32 v[170:171], v[150:151], v[170:171]
	v_pk_mul_f32 v[172:173], v[152:153], v[172:173]
	v_pk_fma_f32 v[38:39], v[38:39], v[146:147], v[170:171]
	v_pk_fma_f32 v[40:41], v[40:41], v[148:149], v[172:173]
	v_pk_mul_f32 v[174:175], v[158:159], v[174:175]
	v_pk_mul_f32 v[176:177], v[160:161], v[176:177]
	v_pk_fma_f32 v[34:35], v[34:35], v[154:155], v[174:175]
	v_pk_fma_f32 v[36:37], v[36:37], v[156:157], v[176:177]
	global_load_dwordx4 v[146:149], v192, s[4:5] offset:0
	global_load_dwordx4 v[150:153], v192, s[4:5] offset:32
	global_load_dwordx4 v[154:157], v192, s[4:5] offset:64
	global_load_dwordx4 v[158:161], v192, s[4:5] offset:96
	v_add_u32_e32 v192, 0x800, v192
	v_mul_f32_e32 v46, s7, v46
	v_mul_f32_e32 v47, s7, v47
	v_mul_f32_e32 v48, s7, v48
	v_mul_f32_e32 v49, s7, v49
	v_cvt_pk_f16_f32 v46, v46, v47
	v_cvt_pk_f16_f32 v47, v48, v49
	global_store_dwordx2 v193, v[46:47], s[22:23] offset:0
	v_mul_f32_e32 v42, s7, v42
	v_mul_f32_e32 v43, s7, v43
	v_mul_f32_e32 v44, s7, v44
	v_mul_f32_e32 v45, s7, v45
	v_cvt_pk_f16_f32 v42, v42, v43
	v_cvt_pk_f16_f32 v43, v44, v45
	global_store_dwordx2 v193, v[42:43], s[22:23] offset:32
	v_mul_f32_e32 v38, s7, v38
	v_mul_f32_e32 v39, s7, v39
	v_mul_f32_e32 v40, s7, v40
	v_mul_f32_e32 v41, s7, v41
	v_cvt_pk_f16_f32 v38, v38, v39
	v_cvt_pk_f16_f32 v39, v40, v41
	global_store_dwordx2 v193, v[38:39], s[22:23] offset:64
	v_mul_f32_e32 v34, s7, v34
	v_mul_f32_e32 v35, s7, v35
	v_mul_f32_e32 v36, s7, v36
	v_mul_f32_e32 v37, s7, v37
	v_cvt_pk_f16_f32 v34, v34, v35
	v_cvt_pk_f16_f32 v35, v36, v37
	global_store_dwordx2 v193, v[34:35], s[22:23] offset:96
	v_add_u32_e32 v193, 0x2000, v193
	ds_bpermute_b32 v162, v190, v30
	ds_bpermute_b32 v163, v190, v31
	ds_bpermute_b32 v164, v190, v32
	ds_bpermute_b32 v165, v190, v33
	ds_bpermute_b32 v166, v190, v26
	ds_bpermute_b32 v167, v190, v27
	ds_bpermute_b32 v168, v190, v28
	ds_bpermute_b32 v169, v190, v29
	ds_bpermute_b32 v170, v190, v22
	ds_bpermute_b32 v171, v190, v23
	ds_bpermute_b32 v172, v190, v24
	ds_bpermute_b32 v173, v190, v25
	ds_bpermute_b32 v174, v190, v18
	ds_bpermute_b32 v175, v190, v19
	ds_bpermute_b32 v176, v190, v20
	ds_bpermute_b32 v177, v190, v21
	s_waitcnt vmcnt(12)
	v_xor_b32_e32 v134, v191, v134
	v_xor_b32_e32 v142, v191, v142
	v_xor_b32_e32 v135, v191, v135
	v_xor_b32_e32 v143, v191, v143
	v_xor_b32_e32 v136, v191, v136
	v_xor_b32_e32 v144, v191, v144
	v_xor_b32_e32 v137, v191, v137
	v_xor_b32_e32 v145, v191, v145
	s_waitcnt lgkmcnt(0)
	v_pk_mul_f32 v[162:163], v[134:135], v[162:163]
	v_pk_mul_f32 v[164:165], v[136:137], v[164:165]
	v_pk_fma_f32 v[30:31], v[30:31], v[130:131], v[162:163]
	v_pk_fma_f32 v[32:33], v[32:33], v[132:133], v[164:165]
	v_pk_mul_f32 v[166:167], v[142:143], v[166:167]
	v_pk_mul_f32 v[168:169], v[144:145], v[168:169]
	v_pk_fma_f32 v[26:27], v[26:27], v[138:139], v[166:167]
	v_pk_fma_f32 v[28:29], v[28:29], v[140:141], v[168:169]
	v_pk_mul_f32 v[170:171], v[134:135], v[170:171]
	v_pk_mul_f32 v[172:173], v[136:137], v[172:173]
	v_pk_fma_f32 v[22:23], v[22:23], v[130:131], v[170:171]
	v_pk_fma_f32 v[24:25], v[24:25], v[132:133], v[172:173]
	v_pk_mul_f32 v[174:175], v[142:143], v[174:175]
	v_pk_mul_f32 v[176:177], v[144:145], v[176:177]
	v_pk_fma_f32 v[18:19], v[18:19], v[138:139], v[174:175]
	v_pk_fma_f32 v[20:21], v[20:21], v[140:141], v[176:177]
	v_mul_f32_e32 v30, s7, v30
	v_mul_f32_e32 v31, s7, v31
	v_mul_f32_e32 v32, s7, v32
	v_mul_f32_e32 v33, s7, v33
	v_cvt_pk_f16_f32 v30, v30, v31
	v_cvt_pk_f16_f32 v31, v32, v33
	global_store_dwordx2 v193, v[30:31], s[22:23] offset:0
	v_mul_f32_e32 v26, s7, v26
	v_mul_f32_e32 v27, s7, v27
	v_mul_f32_e32 v28, s7, v28
	v_mul_f32_e32 v29, s7, v29
	v_cvt_pk_f16_f32 v26, v26, v27
	v_cvt_pk_f16_f32 v27, v28, v29
	global_store_dwordx2 v193, v[26:27], s[22:23] offset:32
	v_mul_f32_e32 v22, s7, v22
	v_mul_f32_e32 v23, s7, v23
	v_mul_f32_e32 v24, s7, v24
	v_mul_f32_e32 v25, s7, v25
	v_cvt_pk_f16_f32 v22, v22, v23
	v_cvt_pk_f16_f32 v23, v24, v25
	global_store_dwordx2 v193, v[22:23], s[22:23] offset:64
	v_mul_f32_e32 v18, s7, v18
	v_mul_f32_e32 v19, s7, v19
	v_mul_f32_e32 v20, s7, v20
	v_mul_f32_e32 v21, s7, v21
	v_cvt_pk_f16_f32 v18, v18, v19
	v_cvt_pk_f16_f32 v19, v20, v21
	global_store_dwordx2 v193, v[18:19], s[22:23] offset:96
	v_add_u32_e32 v193, 0x2000, v193
	ds_bpermute_b32 v162, v190, v14
	ds_bpermute_b32 v163, v190, v15
	ds_bpermute_b32 v164, v190, v16
	ds_bpermute_b32 v165, v190, v17
	ds_bpermute_b32 v166, v190, v10
	ds_bpermute_b32 v167, v190, v11
	ds_bpermute_b32 v168, v190, v12
	ds_bpermute_b32 v169, v190, v13
	ds_bpermute_b32 v170, v190, v6
	ds_bpermute_b32 v171, v190, v7
	ds_bpermute_b32 v172, v190, v8
	ds_bpermute_b32 v173, v190, v9
	ds_bpermute_b32 v174, v190, v2
	ds_bpermute_b32 v175, v190, v3
	ds_bpermute_b32 v176, v190, v4
	ds_bpermute_b32 v177, v190, v5
	s_waitcnt vmcnt(8)
	v_xor_b32_e32 v150, v191, v150
	v_xor_b32_e32 v158, v191, v158
	v_xor_b32_e32 v151, v191, v151
	v_xor_b32_e32 v159, v191, v159
	v_xor_b32_e32 v152, v191, v152
	v_xor_b32_e32 v160, v191, v160
	v_xor_b32_e32 v153, v191, v153
	v_xor_b32_e32 v161, v191, v161
	s_waitcnt lgkmcnt(0)
	v_pk_mul_f32 v[162:163], v[150:151], v[162:163]
	v_pk_mul_f32 v[164:165], v[152:153], v[164:165]
	v_pk_fma_f32 v[14:15], v[14:15], v[146:147], v[162:163]
	v_pk_fma_f32 v[16:17], v[16:17], v[148:149], v[164:165]
	v_pk_mul_f32 v[166:167], v[158:159], v[166:167]
	v_pk_mul_f32 v[168:169], v[160:161], v[168:169]
	v_pk_fma_f32 v[10:11], v[10:11], v[154:155], v[166:167]
	v_pk_fma_f32 v[12:13], v[12:13], v[156:157], v[168:169]
	v_pk_mul_f32 v[170:171], v[150:151], v[170:171]
	v_pk_mul_f32 v[172:173], v[152:153], v[172:173]
	v_pk_fma_f32 v[6:7], v[6:7], v[146:147], v[170:171]
	v_pk_fma_f32 v[8:9], v[8:9], v[148:149], v[172:173]
	v_pk_mul_f32 v[174:175], v[158:159], v[174:175]
	v_pk_mul_f32 v[176:177], v[160:161], v[176:177]
	v_pk_fma_f32 v[2:3], v[2:3], v[154:155], v[174:175]
	v_pk_fma_f32 v[4:5], v[4:5], v[156:157], v[176:177]
	v_mul_f32_e32 v14, s7, v14
	v_mul_f32_e32 v15, s7, v15
	v_mul_f32_e32 v16, s7, v16
	v_mul_f32_e32 v17, s7, v17
	v_cvt_pk_f16_f32 v14, v14, v15
	v_cvt_pk_f16_f32 v15, v16, v17
	global_store_dwordx2 v193, v[14:15], s[22:23] offset:0
	v_mul_f32_e32 v10, s7, v10
	v_mul_f32_e32 v11, s7, v11
	v_mul_f32_e32 v12, s7, v12
	v_mul_f32_e32 v13, s7, v13
	v_cvt_pk_f16_f32 v10, v10, v11
	v_cvt_pk_f16_f32 v11, v12, v13
	global_store_dwordx2 v193, v[10:11], s[22:23] offset:32
	v_mul_f32_e32 v6, s7, v6
	v_mul_f32_e32 v7, s7, v7
	v_mul_f32_e32 v8, s7, v8
	v_mul_f32_e32 v9, s7, v9
	v_cvt_pk_f16_f32 v6, v6, v7
	v_cvt_pk_f16_f32 v7, v8, v9
	global_store_dwordx2 v193, v[6:7], s[22:23] offset:64
	v_mul_f32_e32 v2, s7, v2
	v_mul_f32_e32 v3, s7, v3
	v_mul_f32_e32 v4, s7, v4
	v_mul_f32_e32 v5, s7, v5
	v_cvt_pk_f16_f32 v2, v2, v3
	v_cvt_pk_f16_f32 v3, v4, v5
	global_store_dwordx2 v193, v[2:3], s[22:23] offset:96
	s_branch .Lp1_join
.Lp1_rope_ctx:
	s_add_i32 s2, s53, s95
	s_cmp_lt_i32 s2, s9
	s_cselect_b32 s21, 1, 0
	s_cselect_b32 s53, s2, s53
	s_lshr_b32 s2, s53, 5
	s_mul_hi_u32 s2, s2, 0xcccccccd
	s_lshr_b32 s2, s2, 2
	s_lshl_b32 s3, s2, 4
	s_mul_i32 s2, s2, 0xa0
	s_sub_i32 s2, s53, s2
	s_lshr_b32 s2, s2, 4
	s_and_b32 s6, s53, 15
	s_add_i32 s3, s3, s6
	s_sub_i32 s28, s53, s58
	s_lshr_b32 s28, s28, 4
	s_add_i32 s28, s28, 8
	s_or_b32 s6, s6, 0x80
	s_cmp_ge_i32 s53, s58
	s_cselect_b32 s6, s6, s3
	s_cselect_b32 s28, s28, s2
	s_lshl_b32 s2, s6, 19
	s_add_u32 s12, s64, s2
	s_addc_u32 s13, s65, 0
	s_lshl_b32 s2, s28, 19
	s_add_u32 s14, s34, s2
	s_addc_u32 s15, s35, 0
	s_mov_b32 m0, s18
	s_nop 0
	global_load_lds_dwordx4 v1, s[12:13]
	s_add_i32 m0, s18, 0x2000
	s_add_u32 s16, s12, 0x20000
	s_addc_u32 s17, s13, 0
	global_load_lds_dwordx4 v1, s[16:17]
	s_add_i32 m0, s18, 0x4000
	s_add_u32 s16, s12, 0x40000
	s_addc_u32 s17, s13, 0
	global_load_lds_dwordx4 v1, s[16:17]
	s_add_i32 m0, s18, 0x6000
	s_add_u32 s16, s12, 0x60000
	s_addc_u32 s17, s13, 0
	global_load_lds_dwordx4 v1, s[16:17]
	s_add_i32 m0, s18, 0x8000
	s_nop 0
	global_load_lds_dwordx4 v1, s[14:15]
	s_add_i32 m0, s18, 0xa000
	s_add_u32 s16, s14, 0x20000
	s_addc_u32 s17, s15, 0
	global_load_lds_dwordx4 v1, s[16:17]
	s_add_i32 m0, s18, 0xc000
	s_add_u32 s16, s14, 0x40000
	s_addc_u32 s17, s15, 0
	global_load_lds_dwordx4 v1, s[16:17]
	s_add_i32 m0, s18, 0xe000
	s_add_u32 s16, s14, 0x60000
	s_addc_u32 s17, s15, 0
	global_load_lds_dwordx4 v1, s[16:17]
	v_mul_f32_e32 v126, s7, v126
	v_mul_f32_e32 v127, s7, v127
	v_mul_f32_e32 v128, s7, v128
	v_mul_f32_e32 v129, s7, v129
	v_cvt_pk_f16_f32 v126, v126, v127
	v_cvt_pk_f16_f32 v127, v128, v129
	global_store_dwordx2 v193, v[126:127], s[22:23] offset:0
	v_mul_f32_e32 v122, s7, v122
	v_mul_f32_e32 v123, s7, v123
	v_mul_f32_e32 v124, s7, v124
	v_mul_f32_e32 v125, s7, v125
	v_cvt_pk_f16_f32 v122, v122, v123
	v_cvt_pk_f16_f32 v123, v124, v125
	global_store_dwordx2 v193, v[122:123], s[22:23] offset:32
	v_mul_f32_e32 v118, s7, v118
	v_mul_f32_e32 v119, s7, v119
	v_mul_f32_e32 v120, s7, v120
	v_mul_f32_e32 v121, s7, v121
	v_cvt_pk_f16_f32 v118, v118, v119
	v_cvt_pk_f16_f32 v119, v120, v121
	global_store_dwordx2 v193, v[118:119], s[22:23] offset:64
	v_mul_f32_e32 v114, s7, v114
	v_mul_f32_e32 v115, s7, v115
	v_mul_f32_e32 v116, s7, v116
	v_mul_f32_e32 v117, s7, v117
	v_cvt_pk_f16_f32 v114, v114, v115
	v_cvt_pk_f16_f32 v115, v116, v117
	global_store_dwordx2 v193, v[114:115], s[22:23] offset:96
	v_add_u32_e32 v193, 0x2000, v193
	v_mul_f32_e32 v110, s7, v110
	v_mul_f32_e32 v111, s7, v111
	v_mul_f32_e32 v112, s7, v112
	v_mul_f32_e32 v113, s7, v113
	v_cvt_pk_f16_f32 v110, v110, v111
	v_cvt_pk_f16_f32 v111, v112, v113
	global_store_dwordx2 v193, v[110:111], s[22:23] offset:0
	v_mul_f32_e32 v106, s7, v106
	v_mul_f32_e32 v107, s7, v107
	v_mul_f32_e32 v108, s7, v108
	v_mul_f32_e32 v109, s7, v109
	v_cvt_pk_f16_f32 v106, v106, v107
	v_cvt_pk_f16_f32 v107, v108, v109
	global_store_dwordx2 v193, v[106:107], s[22:23] offset:32
	v_mul_f32_e32 v102, s7, v102
	v_mul_f32_e32 v103, s7, v103
	v_mul_f32_e32 v104, s7, v104
	v_mul_f32_e32 v105, s7, v105
	v_cvt_pk_f16_f32 v102, v102, v103
	v_cvt_pk_f16_f32 v103, v104, v105
	global_store_dwordx2 v193, v[102:103], s[22:23] offset:64
	v_mul_f32_e32 v98, s7, v98
	v_mul_f32_e32 v99, s7, v99
	v_mul_f32_e32 v100, s7, v100
	v_mul_f32_e32 v101, s7, v101
	v_cvt_pk_f16_f32 v98, v98, v99
	v_cvt_pk_f16_f32 v99, v100, v101
	global_store_dwordx2 v193, v[98:99], s[22:23] offset:96
	v_add_u32_e32 v193, 0x2000, v193
	v_mul_f32_e32 v94, s7, v94
	v_mul_f32_e32 v95, s7, v95
	v_mul_f32_e32 v96, s7, v96
	v_mul_f32_e32 v97, s7, v97
	v_cvt_pk_f16_f32 v94, v94, v95
	v_cvt_pk_f16_f32 v95, v96, v97
	global_store_dwordx2 v193, v[94:95], s[22:23] offset:0
	v_mul_f32_e32 v90, s7, v90
	v_mul_f32_e32 v91, s7, v91
	v_mul_f32_e32 v92, s7, v92
	v_mul_f32_e32 v93, s7, v93
	v_cvt_pk_f16_f32 v90, v90, v91
	v_cvt_pk_f16_f32 v91, v92, v93
	global_store_dwordx2 v193, v[90:91], s[22:23] offset:32
	v_mul_f32_e32 v86, s7, v86
	v_mul_f32_e32 v87, s7, v87
	v_mul_f32_e32 v88, s7, v88
	v_mul_f32_e32 v89, s7, v89
	v_cvt_pk_f16_f32 v86, v86, v87
	v_cvt_pk_f16_f32 v87, v88, v89
	global_store_dwordx2 v193, v[86:87], s[22:23] offset:64
	v_mul_f32_e32 v82, s7, v82
	v_mul_f32_e32 v83, s7, v83
	v_mul_f32_e32 v84, s7, v84
	v_mul_f32_e32 v85, s7, v85
	v_cvt_pk_f16_f32 v82, v82, v83
	v_cvt_pk_f16_f32 v83, v84, v85
	global_store_dwordx2 v193, v[82:83], s[22:23] offset:96
	v_add_u32_e32 v193, 0x2000, v193
	v_mul_f32_e32 v78, s7, v78
	v_mul_f32_e32 v79, s7, v79
	v_mul_f32_e32 v80, s7, v80
	v_mul_f32_e32 v81, s7, v81
	v_cvt_pk_f16_f32 v78, v78, v79
	v_cvt_pk_f16_f32 v79, v80, v81
	global_store_dwordx2 v193, v[78:79], s[22:23] offset:0
	v_mul_f32_e32 v74, s7, v74
	v_mul_f32_e32 v75, s7, v75
	v_mul_f32_e32 v76, s7, v76
	v_mul_f32_e32 v77, s7, v77
	v_cvt_pk_f16_f32 v74, v74, v75
	v_cvt_pk_f16_f32 v75, v76, v77
	global_store_dwordx2 v193, v[74:75], s[22:23] offset:32
	v_mul_f32_e32 v70, s7, v70
	v_mul_f32_e32 v71, s7, v71
	v_mul_f32_e32 v72, s7, v72
	v_mul_f32_e32 v73, s7, v73
	v_cvt_pk_f16_f32 v70, v70, v71
	v_cvt_pk_f16_f32 v71, v72, v73
	global_store_dwordx2 v193, v[70:71], s[22:23] offset:64
	v_mul_f32_e32 v66, s7, v66
	v_mul_f32_e32 v67, s7, v67
	v_mul_f32_e32 v68, s7, v68
	v_mul_f32_e32 v69, s7, v69
	v_cvt_pk_f16_f32 v66, v66, v67
	v_cvt_pk_f16_f32 v67, v68, v69
	global_store_dwordx2 v193, v[66:67], s[22:23] offset:96
	v_add_u32_e32 v193, 0x2000, v193
	v_mul_f32_e32 v62, s7, v62
	v_mul_f32_e32 v63, s7, v63
	v_mul_f32_e32 v64, s7, v64
	v_mul_f32_e32 v65, s7, v65
	v_cvt_pk_f16_f32 v62, v62, v63
	v_cvt_pk_f16_f32 v63, v64, v65
	global_store_dwordx2 v193, v[62:63], s[22:23] offset:0
	v_mul_f32_e32 v58, s7, v58
	v_mul_f32_e32 v59, s7, v59
	v_mul_f32_e32 v60, s7, v60
	v_mul_f32_e32 v61, s7, v61
	v_cvt_pk_f16_f32 v58, v58, v59
	v_cvt_pk_f16_f32 v59, v60, v61
	global_store_dwordx2 v193, v[58:59], s[22:23] offset:32
	v_mul_f32_e32 v54, s7, v54
	v_mul_f32_e32 v55, s7, v55
	v_mul_f32_e32 v56, s7, v56
	v_mul_f32_e32 v57, s7, v57
	v_cvt_pk_f16_f32 v54, v54, v55
	v_cvt_pk_f16_f32 v55, v56, v57
	global_store_dwordx2 v193, v[54:55], s[22:23] offset:64
	v_mul_f32_e32 v50, s7, v50
	v_mul_f32_e32 v51, s7, v51
	v_mul_f32_e32 v52, s7, v52
	v_mul_f32_e32 v53, s7, v53
	v_cvt_pk_f16_f32 v50, v50, v51
	v_cvt_pk_f16_f32 v51, v52, v53
	global_store_dwordx2 v193, v[50:51], s[22:23] offset:96
	v_add_u32_e32 v193, 0x2000, v193
	v_mul_f32_e32 v46, s7, v46
	v_mul_f32_e32 v47, s7, v47
	v_mul_f32_e32 v48, s7, v48
	v_mul_f32_e32 v49, s7, v49
	v_cvt_pk_f16_f32 v46, v46, v47
	v_cvt_pk_f16_f32 v47, v48, v49
	global_store_dwordx2 v193, v[46:47], s[22:23] offset:0
	v_mul_f32_e32 v42, s7, v42
	v_mul_f32_e32 v43, s7, v43
	v_mul_f32_e32 v44, s7, v44
	v_mul_f32_e32 v45, s7, v45
	v_cvt_pk_f16_f32 v42, v42, v43
	v_cvt_pk_f16_f32 v43, v44, v45
	global_store_dwordx2 v193, v[42:43], s[22:23] offset:32
	v_mul_f32_e32 v38, s7, v38
	v_mul_f32_e32 v39, s7, v39
	v_mul_f32_e32 v40, s7, v40
	v_mul_f32_e32 v41, s7, v41
	v_cvt_pk_f16_f32 v38, v38, v39
	v_cvt_pk_f16_f32 v39, v40, v41
	global_store_dwordx2 v193, v[38:39], s[22:23] offset:64
	v_mul_f32_e32 v34, s7, v34
	v_mul_f32_e32 v35, s7, v35
	v_mul_f32_e32 v36, s7, v36
	v_mul_f32_e32 v37, s7, v37
	v_cvt_pk_f16_f32 v34, v34, v35
	v_cvt_pk_f16_f32 v35, v36, v37
	global_store_dwordx2 v193, v[34:35], s[22:23] offset:96
	v_add_u32_e32 v193, 0x2000, v193
	v_mul_f32_e32 v30, s7, v30
	v_mul_f32_e32 v31, s7, v31
	v_mul_f32_e32 v32, s7, v32
	v_mul_f32_e32 v33, s7, v33
	v_cvt_pk_f16_f32 v30, v30, v31
	v_cvt_pk_f16_f32 v31, v32, v33
	global_store_dwordx2 v193, v[30:31], s[22:23] offset:0
	v_mul_f32_e32 v26, s7, v26
	v_mul_f32_e32 v27, s7, v27
	v_mul_f32_e32 v28, s7, v28
	v_mul_f32_e32 v29, s7, v29
	v_cvt_pk_f16_f32 v26, v26, v27
	v_cvt_pk_f16_f32 v27, v28, v29
	global_store_dwordx2 v193, v[26:27], s[22:23] offset:32
	v_mul_f32_e32 v22, s7, v22
	v_mul_f32_e32 v23, s7, v23
	v_mul_f32_e32 v24, s7, v24
	v_mul_f32_e32 v25, s7, v25
	v_cvt_pk_f16_f32 v22, v22, v23
	v_cvt_pk_f16_f32 v23, v24, v25
	global_store_dwordx2 v193, v[22:23], s[22:23] offset:64
	v_mul_f32_e32 v18, s7, v18
	v_mul_f32_e32 v19, s7, v19
	v_mul_f32_e32 v20, s7, v20
	v_mul_f32_e32 v21, s7, v21
	v_cvt_pk_f16_f32 v18, v18, v19
	v_cvt_pk_f16_f32 v19, v20, v21
	global_store_dwordx2 v193, v[18:19], s[22:23] offset:96
	v_add_u32_e32 v193, 0x2000, v193
	v_mul_f32_e32 v14, s7, v14
	v_mul_f32_e32 v15, s7, v15
	v_mul_f32_e32 v16, s7, v16
	v_mul_f32_e32 v17, s7, v17
	v_cvt_pk_f16_f32 v14, v14, v15
	v_cvt_pk_f16_f32 v15, v16, v17
	global_store_dwordx2 v193, v[14:15], s[22:23] offset:0
	v_mul_f32_e32 v10, s7, v10
	v_mul_f32_e32 v11, s7, v11
	v_mul_f32_e32 v12, s7, v12
	v_mul_f32_e32 v13, s7, v13
	v_cvt_pk_f16_f32 v10, v10, v11
	v_cvt_pk_f16_f32 v11, v12, v13
	global_store_dwordx2 v193, v[10:11], s[22:23] offset:32
	v_mul_f32_e32 v6, s7, v6
	v_mul_f32_e32 v7, s7, v7
	v_mul_f32_e32 v8, s7, v8
	v_mul_f32_e32 v9, s7, v9
	v_cvt_pk_f16_f32 v6, v6, v7
	v_cvt_pk_f16_f32 v7, v8, v9
	global_store_dwordx2 v193, v[6:7], s[22:23] offset:64
	v_mul_f32_e32 v2, s7, v2
	v_mul_f32_e32 v3, s7, v3
	v_mul_f32_e32 v4, s7, v4
	v_mul_f32_e32 v5, s7, v5
	v_cvt_pk_f16_f32 v2, v2, v3
	v_cvt_pk_f16_f32 v3, v4, v5
	global_store_dwordx2 v193, v[2:3], s[22:23] offset:96
	s_waitcnt vmcnt(32)
.Lp1_join:
	s_cmp_lg_u32 s21, 0
	s_cbranch_scc1 .Lp1_cont
	s_branch .LBB0_689
